# GEMM loops: priority flips inverted (load segment at prio 1, MFMA segment at prio 0)
# baseline (speedup 1.0000x reference)
.LBB0_58:
	s_add_u32 s44, s42, 0x100
	s_addc_u32 s45, s43, 0
	s_add_i32 s23, 0, 0x10000
	v_add_u32_e32 v145, s23, v143
	ds_read_b128 v[146:149], v145
	ds_read_b128 v[150:153], v145 offset:1024
	ds_read_b128 v[154:157], v145 offset:2048
	ds_read_b128 v[158:161], v145 offset:3072
	s_cmp_eq_u32 s22, 40
	s_cselect_b32 s49, s1, s45
	s_cselect_b32 s48, s0, s44
	s_cselect_b32 s47, s41, s21
	s_cselect_b32 s46, s40, s20
	v_lshl_add_u64 v[194:195], s[42:43], 0, v[138:139]
	s_add_i32 m0, s52, 0xc000
	ds_read_b128 v[162:165], v144
	ds_read_b128 v[166:169], v144 offset:1024
	ds_read_b128 v[170:173], v144 offset:2048
	ds_read_b128 v[174:177], v144 offset:3072
	ds_read_b128 v[178:181], v144 offset:4096
	ds_read_b128 v[182:185], v144 offset:5120
	ds_read_b128 v[186:189], v144 offset:6144
	ds_read_b128 v[190:193], v144 offset:7168
	global_load_lds_dwordx4 v[194:195], off
	v_lshl_add_u64 v[194:195], s[42:43], 0, v[140:141]
	s_add_i32 m0, s52, 0xe000
	s_nop 0
	global_load_lds_dwordx4 v[194:195], off
	s_waitcnt lgkmcnt(8)
	s_barrier
	s_waitcnt lgkmcnt(0)
	s_setprio 0
	s_waitcnt lgkmcnt(0)
	v_mfma_f32_16x16x32_bf16 v[128:131], v[146:149], v[162:165], v[128:131]
	v_mfma_f32_16x16x32_bf16 v[124:127], v[154:157], v[162:165], v[124:127]
	v_mfma_f32_16x16x32_bf16 v[120:123], v[146:149], v[170:173], v[120:123]
	v_mfma_f32_16x16x32_bf16 v[116:119], v[154:157], v[170:173], v[116:119]
	v_mfma_f32_16x16x32_bf16 v[104:107], v[146:149], v[178:181], v[104:107]
	v_mfma_f32_16x16x32_bf16 v[100:103], v[154:157], v[178:181], v[100:103]
	v_mfma_f32_16x16x32_bf16 v[88:91], v[146:149], v[186:189], v[88:91]
	v_mfma_f32_16x16x32_bf16 v[84:87], v[154:157], v[186:189], v[84:87]
	v_mfma_f32_16x16x32_bf16 v[128:131], v[150:153], v[166:169], v[128:131]
	v_mfma_f32_16x16x32_bf16 v[124:127], v[158:161], v[166:169], v[124:127]
	v_mfma_f32_16x16x32_bf16 v[120:123], v[150:153], v[174:177], v[120:123]
	v_mfma_f32_16x16x32_bf16 v[116:119], v[158:161], v[174:177], v[116:119]
	v_mfma_f32_16x16x32_bf16 v[104:107], v[150:153], v[182:185], v[104:107]
	v_mfma_f32_16x16x32_bf16 v[100:103], v[158:161], v[182:185], v[100:103]
	v_mfma_f32_16x16x32_bf16 v[88:91], v[150:153], v[190:193], v[88:91]
	v_mfma_f32_16x16x32_bf16 v[84:87], v[158:161], v[190:193], v[84:87]
	s_setprio 1
	s_barrier
	s_add_i32 s26, 0, 0x14000
	s_add_i32 s23, s23, s37
	v_add_u32_e32 v145, s26, v143
	v_lshl_add_u64 v[194:195], s[46:47], 0, v[132:133]
	s_mov_b32 m0, s23
	ds_read_b128 v[202:205], v145
	ds_read_b128 v[206:209], v145 offset:1024
	ds_read_b128 v[210:213], v145 offset:2048
	ds_read_b128 v[214:217], v145 offset:3072
	global_load_lds_dwordx4 v[194:195], off
	v_lshl_add_u64 v[198:199], s[46:47], 0, v[136:137]
	s_add_i32 m0, s23, 0x2000
	s_nop 0
	global_load_lds_dwordx4 v[198:199], off
	s_barrier
	s_waitcnt lgkmcnt(0)
	s_setprio 0
	s_waitcnt lgkmcnt(0)
	v_mfma_f32_16x16x32_bf16 v[112:115], v[202:205], v[162:165], v[112:115]
	v_mfma_f32_16x16x32_bf16 v[108:111], v[210:213], v[162:165], v[108:111]
	v_mfma_f32_16x16x32_bf16 v[96:99], v[202:205], v[170:173], v[96:99]
	v_mfma_f32_16x16x32_bf16 v[92:95], v[210:213], v[170:173], v[92:95]
	v_mfma_f32_16x16x32_bf16 v[80:83], v[202:205], v[178:181], v[80:83]
	v_mfma_f32_16x16x32_bf16 v[76:79], v[210:213], v[178:181], v[76:79]
	v_mfma_f32_16x16x32_bf16 v[72:75], v[202:205], v[186:189], v[72:75]
	v_mfma_f32_16x16x32_bf16 v[68:71], v[210:213], v[186:189], v[68:71]
	v_mfma_f32_16x16x32_bf16 v[112:115], v[206:209], v[166:169], v[112:115]
	v_mfma_f32_16x16x32_bf16 v[108:111], v[214:217], v[166:169], v[108:111]
	v_mfma_f32_16x16x32_bf16 v[96:99], v[206:209], v[174:177], v[96:99]
	v_mfma_f32_16x16x32_bf16 v[92:95], v[214:217], v[174:177], v[92:95]
	v_mfma_f32_16x16x32_bf16 v[80:83], v[206:209], v[182:185], v[80:83]
	v_mfma_f32_16x16x32_bf16 v[76:79], v[214:217], v[182:185], v[76:79]
	v_mfma_f32_16x16x32_bf16 v[72:75], v[206:209], v[190:193], v[72:75]
	v_mfma_f32_16x16x32_bf16 v[68:71], v[214:217], v[190:193], v[68:71]
	s_setprio 1
	s_mov_b32 m0, s52
	v_lshl_add_u64 v[222:223], s[48:49], 0, v[0:1]
	s_barrier
	ds_read_b128 v[162:165], v144 offset:16384
	ds_read_b128 v[166:169], v144 offset:17408
	ds_read_b128 v[170:173], v144 offset:18432
	ds_read_b128 v[174:177], v144 offset:19456
	ds_read_b128 v[178:181], v144 offset:20480
	ds_read_b128 v[182:185], v144 offset:21504
	ds_read_b128 v[186:189], v144 offset:22528
	ds_read_b128 v[190:193], v144 offset:23552
	global_load_lds_dwordx4 v[222:223], off
	v_lshl_add_u64 v[236:237], s[48:49], 0, v[134:135]
	s_mov_b32 m0, s53
	s_nop 0
	global_load_lds_dwordx4 v[236:237], off
	s_barrier
	s_waitcnt lgkmcnt(0)
	s_setprio 0
	s_waitcnt lgkmcnt(0)
	v_mfma_f32_16x16x32_bf16 v[64:67], v[146:149], v[162:165], v[64:67]
	v_mfma_f32_16x16x32_bf16 v[60:63], v[154:157], v[162:165], v[60:63]
	v_mfma_f32_16x16x32_bf16 v[56:59], v[146:149], v[170:173], v[56:59]
	v_mfma_f32_16x16x32_bf16 v[52:55], v[154:157], v[170:173], v[52:55]
	v_mfma_f32_16x16x32_bf16 v[40:43], v[146:149], v[178:181], v[40:43]
	v_mfma_f32_16x16x32_bf16 v[36:39], v[154:157], v[178:181], v[36:39]
	v_mfma_f32_16x16x32_bf16 v[24:27], v[146:149], v[186:189], v[24:27]
	v_mfma_f32_16x16x32_bf16 v[16:19], v[154:157], v[186:189], v[16:19]
	v_mfma_f32_16x16x32_bf16 v[64:67], v[150:153], v[166:169], v[64:67]
	v_mfma_f32_16x16x32_bf16 v[60:63], v[158:161], v[166:169], v[60:63]
	v_mfma_f32_16x16x32_bf16 v[56:59], v[150:153], v[174:177], v[56:59]
	v_mfma_f32_16x16x32_bf16 v[52:55], v[158:161], v[174:177], v[52:55]
	v_mfma_f32_16x16x32_bf16 v[40:43], v[150:153], v[182:185], v[40:43]
	v_mfma_f32_16x16x32_bf16 v[36:39], v[158:161], v[182:185], v[36:39]
	v_mfma_f32_16x16x32_bf16 v[24:27], v[150:153], v[190:193], v[24:27]
	v_mfma_f32_16x16x32_bf16 v[16:19], v[158:161], v[190:193], v[16:19]
	s_setprio 1
	s_barrier
	s_add_u32 s24, s46, 0xb0000
	s_addc_u32 s25, s47, 0
	s_add_i32 s23, s26, s37
	v_lshl_add_u64 v[146:147], s[24:25], 0, v[132:133]
	s_mov_b32 m0, s23
	s_nop 0
	global_load_lds_dwordx4 v[146:147], off
	v_lshl_add_u64 v[146:147], s[24:25], 0, v[136:137]
	s_add_i32 m0, s23, 0x2000
	s_nop 0
	global_load_lds_dwordx4 v[146:147], off
	s_waitcnt vmcnt(6)
	s_barrier
	s_setprio 0
	v_mfma_f32_16x16x32_bf16 v[48:51], v[202:205], v[162:165], v[48:51]
	v_mfma_f32_16x16x32_bf16 v[44:47], v[210:213], v[162:165], v[44:47]
	v_mfma_f32_16x16x32_bf16 v[32:35], v[202:205], v[170:173], v[32:35]
	v_mfma_f32_16x16x32_bf16 v[28:31], v[210:213], v[170:173], v[28:31]
	v_mfma_f32_16x16x32_bf16 v[20:23], v[202:205], v[178:181], v[20:23]
	v_mfma_f32_16x16x32_bf16 v[12:15], v[210:213], v[178:181], v[12:15]
	v_mfma_f32_16x16x32_bf16 v[8:11], v[202:205], v[186:189], v[8:11]
	v_mfma_f32_16x16x32_bf16 v[4:7], v[210:213], v[186:189], v[4:7]
	v_mfma_f32_16x16x32_bf16 v[48:51], v[206:209], v[166:169], v[48:51]
	v_mfma_f32_16x16x32_bf16 v[44:47], v[214:217], v[166:169], v[44:47]
	v_mfma_f32_16x16x32_bf16 v[32:35], v[206:209], v[174:177], v[32:35]
	v_mfma_f32_16x16x32_bf16 v[28:31], v[214:217], v[174:177], v[28:31]
	v_mfma_f32_16x16x32_bf16 v[20:23], v[206:209], v[182:185], v[20:23]
	v_mfma_f32_16x16x32_bf16 v[12:15], v[214:217], v[182:185], v[12:15]
	v_mfma_f32_16x16x32_bf16 v[8:11], v[206:209], v[190:193], v[8:11]
	v_mfma_f32_16x16x32_bf16 v[4:7], v[214:217], v[190:193], v[4:7]
	s_setprio 1
	s_add_i32 s23, 0, 0x18000
	v_add_u32_e32 v145, s23, v143
	s_barrier
	ds_read_b128 v[146:149], v145
	ds_read_b128 v[150:153], v145 offset:1024
	ds_read_b128 v[154:157], v145 offset:2048
	ds_read_b128 v[158:161], v145 offset:3072
	s_add_u32 s24, s48, 0xb0000
	s_addc_u32 s25, s49, 0
	s_mov_b32 m0, s54
	v_lshl_add_u64 v[202:203], s[24:25], 0, v[0:1]
	ds_read_b128 v[162:165], v144 offset:32768
	ds_read_b128 v[166:169], v144 offset:33792
	ds_read_b128 v[170:173], v144 offset:34816
	ds_read_b128 v[174:177], v144 offset:35840
	ds_read_b128 v[178:181], v144 offset:36864
	ds_read_b128 v[182:185], v144 offset:37888
	ds_read_b128 v[186:189], v144 offset:38912
	ds_read_b128 v[190:193], v144 offset:39936
	global_load_lds_dwordx4 v[202:203], off
	v_lshl_add_u64 v[202:203], s[24:25], 0, v[134:135]
	s_mov_b32 m0, s55
	s_nop 0
	global_load_lds_dwordx4 v[202:203], off
	s_waitcnt lgkmcnt(8)
	s_barrier
	s_waitcnt lgkmcnt(0)
	s_setprio 0
	s_waitcnt lgkmcnt(0)
	v_mfma_f32_16x16x32_bf16 v[128:131], v[146:149], v[162:165], v[128:131]
	v_mfma_f32_16x16x32_bf16 v[124:127], v[154:157], v[162:165], v[124:127]
	v_mfma_f32_16x16x32_bf16 v[120:123], v[146:149], v[170:173], v[120:123]
	v_mfma_f32_16x16x32_bf16 v[116:119], v[154:157], v[170:173], v[116:119]
	v_mfma_f32_16x16x32_bf16 v[104:107], v[146:149], v[178:181], v[104:107]
	v_mfma_f32_16x16x32_bf16 v[100:103], v[154:157], v[178:181], v[100:103]
	v_mfma_f32_16x16x32_bf16 v[88:91], v[146:149], v[186:189], v[88:91]
	v_mfma_f32_16x16x32_bf16 v[84:87], v[154:157], v[186:189], v[84:87]
	v_mfma_f32_16x16x32_bf16 v[128:131], v[150:153], v[166:169], v[128:131]
	v_mfma_f32_16x16x32_bf16 v[124:127], v[158:161], v[166:169], v[124:127]
	v_mfma_f32_16x16x32_bf16 v[120:123], v[150:153], v[174:177], v[120:123]
	v_mfma_f32_16x16x32_bf16 v[116:119], v[158:161], v[174:177], v[116:119]
	v_mfma_f32_16x16x32_bf16 v[104:107], v[150:153], v[182:185], v[104:107]
	v_mfma_f32_16x16x32_bf16 v[100:103], v[158:161], v[182:185], v[100:103]
	v_mfma_f32_16x16x32_bf16 v[88:91], v[150:153], v[190:193], v[88:91]
	v_mfma_f32_16x16x32_bf16 v[84:87], v[158:161], v[190:193], v[84:87]
	s_setprio 1
	s_barrier
	s_add_i32 s26, 0, 0x1c000
	s_add_i32 s23, s23, s37
	v_add_u32_e32 v145, s26, v143
	v_lshl_add_u64 v[194:195], v[194:195], 0, s[76:77]
	s_mov_b32 m0, s23
	ds_read_b128 v[202:205], v145
	ds_read_b128 v[206:209], v145 offset:1024
	ds_read_b128 v[210:213], v145 offset:2048
	ds_read_b128 v[214:217], v145 offset:3072
	global_load_lds_dwordx4 v[194:195], off
	v_lshl_add_u64 v[194:195], v[198:199], 0, s[76:77]
	s_add_i32 m0, s23, 0x2000
	s_nop 0
	global_load_lds_dwordx4 v[194:195], off
	s_barrier
	s_waitcnt lgkmcnt(0)
	s_setprio 0
	s_waitcnt lgkmcnt(0)
	v_mfma_f32_16x16x32_bf16 v[112:115], v[202:205], v[162:165], v[112:115]
	v_mfma_f32_16x16x32_bf16 v[108:111], v[210:213], v[162:165], v[108:111]
	v_mfma_f32_16x16x32_bf16 v[96:99], v[202:205], v[170:173], v[96:99]
	v_mfma_f32_16x16x32_bf16 v[92:95], v[210:213], v[170:173], v[92:95]
	v_mfma_f32_16x16x32_bf16 v[80:83], v[202:205], v[178:181], v[80:83]
	v_mfma_f32_16x16x32_bf16 v[76:79], v[210:213], v[178:181], v[76:79]
	v_mfma_f32_16x16x32_bf16 v[72:75], v[202:205], v[186:189], v[72:75]
	v_mfma_f32_16x16x32_bf16 v[68:71], v[210:213], v[186:189], v[68:71]
	v_mfma_f32_16x16x32_bf16 v[112:115], v[206:209], v[166:169], v[112:115]
	v_mfma_f32_16x16x32_bf16 v[108:111], v[214:217], v[166:169], v[108:111]
	v_mfma_f32_16x16x32_bf16 v[96:99], v[206:209], v[174:177], v[96:99]
	v_mfma_f32_16x16x32_bf16 v[92:95], v[214:217], v[174:177], v[92:95]
	v_mfma_f32_16x16x32_bf16 v[80:83], v[206:209], v[182:185], v[80:83]
	v_mfma_f32_16x16x32_bf16 v[76:79], v[214:217], v[182:185], v[76:79]
	v_mfma_f32_16x16x32_bf16 v[72:75], v[206:209], v[190:193], v[72:75]
	v_mfma_f32_16x16x32_bf16 v[68:71], v[214:217], v[190:193], v[68:71]
	s_setprio 1
	s_mov_b32 m0, s56
	v_lshl_add_u64 v[194:195], v[222:223], 0, s[76:77]
	s_barrier
	ds_read_b128 v[162:165], v144 offset:49152
	ds_read_b128 v[166:169], v144 offset:50176
	ds_read_b128 v[170:173], v144 offset:51200
	ds_read_b128 v[174:177], v144 offset:52224
	ds_read_b128 v[178:181], v144 offset:53248
	ds_read_b128 v[182:185], v144 offset:54272
	ds_read_b128 v[186:189], v144 offset:55296
	ds_read_b128 v[190:193], v144 offset:56320
	global_load_lds_dwordx4 v[194:195], off
	v_lshl_add_u64 v[194:195], v[236:237], 0, s[76:77]
	s_mov_b32 m0, s57
	s_nop 0
	global_load_lds_dwordx4 v[194:195], off
	s_barrier
	s_waitcnt lgkmcnt(0)
	s_setprio 0
	s_waitcnt lgkmcnt(0)
	v_mfma_f32_16x16x32_bf16 v[64:67], v[146:149], v[162:165], v[64:67]
	v_mfma_f32_16x16x32_bf16 v[60:63], v[154:157], v[162:165], v[60:63]
	v_mfma_f32_16x16x32_bf16 v[56:59], v[146:149], v[170:173], v[56:59]
	v_mfma_f32_16x16x32_bf16 v[52:55], v[154:157], v[170:173], v[52:55]
	v_mfma_f32_16x16x32_bf16 v[40:43], v[146:149], v[178:181], v[40:43]
	v_mfma_f32_16x16x32_bf16 v[36:39], v[154:157], v[178:181], v[36:39]
	v_mfma_f32_16x16x32_bf16 v[24:27], v[146:149], v[186:189], v[24:27]
	v_mfma_f32_16x16x32_bf16 v[16:19], v[154:157], v[186:189], v[16:19]
	v_mfma_f32_16x16x32_bf16 v[64:67], v[150:153], v[166:169], v[64:67]
	v_mfma_f32_16x16x32_bf16 v[60:63], v[158:161], v[166:169], v[60:63]
	v_mfma_f32_16x16x32_bf16 v[56:59], v[150:153], v[174:177], v[56:59]
	v_mfma_f32_16x16x32_bf16 v[52:55], v[158:161], v[174:177], v[52:55]
	v_mfma_f32_16x16x32_bf16 v[40:43], v[150:153], v[182:185], v[40:43]
	v_mfma_f32_16x16x32_bf16 v[36:39], v[158:161], v[182:185], v[36:39]
	v_mfma_f32_16x16x32_bf16 v[24:27], v[150:153], v[190:193], v[24:27]
	v_mfma_f32_16x16x32_bf16 v[16:19], v[158:161], v[190:193], v[16:19]
	s_setprio 1
	s_barrier
	s_add_u32 s24, s46, 0xb0080
	s_addc_u32 s25, s47, 0
	s_add_i32 s23, s26, s37
	v_lshl_add_u64 v[146:147], s[24:25], 0, v[132:133]
	s_mov_b32 m0, s23
	s_nop 0
	global_load_lds_dwordx4 v[146:147], off
	v_lshl_add_u64 v[146:147], s[24:25], 0, v[136:137]
	s_add_i32 m0, s23, 0x2000
	s_nop 0
	global_load_lds_dwordx4 v[146:147], off
	s_waitcnt vmcnt(6)
	s_barrier
	s_setprio 0
	v_mfma_f32_16x16x32_bf16 v[48:51], v[202:205], v[162:165], v[48:51]
	v_mfma_f32_16x16x32_bf16 v[44:47], v[210:213], v[162:165], v[44:47]
	v_mfma_f32_16x16x32_bf16 v[32:35], v[202:205], v[170:173], v[32:35]
	v_mfma_f32_16x16x32_bf16 v[28:31], v[210:213], v[170:173], v[28:31]
	v_mfma_f32_16x16x32_bf16 v[20:23], v[202:205], v[178:181], v[20:23]
	v_mfma_f32_16x16x32_bf16 v[12:15], v[210:213], v[178:181], v[12:15]
	v_mfma_f32_16x16x32_bf16 v[8:11], v[202:205], v[186:189], v[8:11]
	v_mfma_f32_16x16x32_bf16 v[4:7], v[210:213], v[186:189], v[4:7]
	v_mfma_f32_16x16x32_bf16 v[48:51], v[206:209], v[166:169], v[48:51]
	v_mfma_f32_16x16x32_bf16 v[44:47], v[214:217], v[166:169], v[44:47]
	v_mfma_f32_16x16x32_bf16 v[32:35], v[206:209], v[174:177], v[32:35]
	v_mfma_f32_16x16x32_bf16 v[28:31], v[214:217], v[174:177], v[28:31]
	v_mfma_f32_16x16x32_bf16 v[20:23], v[206:209], v[182:185], v[20:23]
	v_mfma_f32_16x16x32_bf16 v[12:15], v[214:217], v[182:185], v[12:15]
	v_mfma_f32_16x16x32_bf16 v[8:11], v[206:209], v[190:193], v[8:11]
	v_mfma_f32_16x16x32_bf16 v[4:7], v[214:217], v[190:193], v[4:7]
	s_setprio 1
	s_add_i32 s22, s22, 2
	s_add_u32 s20, s20, 0x100
	s_addc_u32 s21, s21, 0
	s_cmp_gt_u32 s22, 41
	s_mov_b64 s[42:43], s[44:45]
	s_barrier
	s_cbranch_scc0 .LBB0_58
	v_lshl_add_u32 v146, s61, 8, v142
	v_cvt_pk_bf16_f32 v72, v72, v73
	v_cvt_pk_bf16_f32 v73, v74, v75
	v_cvt_pk_bf16_f32 v74, v68, v69
	v_add_u32_e32 v68, 0x80, v146
	s_lshl_b32 s20, s62, 8
	v_ashrrev_i32_e32 v147, 31, v146
	v_readlane_b32 s22, v252, 10
	v_cvt_pk_bf16_f32 v112, v112, v113
	v_cvt_pk_bf16_f32 v113, v114, v115
	v_cvt_pk_bf16_f32 v114, v108, v109
	v_or_b32_e32 v108, 16, v146
	v_ashrrev_i32_e32 v69, 31, v68
	v_cvt_pk_bf16_f32 v48, v48, v49
	v_cvt_pk_bf16_f32 v49, v50, v51
	v_cvt_pk_bf16_f32 v50, v44, v45
	v_add_u32_e32 v44, 0x90, v146
	s_ashr_i32 s21, s20, 31
	v_lshlrev_b64 v[148:149], 11, v[146:147]
	v_readlane_b32 s23, v252, 11
	v_ashrrev_i32_e32 v109, 31, v108
	v_cvt_pk_bf16_f32 v96, v96, v97
	v_cvt_pk_bf16_f32 v97, v98, v99
	v_cvt_pk_bf16_f32 v98, v92, v93
	v_or_b32_e32 v92, 32, v146
	v_lshlrev_b64 v[68:69], 11, v[68:69]
	v_ashrrev_i32_e32 v45, 31, v44
	v_cvt_pk_bf16_f32 v32, v32, v33
	v_cvt_pk_bf16_f32 v33, v34, v35
	v_cvt_pk_bf16_f32 v34, v28, v29
	v_add_u32_e32 v28, 0xa0, v146
	v_lshl_add_u64 v[148:149], s[22:23], 0, v[148:149]
	s_lshl_b64 s[42:43], s[20:21], 1
	v_lshlrev_b64 v[108:109], 11, v[108:109]
	v_ashrrev_i32_e32 v93, 31, v92
	v_cvt_pk_bf16_f32 v80, v80, v81
	v_cvt_pk_bf16_f32 v81, v82, v83
	v_cvt_pk_bf16_f32 v82, v76, v77
	v_or_b32_e32 v76, 48, v146
	v_lshl_add_u64 v[68:69], s[22:23], 0, v[68:69]
	v_lshlrev_b64 v[44:45], 11, v[44:45]
	v_ashrrev_i32_e32 v29, 31, v28
	v_cvt_pk_bf16_f32 v20, v20, v21
	v_cvt_pk_bf16_f32 v21, v22, v23
	v_cvt_pk_bf16_f32 v22, v12, v13
	v_add_u32_e32 v12, 0xb0, v146
	v_lshl_add_u64 v[148:149], v[148:149], 0, s[42:43]
	v_lshl_add_u64 v[108:109], s[22:23], 0, v[108:109]
	v_lshlrev_b64 v[92:93], 11, v[92:93]
	v_ashrrev_i32_e32 v77, 31, v76
	v_lshl_add_u64 v[68:69], v[68:69], 0, s[42:43]
	v_lshl_add_u64 v[44:45], s[22:23], 0, v[44:45]
	v_lshlrev_b64 v[28:29], 11, v[28:29]
	v_ashrrev_i32_e32 v13, 31, v12
	v_lshl_add_u64 v[148:149], v[148:149], 0, s[72:73]
	v_lshl_add_u64 v[108:109], v[108:109], 0, s[42:43]
	v_lshl_add_u64 v[92:93], s[22:23], 0, v[92:93]
	v_lshlrev_b64 v[76:77], 11, v[76:77]
	v_lshl_add_u64 v[68:69], v[68:69], 0, s[72:73]
	v_lshl_add_u64 v[44:45], v[44:45], 0, s[42:43]
	v_lshl_add_u64 v[28:29], s[22:23], 0, v[28:29]
	v_lshlrev_b64 v[12:13], 11, v[12:13]
	v_lshl_add_u64 v[148:149], v[148:149], 0, v[2:3]
	v_cvt_pk_bf16_f32 v115, v110, v111
	v_lshl_add_u64 v[108:109], v[108:109], 0, s[72:73]
	v_lshl_add_u64 v[92:93], v[92:93], 0, s[42:43]
	v_lshl_add_u64 v[76:77], s[22:23], 0, v[76:77]
	v_lshl_add_u64 v[68:69], v[68:69], 0, v[2:3]
	v_cvt_pk_bf16_f32 v51, v46, v47
	v_lshl_add_u64 v[44:45], v[44:45], 0, s[72:73]
	v_lshl_add_u64 v[28:29], v[28:29], 0, s[42:43]
	v_lshl_add_u64 v[12:13], s[22:23], 0, v[12:13]
	global_store_dwordx4 v[148:149], v[112:115], off offset:256
	v_cvt_pk_bf16_f32 v99, v94, v95
	v_lshl_add_u64 v[92:93], v[92:93], 0, s[72:73]
	v_lshl_add_u64 v[112:113], v[108:109], 0, v[2:3]
	v_lshl_add_u64 v[76:77], v[76:77], 0, s[42:43]
	global_store_dwordx4 v[68:69], v[48:51], off offset:256
	v_cvt_pk_bf16_f32 v35, v30, v31
	v_lshl_add_u64 v[28:29], v[28:29], 0, s[72:73]
	v_lshl_add_u64 v[48:49], v[44:45], 0, v[2:3]
	v_lshl_add_u64 v[12:13], v[12:13], 0, s[42:43]
	global_store_dwordx4 v[112:113], v[96:99], off offset:256
	v_cvt_pk_bf16_f32 v83, v78, v79
	v_lshl_add_u64 v[76:77], v[76:77], 0, s[72:73]
	v_lshl_add_u64 v[96:97], v[92:93], 0, v[2:3]
	global_store_dwordx4 v[48:49], v[32:35], off offset:256
	v_cvt_pk_bf16_f32 v23, v14, v15
	v_lshl_add_u64 v[12:13], v[12:13], 0, s[72:73]
	v_lshl_add_u64 v[32:33], v[28:29], 0, v[2:3]
	v_cvt_pk_bf16_f32 v128, v128, v129
	v_cvt_pk_bf16_f32 v129, v130, v131
	v_cvt_pk_bf16_f32 v130, v124, v125
	v_cvt_pk_bf16_f32 v131, v126, v127
	v_cvt_pk_bf16_f32 v108, v120, v121
	v_cvt_pk_bf16_f32 v109, v122, v123
	v_cvt_pk_bf16_f32 v110, v116, v117
	v_cvt_pk_bf16_f32 v111, v118, v119
	v_cvt_pk_bf16_f32 v92, v104, v105
	v_cvt_pk_bf16_f32 v93, v106, v107
	v_cvt_pk_bf16_f32 v94, v100, v101
	v_cvt_pk_bf16_f32 v95, v102, v103
	global_store_dwordx4 v[96:97], v[80:83], off offset:256
	v_cvt_pk_bf16_f32 v78, v84, v85
	v_cvt_pk_bf16_f32 v79, v86, v87
	v_lshl_add_u64 v[80:81], v[76:77], 0, v[2:3]
	v_cvt_pk_bf16_f32 v76, v88, v89
	v_cvt_pk_bf16_f32 v77, v90, v91
	v_cvt_pk_bf16_f32 v75, v70, v71
	v_cvt_pk_bf16_f32 v64, v64, v65
	v_cvt_pk_bf16_f32 v65, v66, v67
	v_cvt_pk_bf16_f32 v66, v60, v61
	v_cvt_pk_bf16_f32 v67, v62, v63
	v_cvt_pk_bf16_f32 v44, v56, v57
	v_cvt_pk_bf16_f32 v45, v58, v59
	v_cvt_pk_bf16_f32 v46, v52, v53
	v_cvt_pk_bf16_f32 v47, v54, v55
	v_cvt_pk_bf16_f32 v28, v40, v41
	v_cvt_pk_bf16_f32 v29, v42, v43
	v_cvt_pk_bf16_f32 v30, v36, v37
	v_cvt_pk_bf16_f32 v31, v38, v39
	global_store_dwordx4 v[32:33], v[20:23], off offset:256
	v_cvt_pk_bf16_f32 v14, v16, v17
	v_cvt_pk_bf16_f32 v15, v18, v19
	v_lshl_add_u64 v[20:21], v[12:13], 0, v[2:3]
	v_cvt_pk_bf16_f32 v12, v24, v25
	v_cvt_pk_bf16_f32 v13, v26, v27
	v_cvt_pk_bf16_f32 v8, v8, v9
	v_cvt_pk_bf16_f32 v9, v10, v11
	v_cvt_pk_bf16_f32 v10, v4, v5
	v_cvt_pk_bf16_f32 v11, v6, v7
	s_and_b64 vcc, exec, s[38:39]
	s_mov_b32 s62, s59
	s_mov_b32 s61, s60
	s_mov_b64 s[44:45], s[40:41]
	s_mov_b64 s[42:43], s[0:1]
	global_store_dwordx4 v[148:149], v[128:131], off
	global_store_dwordx4 v[112:113], v[108:111], off
	global_store_dwordx4 v[96:97], v[92:95], off
	global_store_dwordx4 v[80:81], v[76:79], off
	global_store_dwordx4 v[80:81], v[72:75], off offset:256
	global_store_dwordx4 v[68:69], v[64:67], off
	global_store_dwordx4 v[48:49], v[44:47], off
	global_store_dwordx4 v[32:33], v[28:31], off
	global_store_dwordx4 v[20:21], v[12:15], off
	global_store_dwordx4 v[20:21], v[8:11], off offset:256
	s_cbranch_vccz .LBB0_51
	s_waitcnt vmcnt(0)
	s_cmpk_gt_u32 s36, 0xff
	s_cbranch_scc1 .LBB0_62
	s_barrier

.LBB0_80:
	s_add_u32 s22, s52, 0xfffc0080
	s_addc_u32 s23, s53, -1
	s_add_i32 s24, 0, 0x10000
	v_add_u32_e32 v64, s24, v235
	ds_read_b128 v[52:55], v64
	ds_read_b128 v[56:59], v64 offset:1024
	ds_read_b128 v[60:63], v64 offset:2048
	ds_read_b128 v[64:67], v64 offset:3072
	s_cmp_eq_u32 s21, 12
	s_cselect_b32 s57, s47, s23
	s_cselect_b32 s56, s46, s22
	s_cselect_b32 s55, s49, s20
	s_cselect_b32 s54, s48, s1
	v_lshl_add_u64 v[116:117], s[52:53], 0, v[206:207]
	s_add_i32 m0, s62, 0xc000
	ds_read_b128 v[76:79], v239
	ds_read_b128 v[80:83], v239 offset:1024
	ds_read_b128 v[84:87], v239 offset:2048
	ds_read_b128 v[88:91], v239 offset:3072
	ds_read_b128 v[92:95], v239 offset:4096
	ds_read_b128 v[96:99], v239 offset:5120
	ds_read_b128 v[100:103], v239 offset:6144
	ds_read_b128 v[104:107], v239 offset:7168
	global_load_lds_dwordx4 v[116:117], off
	v_lshl_add_u64 v[116:117], s[52:53], 0, v[208:209]
	s_add_i32 m0, s62, 0xe000
	s_nop 0
	global_load_lds_dwordx4 v[116:117], off
	s_waitcnt lgkmcnt(8)
	s_barrier
	s_waitcnt lgkmcnt(0)
	s_setprio 0
	s_waitcnt lgkmcnt(0)
	v_mfma_f32_16x16x32_bf16 v[160:163], v[52:55], v[92:95], v[160:163]
	v_mfma_f32_16x16x32_bf16 v[152:155], v[60:63], v[92:95], v[152:155]
	v_mfma_f32_16x16x32_bf16 v[144:147], v[52:55], v[100:103], v[144:147]
	v_mfma_f32_16x16x32_bf16 v[140:143], v[60:63], v[100:103], v[140:143]
	v_mfma_f32_16x16x32_bf16 v[116:119], v[52:55], v[76:79], v[192:195]
	v_mfma_f32_16x16x32_bf16 v[120:123], v[60:63], v[76:79], v[184:187]
	v_mfma_f32_16x16x32_bf16 v[124:127], v[52:55], v[84:87], v[176:179]
	v_mfma_f32_16x16x32_bf16 v[128:131], v[60:63], v[84:87], v[168:171]
	v_mfma_f32_16x16x32_bf16 v[160:163], v[56:59], v[96:99], v[160:163]
	v_mfma_f32_16x16x32_bf16 v[152:155], v[64:67], v[96:99], v[152:155]
	v_mfma_f32_16x16x32_bf16 v[144:147], v[56:59], v[104:107], v[144:147]
	v_mfma_f32_16x16x32_bf16 v[140:143], v[64:67], v[104:107], v[140:143]
	v_mfma_f32_16x16x32_bf16 v[116:119], v[56:59], v[80:83], v[116:119]
	v_mfma_f32_16x16x32_bf16 v[120:123], v[64:67], v[80:83], v[120:123]
	v_mfma_f32_16x16x32_bf16 v[124:127], v[56:59], v[88:91], v[124:127]
	v_mfma_f32_16x16x32_bf16 v[128:131], v[64:67], v[88:91], v[128:131]
	s_setprio 1
	s_barrier
	s_add_i32 s25, 0, 0x14000
	s_add_i32 s22, s24, s60
	v_add_u32_e32 v192, s25, v235
	v_lshl_add_u64 v[198:199], s[54:55], 0, v[2:3]
	s_mov_b32 m0, s22
	ds_read_b128 v[168:171], v192
	ds_read_b128 v[176:179], v192 offset:1024
	ds_read_b128 v[184:187], v192 offset:2048
	ds_read_b128 v[192:195], v192 offset:3072
	global_load_lds_dwordx4 v[198:199], off
	v_lshl_add_u64 v[222:223], s[54:55], 0, v[0:1]
	s_add_i32 m0, s22, 0x2000
	s_nop 0
	global_load_lds_dwordx4 v[222:223], off
	s_barrier
	s_waitcnt lgkmcnt(0)
	s_setprio 0
	s_waitcnt lgkmcnt(0)
	v_mfma_f32_16x16x32_bf16 v[188:191], v[168:171], v[76:79], v[188:191]
	v_mfma_f32_16x16x32_bf16 v[76:79], v[184:187], v[76:79], v[180:183]
	v_mfma_f32_16x16x32_bf16 v[188:191], v[176:179], v[80:83], v[188:191]
	v_mfma_f32_16x16x32_bf16 v[76:79], v[192:195], v[80:83], v[76:79]
	v_mfma_f32_16x16x32_bf16 v[80:83], v[168:171], v[84:87], v[172:175]
	v_mfma_f32_16x16x32_bf16 v[84:87], v[184:187], v[84:87], v[164:167]
	v_mfma_f32_16x16x32_bf16 v[80:83], v[176:179], v[88:91], v[80:83]
	v_mfma_f32_16x16x32_bf16 v[84:87], v[192:195], v[88:91], v[84:87]
	v_mfma_f32_16x16x32_bf16 v[88:91], v[168:171], v[92:95], v[156:159]
	v_mfma_f32_16x16x32_bf16 v[92:95], v[184:187], v[92:95], v[148:151]
	v_mfma_f32_16x16x32_bf16 v[88:91], v[176:179], v[96:99], v[88:91]
	v_mfma_f32_16x16x32_bf16 v[92:95], v[192:195], v[96:99], v[92:95]
	v_mfma_f32_16x16x32_bf16 v[96:99], v[168:171], v[100:103], v[136:139]
	v_mfma_f32_16x16x32_bf16 v[100:103], v[184:187], v[100:103], v[132:135]
	v_mfma_f32_16x16x32_bf16 v[96:99], v[176:179], v[104:107], v[96:99]
	v_mfma_f32_16x16x32_bf16 v[100:103], v[192:195], v[104:107], v[100:103]
	s_setprio 1
	s_mov_b32 m0, s62
	v_lshl_add_u64 v[248:249], s[56:57], 0, v[204:205]
	s_barrier
	ds_read_b128 v[104:107], v239 offset:16384
	ds_read_b128 v[132:135], v239 offset:17408
	ds_read_b128 v[136:139], v239 offset:18432
	ds_read_b128 v[148:151], v239 offset:19456
	ds_read_b128 v[156:159], v239 offset:20480
	ds_read_b128 v[164:167], v239 offset:21504
	ds_read_b128 v[172:175], v239 offset:22528
	ds_read_b128 v[180:183], v239 offset:23552
	global_load_lds_dwordx4 v[248:249], off
	v_lshl_add_u64 v[250:251], s[56:57], 0, v[202:203]
	s_mov_b32 m0, s63
	s_nop 0
	global_load_lds_dwordx4 v[250:251], off
	s_barrier
	s_waitcnt lgkmcnt(0)
	s_setprio 0
	s_waitcnt lgkmcnt(0)
	v_mfma_f32_16x16x32_bf16 v[112:115], v[52:55], v[104:107], v[112:115]
	v_mfma_f32_16x16x32_bf16 v[72:75], v[60:63], v[104:107], v[72:75]
	v_mfma_f32_16x16x32_bf16 v[48:51], v[52:55], v[136:139], v[48:51]
	v_mfma_f32_16x16x32_bf16 v[40:43], v[60:63], v[136:139], v[40:43]
	v_mfma_f32_16x16x32_bf16 v[32:35], v[52:55], v[156:159], v[32:35]
	v_mfma_f32_16x16x32_bf16 v[24:27], v[60:63], v[156:159], v[24:27]
	v_mfma_f32_16x16x32_bf16 v[16:19], v[52:55], v[172:175], v[16:19]
	v_mfma_f32_16x16x32_bf16 v[12:15], v[60:63], v[172:175], v[12:15]
	v_mfma_f32_16x16x32_bf16 v[112:115], v[56:59], v[132:135], v[112:115]
	v_mfma_f32_16x16x32_bf16 v[72:75], v[64:67], v[132:135], v[72:75]
	v_mfma_f32_16x16x32_bf16 v[48:51], v[56:59], v[148:151], v[48:51]
	v_mfma_f32_16x16x32_bf16 v[40:43], v[64:67], v[148:151], v[40:43]
	v_mfma_f32_16x16x32_bf16 v[32:35], v[56:59], v[164:167], v[32:35]
	v_mfma_f32_16x16x32_bf16 v[24:27], v[64:67], v[164:167], v[24:27]
	v_mfma_f32_16x16x32_bf16 v[16:19], v[56:59], v[180:183], v[16:19]
	v_mfma_f32_16x16x32_bf16 v[12:15], v[64:67], v[180:183], v[12:15]
	s_setprio 1
	s_barrier
	s_add_u32 s22, s54, 0x40000
	s_addc_u32 s23, s55, 0
	s_add_i32 s24, s25, s60
	v_lshl_add_u64 v[52:53], s[22:23], 0, v[2:3]
	s_mov_b32 m0, s24
	s_nop 0
	global_load_lds_dwordx4 v[52:53], off
	v_lshl_add_u64 v[52:53], s[22:23], 0, v[0:1]
	s_add_i32 m0, s24, 0x2000
	s_nop 0
	global_load_lds_dwordx4 v[52:53], off
	s_waitcnt vmcnt(6)
	s_barrier
	s_setprio 0
	v_mfma_f32_16x16x32_bf16 v[44:47], v[168:171], v[136:139], v[44:47]
	v_mfma_f32_16x16x32_bf16 v[36:39], v[184:187], v[136:139], v[36:39]
	v_mfma_f32_16x16x32_bf16 v[28:31], v[168:171], v[156:159], v[28:31]
	v_mfma_f32_16x16x32_bf16 v[20:23], v[184:187], v[156:159], v[20:23]
	v_mfma_f32_16x16x32_bf16 v[8:11], v[168:171], v[172:175], v[8:11]
	v_mfma_f32_16x16x32_bf16 v[4:7], v[184:187], v[172:175], v[4:7]
	v_mfma_f32_16x16x32_bf16 v[52:55], v[168:171], v[104:107], v[108:111]
	v_mfma_f32_16x16x32_bf16 v[56:59], v[184:187], v[104:107], v[68:71]
	v_mfma_f32_16x16x32_bf16 v[44:47], v[176:179], v[148:151], v[44:47]
	v_mfma_f32_16x16x32_bf16 v[36:39], v[192:195], v[148:151], v[36:39]
	v_mfma_f32_16x16x32_bf16 v[28:31], v[176:179], v[164:167], v[28:31]
	v_mfma_f32_16x16x32_bf16 v[20:23], v[192:195], v[164:167], v[20:23]
	v_mfma_f32_16x16x32_bf16 v[8:11], v[176:179], v[180:183], v[8:11]
	v_mfma_f32_16x16x32_bf16 v[4:7], v[192:195], v[180:183], v[4:7]
	v_mfma_f32_16x16x32_bf16 v[52:55], v[176:179], v[132:135], v[52:55]
	v_mfma_f32_16x16x32_bf16 v[56:59], v[192:195], v[132:135], v[56:59]
	s_setprio 1
	s_add_i32 s24, 0, 0x18000
	v_add_u32_e32 v104, s24, v235
	s_barrier
	ds_read_b128 v[60:63], v104
	ds_read_b128 v[64:67], v104 offset:1024
	ds_read_b128 v[68:71], v104 offset:2048
	ds_read_b128 v[104:107], v104 offset:3072
	s_add_u32 s22, s56, 0x40000
	s_addc_u32 s23, s57, 0
	s_mov_b32 m0, s64
	v_lshl_add_u64 v[156:157], s[22:23], 0, v[204:205]
	ds_read_b128 v[108:111], v239 offset:32768
	ds_read_b128 v[132:135], v239 offset:33792
	ds_read_b128 v[136:139], v239 offset:34816
	ds_read_b128 v[148:151], v239 offset:35840
	ds_read_b128 v[210:213], v239 offset:36864
	ds_read_b128 v[214:217], v239 offset:37888
	ds_read_b128 v[240:243], v239 offset:38912
	ds_read_b128 v[244:247], v239 offset:39936
	global_load_lds_dwordx4 v[156:157], off
	v_lshl_add_u64 v[156:157], s[22:23], 0, v[202:203]
	s_mov_b32 m0, s65
	s_nop 0
	global_load_lds_dwordx4 v[156:157], off
	s_waitcnt lgkmcnt(8)
	s_barrier
	s_waitcnt lgkmcnt(0)
	s_setprio 0
	s_waitcnt lgkmcnt(0)
	v_mfma_f32_16x16x32_bf16 v[116:119], v[60:63], v[108:111], v[116:119]
	v_mfma_f32_16x16x32_bf16 v[192:195], v[64:67], v[132:135], v[116:119]
	v_mfma_f32_16x16x32_bf16 v[116:119], v[68:71], v[108:111], v[120:123]
	v_mfma_f32_16x16x32_bf16 v[184:187], v[104:107], v[132:135], v[116:119]
	v_mfma_f32_16x16x32_bf16 v[116:119], v[60:63], v[136:139], v[124:127]
	v_mfma_f32_16x16x32_bf16 v[176:179], v[64:67], v[148:151], v[116:119]
	v_mfma_f32_16x16x32_bf16 v[116:119], v[68:71], v[136:139], v[128:131]
	v_mfma_f32_16x16x32_bf16 v[168:171], v[104:107], v[148:151], v[116:119]
	v_mfma_f32_16x16x32_bf16 v[116:119], v[60:63], v[210:213], v[160:163]
	v_mfma_f32_16x16x32_bf16 v[160:163], v[64:67], v[214:217], v[116:119]
	v_mfma_f32_16x16x32_bf16 v[116:119], v[68:71], v[210:213], v[152:155]
	v_mfma_f32_16x16x32_bf16 v[152:155], v[104:107], v[214:217], v[116:119]
	v_mfma_f32_16x16x32_bf16 v[116:119], v[60:63], v[240:243], v[144:147]
	v_mfma_f32_16x16x32_bf16 v[144:147], v[64:67], v[244:247], v[116:119]
	v_mfma_f32_16x16x32_bf16 v[116:119], v[68:71], v[240:243], v[140:143]
	v_mfma_f32_16x16x32_bf16 v[140:143], v[104:107], v[244:247], v[116:119]
	s_setprio 1
	s_barrier
	s_add_i32 s25, 0, 0x1c000
	s_add_i32 s22, s24, s60
	v_add_u32_e32 v128, s25, v235
	v_lshl_add_u64 v[156:157], v[198:199], 0, s[76:77]
	s_mov_b32 m0, s22
	ds_read_b128 v[116:119], v128
	ds_read_b128 v[120:123], v128 offset:1024
	ds_read_b128 v[124:127], v128 offset:2048
	ds_read_b128 v[128:131], v128 offset:3072
	global_load_lds_dwordx4 v[156:157], off
	v_lshl_add_u64 v[156:157], v[222:223], 0, s[76:77]
	s_add_i32 m0, s22, 0x2000
	s_nop 0
	global_load_lds_dwordx4 v[156:157], off
	s_barrier
	s_waitcnt lgkmcnt(0)
	s_setprio 0
	s_waitcnt lgkmcnt(0)
	v_mfma_f32_16x16x32_bf16 v[76:79], v[124:127], v[108:111], v[76:79]
	v_mfma_f32_16x16x32_bf16 v[180:183], v[128:131], v[132:135], v[76:79]
	v_mfma_f32_16x16x32_bf16 v[76:79], v[116:119], v[136:139], v[80:83]
	v_mfma_f32_16x16x32_bf16 v[172:175], v[120:123], v[148:151], v[76:79]
	v_mfma_f32_16x16x32_bf16 v[76:79], v[124:127], v[136:139], v[84:87]
	v_mfma_f32_16x16x32_bf16 v[156:159], v[116:119], v[108:111], v[188:191]
	v_mfma_f32_16x16x32_bf16 v[164:167], v[128:131], v[148:151], v[76:79]
	v_mfma_f32_16x16x32_bf16 v[76:79], v[116:119], v[210:213], v[88:91]
	v_mfma_f32_16x16x32_bf16 v[188:191], v[120:123], v[132:135], v[156:159]
	v_mfma_f32_16x16x32_bf16 v[156:159], v[120:123], v[214:217], v[76:79]
	v_mfma_f32_16x16x32_bf16 v[76:79], v[124:127], v[210:213], v[92:95]
	v_mfma_f32_16x16x32_bf16 v[148:151], v[128:131], v[214:217], v[76:79]
	v_mfma_f32_16x16x32_bf16 v[76:79], v[116:119], v[240:243], v[96:99]
	v_mfma_f32_16x16x32_bf16 v[136:139], v[120:123], v[244:247], v[76:79]
	v_mfma_f32_16x16x32_bf16 v[76:79], v[124:127], v[240:243], v[100:103]
	v_mfma_f32_16x16x32_bf16 v[132:135], v[128:131], v[244:247], v[76:79]
	s_setprio 1
	s_mov_b32 m0, s72
	v_lshl_add_u64 v[108:109], v[248:249], 0, s[76:77]
	s_barrier
	s_nop 2
	ds_read_b128 v[76:79], v239 offset:49152
	ds_read_b128 v[80:83], v239 offset:50176
	ds_read_b128 v[84:87], v239 offset:51200
	ds_read_b128 v[88:91], v239 offset:52224
	ds_read_b128 v[92:95], v239 offset:53248
	ds_read_b128 v[96:99], v239 offset:54272
	ds_read_b128 v[100:103], v239 offset:55296
	ds_read_b128 v[210:213], v239 offset:56320
	global_load_lds_dwordx4 v[108:109], off
	v_lshl_add_u64 v[108:109], v[250:251], 0, s[76:77]
	s_mov_b32 m0, s74
	s_nop 0
	global_load_lds_dwordx4 v[108:109], off
	s_barrier
	s_waitcnt lgkmcnt(0)
	s_setprio 0
	s_waitcnt lgkmcnt(0)
	v_mfma_f32_16x16x32_bf16 v[108:111], v[60:63], v[76:79], v[112:115]
	v_mfma_f32_16x16x32_bf16 v[72:75], v[68:71], v[76:79], v[72:75]
	v_mfma_f32_16x16x32_bf16 v[48:51], v[60:63], v[84:87], v[48:51]
	v_mfma_f32_16x16x32_bf16 v[40:43], v[68:71], v[84:87], v[40:43]
	v_mfma_f32_16x16x32_bf16 v[32:35], v[60:63], v[92:95], v[32:35]
	v_mfma_f32_16x16x32_bf16 v[24:27], v[68:71], v[92:95], v[24:27]
	v_mfma_f32_16x16x32_bf16 v[16:19], v[60:63], v[100:103], v[16:19]
	v_mfma_f32_16x16x32_bf16 v[12:15], v[68:71], v[100:103], v[12:15]
	v_mfma_f32_16x16x32_bf16 v[112:115], v[64:67], v[80:83], v[108:111]
	v_mfma_f32_16x16x32_bf16 v[72:75], v[104:107], v[80:83], v[72:75]
	v_mfma_f32_16x16x32_bf16 v[48:51], v[64:67], v[88:91], v[48:51]
	v_mfma_f32_16x16x32_bf16 v[40:43], v[104:107], v[88:91], v[40:43]
	v_mfma_f32_16x16x32_bf16 v[32:35], v[64:67], v[96:99], v[32:35]
	v_mfma_f32_16x16x32_bf16 v[24:27], v[104:107], v[96:99], v[24:27]
	v_mfma_f32_16x16x32_bf16 v[16:19], v[64:67], v[210:213], v[16:19]
	v_mfma_f32_16x16x32_bf16 v[12:15], v[104:107], v[210:213], v[12:15]
	s_setprio 1
	s_barrier
	s_add_u32 s22, s54, 0x40080
	s_addc_u32 s23, s55, 0
	s_add_i32 s24, s25, s60
	v_lshl_add_u64 v[60:61], s[22:23], 0, v[2:3]
	s_mov_b32 m0, s24
	s_nop 0
	global_load_lds_dwordx4 v[60:61], off
	v_lshl_add_u64 v[60:61], s[22:23], 0, v[0:1]
	s_add_i32 m0, s24, 0x2000
	s_nop 0
	global_load_lds_dwordx4 v[60:61], off
	s_waitcnt vmcnt(6)
	s_barrier
	s_setprio 0
	v_mfma_f32_16x16x32_bf16 v[52:55], v[116:119], v[76:79], v[52:55]
	v_mfma_f32_16x16x32_bf16 v[108:111], v[120:123], v[80:83], v[52:55]
	v_mfma_f32_16x16x32_bf16 v[52:55], v[124:127], v[76:79], v[56:59]
	v_mfma_f32_16x16x32_bf16 v[44:47], v[116:119], v[84:87], v[44:47]
	v_mfma_f32_16x16x32_bf16 v[36:39], v[124:127], v[84:87], v[36:39]
	v_mfma_f32_16x16x32_bf16 v[28:31], v[116:119], v[92:95], v[28:31]
	v_mfma_f32_16x16x32_bf16 v[20:23], v[124:127], v[92:95], v[20:23]
	v_mfma_f32_16x16x32_bf16 v[8:11], v[116:119], v[100:103], v[8:11]
	v_mfma_f32_16x16x32_bf16 v[4:7], v[124:127], v[100:103], v[4:7]
	v_mfma_f32_16x16x32_bf16 v[68:71], v[128:131], v[80:83], v[52:55]
	v_mfma_f32_16x16x32_bf16 v[44:47], v[120:123], v[88:91], v[44:47]
	v_mfma_f32_16x16x32_bf16 v[36:39], v[128:131], v[88:91], v[36:39]
	v_mfma_f32_16x16x32_bf16 v[28:31], v[120:123], v[96:99], v[28:31]
	v_mfma_f32_16x16x32_bf16 v[20:23], v[128:131], v[96:99], v[20:23]
	v_mfma_f32_16x16x32_bf16 v[8:11], v[120:123], v[210:213], v[8:11]
	v_mfma_f32_16x16x32_bf16 v[4:7], v[128:131], v[210:213], v[4:7]
	s_setprio 1
	s_add_i32 s21, s21, 2
	s_add_u32 s52, s52, 0x100
	s_addc_u32 s53, s53, 0
	s_add_u32 s1, s1, 0x100
	s_addc_u32 s20, s20, 0
	s_cmp_gt_u32 s21, 13
	s_barrier
	s_cbranch_scc0 .LBB0_80
	v_lshl_or_b32 v210, s30, 7, v238
	s_lshl_b32 s1, s50, 8
	s_add_i32 s1, s1, s67
	v_lshlrev_b32_e32 v211, 2, v210
	v_lshlrev_b32_e32 v219, 1, v210
	v_readlane_b32 s2, v252, 4
	v_readlane_b32 s3, v252, 5
	v_readlane_b32 s20, v252, 20
	v_readlane_b32 s21, v252, 21
	v_readlane_b32 s22, v252, 2
	v_readlane_b32 s23, v252, 3
	v_readlane_b32 s24, v252, 22
	v_readlane_b32 s25, v252, 23
	v_readlane_b32 s26, v252, 24
	v_readlane_b32 s27, v252, 25
	v_readlane_b32 s50, v252, 26
	v_readlane_b32 s51, v252, 27
	v_readlane_b32 s56, v252, 28
	v_readlane_b32 s57, v252, 29
	v_readlane_b32 s98, v252, 30
	v_readlane_b32 s99, v252, 31
	v_lshl_add_u32 v240, v201, 2, s1
	v_mul_u32_u24_e32 v240, 0x1600, v240
	v_add_u32_e32 v240, v240, v219
	global_load_dwordx4 v[120:123], v211, s[2:3]
	global_load_dwordx4 v[80:83], v211, s[2:3] offset:16
	global_load_dwordx4 v[116:119], v211, s[20:21]
	global_load_dwordx4 v[76:79], v211, s[20:21] offset:16
	global_load_dwordx4 v[96:99], v211, s[22:23]
	global_load_dwordx4 v[56:59], v211, s[22:23] offset:16
	global_load_dwordx4 v[92:95], v211, s[24:25]
	global_load_dwordx4 v[52:55], v211, s[24:25] offset:16
	global_load_dwordx4 v[104:107], v211, s[26:27]
	global_load_dwordx4 v[64:67], v211, s[26:27] offset:16
	global_load_dwordx4 v[100:103], v211, s[50:51]
	global_load_dwordx4 v[60:63], v211, s[50:51] offset:16
	global_load_dwordx4 v[124:127], v211, s[56:57]
	global_load_dwordx4 v[84:87], v211, s[56:57] offset:16
	global_load_dwordx4 v[128:131], v211, s[98:99]
	global_load_dwordx4 v[88:91], v211, s[98:99] offset:16
	v_readlane_b32 s56, v254, 63
	v_readlane_b32 s57, v255, 0
	v_cmp_eq_u32_e64 s[2:3], 0, v201
	v_cmp_eq_u32_e64 s[26:27], 15, v201
	s_lshr_b32 s24, s1, 4
	s_mov_b64 exec, s[2:3]
	v_cvt_pk_bf16_f32 v212, v192, v193
	v_cvt_pk_bf16_f32 v213, v194, v195
	v_cvt_pk_bf16_f32 v214, v184, v185
	v_cvt_pk_bf16_f32 v215, v186, v187
	s_add_i32 s20, s24, 2
	s_mulk_i32 s20, 0x2c00
	s_add_u32 s22, s56, s20
	s_addc_u32 s23, s57, 0
	global_store_dwordx4 v219, v[212:215], s[22:23]
	v_cvt_pk_bf16_f32 v242, v188, v189
	v_cvt_pk_bf16_f32 v243, v190, v191
	v_cvt_pk_bf16_f32 v244, v180, v181
	v_cvt_pk_bf16_f32 v245, v182, v183
	s_add_u32 s22, s22, 0x1600
	s_addc_u32 s23, s23, 0
	global_store_dwordx4 v219, v[242:245], s[22:23]
	v_cvt_pk_bf16_f32 v246, v176, v177
	v_cvt_pk_bf16_f32 v247, v178, v179
	v_cvt_pk_bf16_f32 v248, v168, v169
	v_cvt_pk_bf16_f32 v249, v170, v171
	s_add_i32 s20, s24, 3
	s_mulk_i32 s20, 0x2c00
	s_add_u32 s22, s56, s20
	s_addc_u32 s23, s57, 0
	global_store_dwordx4 v219, v[246:249], s[22:23]
	v_cvt_pk_bf16_f32 v212, v172, v173
	v_cvt_pk_bf16_f32 v213, v174, v175
	v_cvt_pk_bf16_f32 v214, v164, v165
	v_cvt_pk_bf16_f32 v215, v166, v167
	s_add_u32 s22, s22, 0x1600
	s_addc_u32 s23, s23, 0
	global_store_dwordx4 v219, v[212:215], s[22:23]
	s_mov_b64 exec, s[26:27]
	v_cvt_pk_bf16_f32 v242, v160, v161
	v_cvt_pk_bf16_f32 v243, v162, v163
	v_cvt_pk_bf16_f32 v244, v152, v153
	v_cvt_pk_bf16_f32 v245, v154, v155
	s_add_i32 s20, s24, 0
	s_mulk_i32 s20, 0x2c00
	s_add_u32 s22, s56, s20
	s_addc_u32 s23, s57, 0
	global_store_dwordx4 v219, v[242:245], s[22:23]
	v_cvt_pk_bf16_f32 v246, v156, v157
	v_cvt_pk_bf16_f32 v247, v158, v159
	v_cvt_pk_bf16_f32 v248, v148, v149
	v_cvt_pk_bf16_f32 v249, v150, v151
	s_add_u32 s22, s22, 0x1600
	s_addc_u32 s23, s23, 0
	global_store_dwordx4 v219, v[246:249], s[22:23]
	v_cvt_pk_bf16_f32 v212, v144, v145
	v_cvt_pk_bf16_f32 v213, v146, v147
	v_cvt_pk_bf16_f32 v214, v140, v141
	v_cvt_pk_bf16_f32 v215, v142, v143
	s_add_i32 s20, s24, 1
	s_mulk_i32 s20, 0x2c00
	s_add_u32 s22, s56, s20
	s_addc_u32 s23, s57, 0
	global_store_dwordx4 v219, v[212:215], s[22:23]
	v_cvt_pk_bf16_f32 v242, v136, v137
	v_cvt_pk_bf16_f32 v243, v138, v139
	v_cvt_pk_bf16_f32 v244, v132, v133
	v_cvt_pk_bf16_f32 v245, v134, v135
	s_add_u32 s22, s22, 0x1600
	s_addc_u32 s23, s23, 0
	global_store_dwordx4 v219, v[242:245], s[22:23]
	s_mov_b64 exec, s[2:3]
	v_cvt_pk_bf16_f32 v246, v112, v113
	v_cvt_pk_bf16_f32 v247, v114, v115
	v_cvt_pk_bf16_f32 v248, v72, v73
	v_cvt_pk_bf16_f32 v249, v74, v75
	s_add_i32 s20, s24, 10
	s_mulk_i32 s20, 0x2c00
	s_add_u32 s22, s56, s20
	s_addc_u32 s23, s57, 0
	global_store_dwordx4 v219, v[246:249], s[22:23]
	v_cvt_pk_bf16_f32 v212, v108, v109
	v_cvt_pk_bf16_f32 v213, v110, v111
	v_cvt_pk_bf16_f32 v214, v68, v69
	v_cvt_pk_bf16_f32 v215, v70, v71
	s_add_u32 s22, s22, 0x1600
	s_addc_u32 s23, s23, 0
	global_store_dwordx4 v219, v[212:215], s[22:23]
	v_cvt_pk_bf16_f32 v242, v48, v49
	v_cvt_pk_bf16_f32 v243, v50, v51
	v_cvt_pk_bf16_f32 v244, v40, v41
	v_cvt_pk_bf16_f32 v245, v42, v43
	s_add_i32 s20, s24, 11
	s_mulk_i32 s20, 0x2c00
	s_add_u32 s22, s56, s20
	s_addc_u32 s23, s57, 0
	global_store_dwordx4 v219, v[242:245], s[22:23]
	v_cvt_pk_bf16_f32 v246, v44, v45
	v_cvt_pk_bf16_f32 v247, v46, v47
	v_cvt_pk_bf16_f32 v248, v36, v37
	v_cvt_pk_bf16_f32 v249, v38, v39
	s_add_u32 s22, s22, 0x1600
	s_addc_u32 s23, s23, 0
	global_store_dwordx4 v219, v[246:249], s[22:23]
	s_mov_b64 exec, s[26:27]
	v_cvt_pk_bf16_f32 v212, v32, v33
	v_cvt_pk_bf16_f32 v213, v34, v35
	v_cvt_pk_bf16_f32 v214, v24, v25
	v_cvt_pk_bf16_f32 v215, v26, v27
	s_add_i32 s20, s24, 8
	s_mulk_i32 s20, 0x2c00
	s_add_u32 s22, s56, s20
	s_addc_u32 s23, s57, 0
	global_store_dwordx4 v219, v[212:215], s[22:23]
	v_cvt_pk_bf16_f32 v242, v28, v29
	v_cvt_pk_bf16_f32 v243, v30, v31
	v_cvt_pk_bf16_f32 v244, v20, v21
	v_cvt_pk_bf16_f32 v245, v22, v23
	s_add_u32 s22, s22, 0x1600
	s_addc_u32 s23, s23, 0
	global_store_dwordx4 v219, v[242:245], s[22:23]
	v_cvt_pk_bf16_f32 v246, v16, v17
	v_cvt_pk_bf16_f32 v247, v18, v19
	v_cvt_pk_bf16_f32 v248, v12, v13
	v_cvt_pk_bf16_f32 v249, v14, v15
	s_add_i32 s20, s24, 9
	s_mulk_i32 s20, 0x2c00
	s_add_u32 s22, s56, s20
	s_addc_u32 s23, s57, 0
	global_store_dwordx4 v219, v[246:249], s[22:23]
	v_cvt_pk_bf16_f32 v212, v8, v9
	v_cvt_pk_bf16_f32 v213, v10, v11
	v_cvt_pk_bf16_f32 v214, v4, v5
	v_cvt_pk_bf16_f32 v215, v6, v7
	s_add_u32 s22, s22, 0x1600
	s_addc_u32 s23, s23, 0
	global_store_dwordx4 v219, v[212:215], s[22:23]
	s_mov_b64 exec, -1
	s_mov_b32 s50, 0xbfb8aa3b
	s_mov_b32 s51, 0xbfb8aa3b
	s_waitcnt vmcnt(16)
	v_mov_b32_dpp v198, v144 row_shr:1 row_mask:0xf bank_mask:0xf bound_ctrl:1
	v_mov_b32_dpp v199, v145 row_shr:1 row_mask:0xf bank_mask:0xf bound_ctrl:1
	v_mov_b32_dpp v214, v136 row_shr:1 row_mask:0xf bank_mask:0xf bound_ctrl:1
	v_mov_b32_dpp v215, v137 row_shr:1 row_mask:0xf bank_mask:0xf bound_ctrl:1
	v_mov_b32_dpp v212, v160 row_shr:1 row_mask:0xf bank_mask:0xf bound_ctrl:1
	v_mov_b32_dpp v213, v161 row_shr:1 row_mask:0xf bank_mask:0xf bound_ctrl:1
	v_mov_b32_dpp v216, v156 row_shr:1 row_mask:0xf bank_mask:0xf bound_ctrl:1
	v_mov_b32_dpp v217, v157 row_shr:1 row_mask:0xf bank_mask:0xf bound_ctrl:1
	v_pk_fma_f32 v[144:145], v[144:145], v[124:125], v[120:121]
	v_pk_fma_f32 v[136:137], v[136:137], v[128:129], v[116:117]
	v_pk_fma_f32 v[144:145], v[160:161], v[104:105], v[144:145]
	v_pk_fma_f32 v[136:137], v[156:157], v[100:101], v[136:137]
	v_pk_fma_f32 v[144:145], v[176:177], v[96:97], v[144:145]
	v_pk_fma_f32 v[136:137], v[172:173], v[92:93], v[136:137]
	v_pk_fma_f32 v[160:161], v[160:161], v[124:125], v[120:121]
	v_pk_fma_f32 v[156:157], v[156:157], v[128:129], v[116:117]
	v_pk_fma_f32 v[160:161], v[176:177], v[104:105], v[160:161]
	v_pk_fma_f32 v[156:157], v[172:173], v[100:101], v[156:157]
	v_pk_fma_f32 v[160:161], v[192:193], v[96:97], v[160:161]
	v_pk_fma_f32 v[156:157], v[188:189], v[92:93], v[156:157]
	v_pk_fma_f32 v[176:177], v[176:177], v[124:125], v[120:121]
	v_pk_fma_f32 v[172:173], v[172:173], v[128:129], v[116:117]
	v_pk_fma_f32 v[176:177], v[192:193], v[104:105], v[176:177]
	v_pk_fma_f32 v[172:173], v[188:189], v[100:101], v[172:173]
	v_pk_fma_f32 v[176:177], v[198:199], v[96:97], v[176:177]
	v_pk_fma_f32 v[172:173], v[214:215], v[92:93], v[172:173]
	v_pk_fma_f32 v[192:193], v[192:193], v[124:125], v[120:121]
	v_pk_fma_f32 v[188:189], v[188:189], v[128:129], v[116:117]
	v_pk_fma_f32 v[192:193], v[198:199], v[104:105], v[192:193]
	v_pk_fma_f32 v[188:189], v[214:215], v[100:101], v[188:189]
	v_pk_fma_f32 v[192:193], v[212:213], v[96:97], v[192:193]
	v_pk_fma_f32 v[188:189], v[216:217], v[92:93], v[188:189]
	v_pk_mul_f32 v[222:223], v[192:193], s[50:51]
	v_pk_mul_f32 v[242:243], v[176:177], s[50:51]
	v_pk_mul_f32 v[244:245], v[160:161], s[50:51]
	v_pk_mul_f32 v[246:247], v[144:145], s[50:51]
	v_exp_f32_e32 v222, v222
	v_exp_f32_e32 v223, v223
	v_exp_f32_e32 v242, v242
	v_exp_f32_e32 v243, v243
	v_exp_f32_e32 v244, v244
	v_exp_f32_e32 v245, v245
	v_exp_f32_e32 v246, v246
	v_exp_f32_e32 v247, v247
	v_pk_add_f32 v[222:223], v[222:223], 1.0 op_sel_hi:[1,0]
	v_pk_add_f32 v[242:243], v[242:243], 1.0 op_sel_hi:[1,0]
	v_pk_add_f32 v[244:245], v[244:245], 1.0 op_sel_hi:[1,0]
	v_pk_add_f32 v[246:247], v[246:247], 1.0 op_sel_hi:[1,0]
	v_rcp_f32_e32 v222, v222
	v_rcp_f32_e32 v223, v223
	v_rcp_f32_e32 v242, v242
	v_rcp_f32_e32 v243, v243
	v_rcp_f32_e32 v244, v244
	v_rcp_f32_e32 v245, v245
	v_rcp_f32_e32 v246, v246
	v_rcp_f32_e32 v247, v247
	v_pk_mul_f32 v[192:193], v[192:193], v[222:223]
	v_pk_mul_f32 v[176:177], v[176:177], v[242:243]
	v_pk_mul_f32 v[160:161], v[160:161], v[244:245]
	v_pk_mul_f32 v[144:145], v[144:145], v[246:247]
	v_pk_mul_f32 v[192:193], v[192:193], v[188:189]
	v_pk_mul_f32 v[176:177], v[176:177], v[172:173]
	v_pk_mul_f32 v[160:161], v[160:161], v[156:157]
	v_pk_mul_f32 v[144:145], v[144:145], v[136:137]
	v_cvt_pk_bf16_f32 v192, v192, v193
	v_cvt_pk_bf16_f32 v176, v176, v177
	v_cvt_pk_bf16_f32 v160, v160, v161
	v_cvt_pk_bf16_f32 v144, v144, v145
	v_mov_b32_dpp v198, v146 row_shr:1 row_mask:0xf bank_mask:0xf bound_ctrl:1
	v_mov_b32_dpp v199, v147 row_shr:1 row_mask:0xf bank_mask:0xf bound_ctrl:1
	v_mov_b32_dpp v214, v138 row_shr:1 row_mask:0xf bank_mask:0xf bound_ctrl:1
	v_mov_b32_dpp v215, v139 row_shr:1 row_mask:0xf bank_mask:0xf bound_ctrl:1
	v_mov_b32_dpp v212, v162 row_shr:1 row_mask:0xf bank_mask:0xf bound_ctrl:1
	v_mov_b32_dpp v213, v163 row_shr:1 row_mask:0xf bank_mask:0xf bound_ctrl:1
	v_mov_b32_dpp v216, v158 row_shr:1 row_mask:0xf bank_mask:0xf bound_ctrl:1
	v_mov_b32_dpp v217, v159 row_shr:1 row_mask:0xf bank_mask:0xf bound_ctrl:1
	v_pk_fma_f32 v[146:147], v[146:147], v[126:127], v[122:123]
	v_pk_fma_f32 v[138:139], v[138:139], v[130:131], v[118:119]
	v_pk_fma_f32 v[146:147], v[162:163], v[106:107], v[146:147]
	v_pk_fma_f32 v[138:139], v[158:159], v[102:103], v[138:139]
	v_pk_fma_f32 v[146:147], v[178:179], v[98:99], v[146:147]
	v_pk_fma_f32 v[138:139], v[174:175], v[94:95], v[138:139]
	v_pk_fma_f32 v[162:163], v[162:163], v[126:127], v[122:123]
	v_pk_fma_f32 v[158:159], v[158:159], v[130:131], v[118:119]
	v_pk_fma_f32 v[162:163], v[178:179], v[106:107], v[162:163]
	v_pk_fma_f32 v[158:159], v[174:175], v[102:103], v[158:159]
	v_pk_fma_f32 v[162:163], v[194:195], v[98:99], v[162:163]
	v_pk_fma_f32 v[158:159], v[190:191], v[94:95], v[158:159]
	v_pk_fma_f32 v[178:179], v[178:179], v[126:127], v[122:123]
	v_pk_fma_f32 v[174:175], v[174:175], v[130:131], v[118:119]
	v_pk_fma_f32 v[178:179], v[194:195], v[106:107], v[178:179]
	v_pk_fma_f32 v[174:175], v[190:191], v[102:103], v[174:175]
	v_pk_fma_f32 v[178:179], v[198:199], v[98:99], v[178:179]
	v_pk_fma_f32 v[174:175], v[214:215], v[94:95], v[174:175]
	v_pk_fma_f32 v[194:195], v[194:195], v[126:127], v[122:123]
	v_pk_fma_f32 v[190:191], v[190:191], v[130:131], v[118:119]
	v_pk_fma_f32 v[194:195], v[198:199], v[106:107], v[194:195]
	v_pk_fma_f32 v[190:191], v[214:215], v[102:103], v[190:191]
	v_pk_fma_f32 v[194:195], v[212:213], v[98:99], v[194:195]
	v_pk_fma_f32 v[190:191], v[216:217], v[94:95], v[190:191]
	v_pk_mul_f32 v[222:223], v[194:195], s[50:51]
	v_pk_mul_f32 v[242:243], v[178:179], s[50:51]
	v_pk_mul_f32 v[244:245], v[162:163], s[50:51]
	v_pk_mul_f32 v[246:247], v[146:147], s[50:51]
	v_exp_f32_e32 v222, v222
	v_exp_f32_e32 v223, v223
	v_exp_f32_e32 v242, v242
	v_exp_f32_e32 v243, v243
	v_exp_f32_e32 v244, v244
	v_exp_f32_e32 v245, v245
	v_exp_f32_e32 v246, v246
	v_exp_f32_e32 v247, v247
	v_pk_add_f32 v[222:223], v[222:223], 1.0 op_sel_hi:[1,0]
	v_pk_add_f32 v[242:243], v[242:243], 1.0 op_sel_hi:[1,0]
	v_pk_add_f32 v[244:245], v[244:245], 1.0 op_sel_hi:[1,0]
	v_pk_add_f32 v[246:247], v[246:247], 1.0 op_sel_hi:[1,0]
	v_rcp_f32_e32 v222, v222
	v_rcp_f32_e32 v223, v223
	v_rcp_f32_e32 v242, v242
	v_rcp_f32_e32 v243, v243
	v_rcp_f32_e32 v244, v244
	v_rcp_f32_e32 v245, v245
	v_rcp_f32_e32 v246, v246
	v_rcp_f32_e32 v247, v247
	v_pk_mul_f32 v[194:195], v[194:195], v[222:223]
	v_pk_mul_f32 v[178:179], v[178:179], v[242:243]
	v_pk_mul_f32 v[162:163], v[162:163], v[244:245]
	v_pk_mul_f32 v[146:147], v[146:147], v[246:247]
	v_pk_mul_f32 v[194:195], v[194:195], v[190:191]
	v_pk_mul_f32 v[178:179], v[178:179], v[174:175]
	v_pk_mul_f32 v[162:163], v[162:163], v[158:159]
	v_pk_mul_f32 v[146:147], v[146:147], v[138:139]
	v_cvt_pk_bf16_f32 v193, v194, v195
	v_cvt_pk_bf16_f32 v177, v178, v179
	v_cvt_pk_bf16_f32 v161, v162, v163
	v_cvt_pk_bf16_f32 v145, v146, v147
	v_mov_b32_dpp v198, v140 row_shr:1 row_mask:0xf bank_mask:0xf bound_ctrl:1
	v_mov_b32_dpp v199, v141 row_shr:1 row_mask:0xf bank_mask:0xf bound_ctrl:1
	v_mov_b32_dpp v214, v132 row_shr:1 row_mask:0xf bank_mask:0xf bound_ctrl:1
	v_mov_b32_dpp v215, v133 row_shr:1 row_mask:0xf bank_mask:0xf bound_ctrl:1
	v_mov_b32_dpp v212, v152 row_shr:1 row_mask:0xf bank_mask:0xf bound_ctrl:1
	v_mov_b32_dpp v213, v153 row_shr:1 row_mask:0xf bank_mask:0xf bound_ctrl:1
	v_mov_b32_dpp v216, v148 row_shr:1 row_mask:0xf bank_mask:0xf bound_ctrl:1
	v_mov_b32_dpp v217, v149 row_shr:1 row_mask:0xf bank_mask:0xf bound_ctrl:1
	v_pk_fma_f32 v[140:141], v[140:141], v[84:85], v[80:81]
	v_pk_fma_f32 v[132:133], v[132:133], v[88:89], v[76:77]
	v_pk_fma_f32 v[140:141], v[152:153], v[64:65], v[140:141]
	v_pk_fma_f32 v[132:133], v[148:149], v[60:61], v[132:133]
	v_pk_fma_f32 v[140:141], v[168:169], v[56:57], v[140:141]
	v_pk_fma_f32 v[132:133], v[164:165], v[52:53], v[132:133]
	v_pk_fma_f32 v[152:153], v[152:153], v[84:85], v[80:81]
	v_pk_fma_f32 v[148:149], v[148:149], v[88:89], v[76:77]
	v_pk_fma_f32 v[152:153], v[168:169], v[64:65], v[152:153]
	v_pk_fma_f32 v[148:149], v[164:165], v[60:61], v[148:149]
	v_pk_fma_f32 v[152:153], v[184:185], v[56:57], v[152:153]
	v_pk_fma_f32 v[148:149], v[180:181], v[52:53], v[148:149]
	v_pk_fma_f32 v[168:169], v[168:169], v[84:85], v[80:81]
	v_pk_fma_f32 v[164:165], v[164:165], v[88:89], v[76:77]
	v_pk_fma_f32 v[168:169], v[184:185], v[64:65], v[168:169]
	v_pk_fma_f32 v[164:165], v[180:181], v[60:61], v[164:165]
	v_pk_fma_f32 v[168:169], v[198:199], v[56:57], v[168:169]
	v_pk_fma_f32 v[164:165], v[214:215], v[52:53], v[164:165]
	v_pk_fma_f32 v[184:185], v[184:185], v[84:85], v[80:81]
	v_pk_fma_f32 v[180:181], v[180:181], v[88:89], v[76:77]
	v_pk_fma_f32 v[184:185], v[198:199], v[64:65], v[184:185]
	v_pk_fma_f32 v[180:181], v[214:215], v[60:61], v[180:181]
	v_pk_fma_f32 v[184:185], v[212:213], v[56:57], v[184:185]
	v_pk_fma_f32 v[180:181], v[216:217], v[52:53], v[180:181]
	v_pk_mul_f32 v[222:223], v[184:185], s[50:51]
	v_pk_mul_f32 v[242:243], v[168:169], s[50:51]
	v_pk_mul_f32 v[244:245], v[152:153], s[50:51]
	v_pk_mul_f32 v[246:247], v[140:141], s[50:51]
	v_exp_f32_e32 v222, v222
	v_exp_f32_e32 v223, v223
	v_exp_f32_e32 v242, v242
	v_exp_f32_e32 v243, v243
	v_exp_f32_e32 v244, v244
	v_exp_f32_e32 v245, v245
	v_exp_f32_e32 v246, v246
	v_exp_f32_e32 v247, v247
	v_pk_add_f32 v[222:223], v[222:223], 1.0 op_sel_hi:[1,0]
	v_pk_add_f32 v[242:243], v[242:243], 1.0 op_sel_hi:[1,0]
	v_pk_add_f32 v[244:245], v[244:245], 1.0 op_sel_hi:[1,0]
	v_pk_add_f32 v[246:247], v[246:247], 1.0 op_sel_hi:[1,0]
	v_rcp_f32_e32 v222, v222
	v_rcp_f32_e32 v223, v223
	v_rcp_f32_e32 v242, v242
	v_rcp_f32_e32 v243, v243
	v_rcp_f32_e32 v244, v244
	v_rcp_f32_e32 v245, v245
	v_rcp_f32_e32 v246, v246
	v_rcp_f32_e32 v247, v247
	v_pk_mul_f32 v[184:185], v[184:185], v[222:223]
	v_pk_mul_f32 v[168:169], v[168:169], v[242:243]
	v_pk_mul_f32 v[152:153], v[152:153], v[244:245]
	v_pk_mul_f32 v[140:141], v[140:141], v[246:247]
	v_pk_mul_f32 v[184:185], v[184:185], v[180:181]
	v_pk_mul_f32 v[168:169], v[168:169], v[164:165]
	v_pk_mul_f32 v[152:153], v[152:153], v[148:149]
	v_pk_mul_f32 v[140:141], v[140:141], v[132:133]
	v_cvt_pk_bf16_f32 v194, v184, v185
	v_cvt_pk_bf16_f32 v178, v168, v169
	v_cvt_pk_bf16_f32 v162, v152, v153
	v_cvt_pk_bf16_f32 v146, v140, v141
	v_mov_b32_dpp v198, v142 row_shr:1 row_mask:0xf bank_mask:0xf bound_ctrl:1
	v_mov_b32_dpp v199, v143 row_shr:1 row_mask:0xf bank_mask:0xf bound_ctrl:1
	v_mov_b32_dpp v214, v134 row_shr:1 row_mask:0xf bank_mask:0xf bound_ctrl:1
	v_mov_b32_dpp v215, v135 row_shr:1 row_mask:0xf bank_mask:0xf bound_ctrl:1
	v_mov_b32_dpp v212, v154 row_shr:1 row_mask:0xf bank_mask:0xf bound_ctrl:1
	v_mov_b32_dpp v213, v155 row_shr:1 row_mask:0xf bank_mask:0xf bound_ctrl:1
	v_mov_b32_dpp v216, v150 row_shr:1 row_mask:0xf bank_mask:0xf bound_ctrl:1
	v_mov_b32_dpp v217, v151 row_shr:1 row_mask:0xf bank_mask:0xf bound_ctrl:1
	v_pk_fma_f32 v[142:143], v[142:143], v[86:87], v[82:83]
	v_pk_fma_f32 v[134:135], v[134:135], v[90:91], v[78:79]
	v_pk_fma_f32 v[142:143], v[154:155], v[66:67], v[142:143]
	v_pk_fma_f32 v[134:135], v[150:151], v[62:63], v[134:135]
	v_pk_fma_f32 v[142:143], v[170:171], v[58:59], v[142:143]
	v_pk_fma_f32 v[134:135], v[166:167], v[54:55], v[134:135]
	v_pk_fma_f32 v[154:155], v[154:155], v[86:87], v[82:83]
	v_pk_fma_f32 v[150:151], v[150:151], v[90:91], v[78:79]
	v_pk_fma_f32 v[154:155], v[170:171], v[66:67], v[154:155]
	v_pk_fma_f32 v[150:151], v[166:167], v[62:63], v[150:151]
	v_pk_fma_f32 v[154:155], v[186:187], v[58:59], v[154:155]
	v_pk_fma_f32 v[150:151], v[182:183], v[54:55], v[150:151]
	v_pk_fma_f32 v[170:171], v[170:171], v[86:87], v[82:83]
	v_pk_fma_f32 v[166:167], v[166:167], v[90:91], v[78:79]
	v_pk_fma_f32 v[170:171], v[186:187], v[66:67], v[170:171]
	v_pk_fma_f32 v[166:167], v[182:183], v[62:63], v[166:167]
	v_pk_fma_f32 v[170:171], v[198:199], v[58:59], v[170:171]
	v_pk_fma_f32 v[166:167], v[214:215], v[54:55], v[166:167]
	v_pk_fma_f32 v[186:187], v[186:187], v[86:87], v[82:83]
	v_pk_fma_f32 v[182:183], v[182:183], v[90:91], v[78:79]
	v_pk_fma_f32 v[186:187], v[198:199], v[66:67], v[186:187]
	v_pk_fma_f32 v[182:183], v[214:215], v[62:63], v[182:183]
	v_pk_fma_f32 v[186:187], v[212:213], v[58:59], v[186:187]
	v_pk_fma_f32 v[182:183], v[216:217], v[54:55], v[182:183]
	v_pk_mul_f32 v[222:223], v[186:187], s[50:51]
	v_pk_mul_f32 v[242:243], v[170:171], s[50:51]
	v_pk_mul_f32 v[244:245], v[154:155], s[50:51]
	v_pk_mul_f32 v[246:247], v[142:143], s[50:51]
	v_exp_f32_e32 v222, v222
	v_exp_f32_e32 v223, v223
	v_exp_f32_e32 v242, v242
	v_exp_f32_e32 v243, v243
	v_exp_f32_e32 v244, v244
	v_exp_f32_e32 v245, v245
	v_exp_f32_e32 v246, v246
	v_exp_f32_e32 v247, v247
	v_pk_add_f32 v[222:223], v[222:223], 1.0 op_sel_hi:[1,0]
	v_pk_add_f32 v[242:243], v[242:243], 1.0 op_sel_hi:[1,0]
	v_pk_add_f32 v[244:245], v[244:245], 1.0 op_sel_hi:[1,0]
	v_pk_add_f32 v[246:247], v[246:247], 1.0 op_sel_hi:[1,0]
	v_rcp_f32_e32 v222, v222
	v_rcp_f32_e32 v223, v223
	v_rcp_f32_e32 v242, v242
	v_rcp_f32_e32 v243, v243
	v_rcp_f32_e32 v244, v244
	v_rcp_f32_e32 v245, v245
	v_rcp_f32_e32 v246, v246
	v_rcp_f32_e32 v247, v247
	v_pk_mul_f32 v[186:187], v[186:187], v[222:223]
	v_pk_mul_f32 v[170:171], v[170:171], v[242:243]
	v_pk_mul_f32 v[154:155], v[154:155], v[244:245]
	v_pk_mul_f32 v[142:143], v[142:143], v[246:247]
	v_pk_mul_f32 v[186:187], v[186:187], v[182:183]
	v_pk_mul_f32 v[170:171], v[170:171], v[166:167]
	v_pk_mul_f32 v[154:155], v[154:155], v[150:151]
	v_pk_mul_f32 v[142:143], v[142:143], v[134:135]
	v_cvt_pk_bf16_f32 v195, v186, v187
	v_cvt_pk_bf16_f32 v179, v170, v171
	v_cvt_pk_bf16_f32 v163, v154, v155
	v_cvt_pk_bf16_f32 v147, v142, v143
	s_mov_b64 s[20:21], s[82:83]
	global_store_dwordx4 v240, v[192:195], s[20:21]
	s_add_u32 s20, s82, 0x1600
	s_addc_u32 s21, s83, 0
	global_store_dwordx4 v240, v[176:179], s[20:21]
	s_add_u32 s20, s82, 0x2c00
	s_addc_u32 s21, s83, 0
	global_store_dwordx4 v240, v[160:163], s[20:21]
	s_add_u32 s20, s82, 0x4200
	s_addc_u32 s21, s83, 0
	global_store_dwordx4 v240, v[144:147], s[20:21]
	v_mov_b32_dpp v198, v16 row_shr:1 row_mask:0xf bank_mask:0xf bound_ctrl:1
	v_mov_b32_dpp v199, v17 row_shr:1 row_mask:0xf bank_mask:0xf bound_ctrl:1
	v_mov_b32_dpp v214, v8 row_shr:1 row_mask:0xf bank_mask:0xf bound_ctrl:1
	v_mov_b32_dpp v215, v9 row_shr:1 row_mask:0xf bank_mask:0xf bound_ctrl:1
	v_mov_b32_dpp v212, v32 row_shr:1 row_mask:0xf bank_mask:0xf bound_ctrl:1
	v_mov_b32_dpp v213, v33 row_shr:1 row_mask:0xf bank_mask:0xf bound_ctrl:1
	v_mov_b32_dpp v216, v28 row_shr:1 row_mask:0xf bank_mask:0xf bound_ctrl:1
	v_mov_b32_dpp v217, v29 row_shr:1 row_mask:0xf bank_mask:0xf bound_ctrl:1
	v_pk_fma_f32 v[16:17], v[16:17], v[124:125], v[120:121]
	v_pk_fma_f32 v[8:9], v[8:9], v[128:129], v[116:117]
	v_pk_fma_f32 v[16:17], v[32:33], v[104:105], v[16:17]
	v_pk_fma_f32 v[8:9], v[28:29], v[100:101], v[8:9]
	v_pk_fma_f32 v[16:17], v[48:49], v[96:97], v[16:17]
	v_pk_fma_f32 v[8:9], v[44:45], v[92:93], v[8:9]
	v_pk_fma_f32 v[32:33], v[32:33], v[124:125], v[120:121]
	v_pk_fma_f32 v[28:29], v[28:29], v[128:129], v[116:117]
	v_pk_fma_f32 v[32:33], v[48:49], v[104:105], v[32:33]
	v_pk_fma_f32 v[28:29], v[44:45], v[100:101], v[28:29]
	v_pk_fma_f32 v[32:33], v[112:113], v[96:97], v[32:33]
	v_pk_fma_f32 v[28:29], v[108:109], v[92:93], v[28:29]
	v_pk_fma_f32 v[48:49], v[48:49], v[124:125], v[120:121]
	v_pk_fma_f32 v[44:45], v[44:45], v[128:129], v[116:117]
	v_pk_fma_f32 v[48:49], v[112:113], v[104:105], v[48:49]
	v_pk_fma_f32 v[44:45], v[108:109], v[100:101], v[44:45]
	v_pk_fma_f32 v[48:49], v[198:199], v[96:97], v[48:49]
	v_pk_fma_f32 v[44:45], v[214:215], v[92:93], v[44:45]
	v_pk_fma_f32 v[112:113], v[112:113], v[124:125], v[120:121]
	v_pk_fma_f32 v[108:109], v[108:109], v[128:129], v[116:117]
	v_pk_fma_f32 v[112:113], v[198:199], v[104:105], v[112:113]
	v_pk_fma_f32 v[108:109], v[214:215], v[100:101], v[108:109]
	v_pk_fma_f32 v[112:113], v[212:213], v[96:97], v[112:113]
	v_pk_fma_f32 v[108:109], v[216:217], v[92:93], v[108:109]
	v_pk_mul_f32 v[222:223], v[112:113], s[50:51]
	v_pk_mul_f32 v[242:243], v[48:49], s[50:51]
	v_pk_mul_f32 v[244:245], v[32:33], s[50:51]
	v_pk_mul_f32 v[246:247], v[16:17], s[50:51]
	v_exp_f32_e32 v222, v222
	v_exp_f32_e32 v223, v223
	v_exp_f32_e32 v242, v242
	v_exp_f32_e32 v243, v243
	v_exp_f32_e32 v244, v244
	v_exp_f32_e32 v245, v245
	v_exp_f32_e32 v246, v246
	v_exp_f32_e32 v247, v247
	v_pk_add_f32 v[222:223], v[222:223], 1.0 op_sel_hi:[1,0]
	v_pk_add_f32 v[242:243], v[242:243], 1.0 op_sel_hi:[1,0]
	v_pk_add_f32 v[244:245], v[244:245], 1.0 op_sel_hi:[1,0]
	v_pk_add_f32 v[246:247], v[246:247], 1.0 op_sel_hi:[1,0]
	v_rcp_f32_e32 v222, v222
	v_rcp_f32_e32 v223, v223
	v_rcp_f32_e32 v242, v242
	v_rcp_f32_e32 v243, v243
	v_rcp_f32_e32 v244, v244
	v_rcp_f32_e32 v245, v245
	v_rcp_f32_e32 v246, v246
	v_rcp_f32_e32 v247, v247
	v_pk_mul_f32 v[112:113], v[112:113], v[222:223]
	v_pk_mul_f32 v[48:49], v[48:49], v[242:243]
	v_pk_mul_f32 v[32:33], v[32:33], v[244:245]
	v_pk_mul_f32 v[16:17], v[16:17], v[246:247]
	v_pk_mul_f32 v[112:113], v[112:113], v[108:109]
	v_pk_mul_f32 v[48:49], v[48:49], v[44:45]
	v_pk_mul_f32 v[32:33], v[32:33], v[28:29]
	v_pk_mul_f32 v[16:17], v[16:17], v[8:9]
	v_cvt_pk_bf16_f32 v112, v112, v113
	v_cvt_pk_bf16_f32 v48, v48, v49
	v_cvt_pk_bf16_f32 v32, v32, v33
	v_cvt_pk_bf16_f32 v16, v16, v17
	v_mov_b32_dpp v198, v18 row_shr:1 row_mask:0xf bank_mask:0xf bound_ctrl:1
	v_mov_b32_dpp v199, v19 row_shr:1 row_mask:0xf bank_mask:0xf bound_ctrl:1
	v_mov_b32_dpp v214, v10 row_shr:1 row_mask:0xf bank_mask:0xf bound_ctrl:1
	v_mov_b32_dpp v215, v11 row_shr:1 row_mask:0xf bank_mask:0xf bound_ctrl:1
	v_mov_b32_dpp v212, v34 row_shr:1 row_mask:0xf bank_mask:0xf bound_ctrl:1
	v_mov_b32_dpp v213, v35 row_shr:1 row_mask:0xf bank_mask:0xf bound_ctrl:1
	v_mov_b32_dpp v216, v30 row_shr:1 row_mask:0xf bank_mask:0xf bound_ctrl:1
	v_mov_b32_dpp v217, v31 row_shr:1 row_mask:0xf bank_mask:0xf bound_ctrl:1
	v_pk_fma_f32 v[18:19], v[18:19], v[126:127], v[122:123]
	v_pk_fma_f32 v[10:11], v[10:11], v[130:131], v[118:119]
	v_pk_fma_f32 v[18:19], v[34:35], v[106:107], v[18:19]
	v_pk_fma_f32 v[10:11], v[30:31], v[102:103], v[10:11]
	v_pk_fma_f32 v[18:19], v[50:51], v[98:99], v[18:19]
	v_pk_fma_f32 v[10:11], v[46:47], v[94:95], v[10:11]
	v_pk_fma_f32 v[34:35], v[34:35], v[126:127], v[122:123]
	v_pk_fma_f32 v[30:31], v[30:31], v[130:131], v[118:119]
	v_pk_fma_f32 v[34:35], v[50:51], v[106:107], v[34:35]
	v_pk_fma_f32 v[30:31], v[46:47], v[102:103], v[30:31]
	v_pk_fma_f32 v[34:35], v[114:115], v[98:99], v[34:35]
	v_pk_fma_f32 v[30:31], v[110:111], v[94:95], v[30:31]
	v_pk_fma_f32 v[50:51], v[50:51], v[126:127], v[122:123]
	v_pk_fma_f32 v[46:47], v[46:47], v[130:131], v[118:119]
	v_pk_fma_f32 v[50:51], v[114:115], v[106:107], v[50:51]
	v_pk_fma_f32 v[46:47], v[110:111], v[102:103], v[46:47]
	v_pk_fma_f32 v[50:51], v[198:199], v[98:99], v[50:51]
	v_pk_fma_f32 v[46:47], v[214:215], v[94:95], v[46:47]
	v_pk_fma_f32 v[114:115], v[114:115], v[126:127], v[122:123]
	v_pk_fma_f32 v[110:111], v[110:111], v[130:131], v[118:119]
	v_pk_fma_f32 v[114:115], v[198:199], v[106:107], v[114:115]
	v_pk_fma_f32 v[110:111], v[214:215], v[102:103], v[110:111]
	v_pk_fma_f32 v[114:115], v[212:213], v[98:99], v[114:115]
	v_pk_fma_f32 v[110:111], v[216:217], v[94:95], v[110:111]
	v_pk_mul_f32 v[222:223], v[114:115], s[50:51]
	v_pk_mul_f32 v[242:243], v[50:51], s[50:51]
	v_pk_mul_f32 v[244:245], v[34:35], s[50:51]
	v_pk_mul_f32 v[246:247], v[18:19], s[50:51]
	v_exp_f32_e32 v222, v222
	v_exp_f32_e32 v223, v223
	v_exp_f32_e32 v242, v242
	v_exp_f32_e32 v243, v243
	v_exp_f32_e32 v244, v244
	v_exp_f32_e32 v245, v245
	v_exp_f32_e32 v246, v246
	v_exp_f32_e32 v247, v247
	v_pk_add_f32 v[222:223], v[222:223], 1.0 op_sel_hi:[1,0]
	v_pk_add_f32 v[242:243], v[242:243], 1.0 op_sel_hi:[1,0]
	v_pk_add_f32 v[244:245], v[244:245], 1.0 op_sel_hi:[1,0]
	v_pk_add_f32 v[246:247], v[246:247], 1.0 op_sel_hi:[1,0]
	v_rcp_f32_e32 v222, v222
	v_rcp_f32_e32 v223, v223
	v_rcp_f32_e32 v242, v242
	v_rcp_f32_e32 v243, v243
	v_rcp_f32_e32 v244, v244
	v_rcp_f32_e32 v245, v245
	v_rcp_f32_e32 v246, v246
	v_rcp_f32_e32 v247, v247
	v_pk_mul_f32 v[114:115], v[114:115], v[222:223]
	v_pk_mul_f32 v[50:51], v[50:51], v[242:243]
	v_pk_mul_f32 v[34:35], v[34:35], v[244:245]
	v_pk_mul_f32 v[18:19], v[18:19], v[246:247]
	v_pk_mul_f32 v[114:115], v[114:115], v[110:111]
	v_pk_mul_f32 v[50:51], v[50:51], v[46:47]
	v_pk_mul_f32 v[34:35], v[34:35], v[30:31]
	v_pk_mul_f32 v[18:19], v[18:19], v[10:11]
	v_cvt_pk_bf16_f32 v113, v114, v115
	v_cvt_pk_bf16_f32 v49, v50, v51
	v_cvt_pk_bf16_f32 v33, v34, v35
	v_cvt_pk_bf16_f32 v17, v18, v19
	v_mov_b32_dpp v198, v12 row_shr:1 row_mask:0xf bank_mask:0xf bound_ctrl:1
	v_mov_b32_dpp v199, v13 row_shr:1 row_mask:0xf bank_mask:0xf bound_ctrl:1
	v_mov_b32_dpp v214, v4 row_shr:1 row_mask:0xf bank_mask:0xf bound_ctrl:1
	v_mov_b32_dpp v215, v5 row_shr:1 row_mask:0xf bank_mask:0xf bound_ctrl:1
	v_mov_b32_dpp v212, v24 row_shr:1 row_mask:0xf bank_mask:0xf bound_ctrl:1
	v_mov_b32_dpp v213, v25 row_shr:1 row_mask:0xf bank_mask:0xf bound_ctrl:1
	v_mov_b32_dpp v216, v20 row_shr:1 row_mask:0xf bank_mask:0xf bound_ctrl:1
	v_mov_b32_dpp v217, v21 row_shr:1 row_mask:0xf bank_mask:0xf bound_ctrl:1
	v_pk_fma_f32 v[12:13], v[12:13], v[84:85], v[80:81]
	v_pk_fma_f32 v[4:5], v[4:5], v[88:89], v[76:77]
	v_pk_fma_f32 v[12:13], v[24:25], v[64:65], v[12:13]
	v_pk_fma_f32 v[4:5], v[20:21], v[60:61], v[4:5]
	v_pk_fma_f32 v[12:13], v[40:41], v[56:57], v[12:13]
	v_pk_fma_f32 v[4:5], v[36:37], v[52:53], v[4:5]
	v_pk_fma_f32 v[24:25], v[24:25], v[84:85], v[80:81]
	v_pk_fma_f32 v[20:21], v[20:21], v[88:89], v[76:77]
	v_pk_fma_f32 v[24:25], v[40:41], v[64:65], v[24:25]
	v_pk_fma_f32 v[20:21], v[36:37], v[60:61], v[20:21]
	v_pk_fma_f32 v[24:25], v[72:73], v[56:57], v[24:25]
	v_pk_fma_f32 v[20:21], v[68:69], v[52:53], v[20:21]
	v_pk_fma_f32 v[40:41], v[40:41], v[84:85], v[80:81]
	v_pk_fma_f32 v[36:37], v[36:37], v[88:89], v[76:77]
	v_pk_fma_f32 v[40:41], v[72:73], v[64:65], v[40:41]
	v_pk_fma_f32 v[36:37], v[68:69], v[60:61], v[36:37]
	v_pk_fma_f32 v[40:41], v[198:199], v[56:57], v[40:41]
	v_pk_fma_f32 v[36:37], v[214:215], v[52:53], v[36:37]
	v_pk_fma_f32 v[72:73], v[72:73], v[84:85], v[80:81]
	v_pk_fma_f32 v[68:69], v[68:69], v[88:89], v[76:77]
	v_pk_fma_f32 v[72:73], v[198:199], v[64:65], v[72:73]
	v_pk_fma_f32 v[68:69], v[214:215], v[60:61], v[68:69]
	v_pk_fma_f32 v[72:73], v[212:213], v[56:57], v[72:73]
	v_pk_fma_f32 v[68:69], v[216:217], v[52:53], v[68:69]
	v_pk_mul_f32 v[222:223], v[72:73], s[50:51]
	v_pk_mul_f32 v[242:243], v[40:41], s[50:51]
	v_pk_mul_f32 v[244:245], v[24:25], s[50:51]
	v_pk_mul_f32 v[246:247], v[12:13], s[50:51]
	v_exp_f32_e32 v222, v222
	v_exp_f32_e32 v223, v223
	v_exp_f32_e32 v242, v242
	v_exp_f32_e32 v243, v243
	v_exp_f32_e32 v244, v244
	v_exp_f32_e32 v245, v245
	v_exp_f32_e32 v246, v246
	v_exp_f32_e32 v247, v247
	v_pk_add_f32 v[222:223], v[222:223], 1.0 op_sel_hi:[1,0]
	v_pk_add_f32 v[242:243], v[242:243], 1.0 op_sel_hi:[1,0]
	v_pk_add_f32 v[244:245], v[244:245], 1.0 op_sel_hi:[1,0]
	v_pk_add_f32 v[246:247], v[246:247], 1.0 op_sel_hi:[1,0]
	v_rcp_f32_e32 v222, v222
	v_rcp_f32_e32 v223, v223
	v_rcp_f32_e32 v242, v242
	v_rcp_f32_e32 v243, v243
	v_rcp_f32_e32 v244, v244
	v_rcp_f32_e32 v245, v245
	v_rcp_f32_e32 v246, v246
	v_rcp_f32_e32 v247, v247
	v_pk_mul_f32 v[72:73], v[72:73], v[222:223]
	v_pk_mul_f32 v[40:41], v[40:41], v[242:243]
	v_pk_mul_f32 v[24:25], v[24:25], v[244:245]
	v_pk_mul_f32 v[12:13], v[12:13], v[246:247]
	v_pk_mul_f32 v[72:73], v[72:73], v[68:69]
	v_pk_mul_f32 v[40:41], v[40:41], v[36:37]
	v_pk_mul_f32 v[24:25], v[24:25], v[20:21]
	v_pk_mul_f32 v[12:13], v[12:13], v[4:5]
	v_cvt_pk_bf16_f32 v114, v72, v73
	v_cvt_pk_bf16_f32 v50, v40, v41
	v_cvt_pk_bf16_f32 v34, v24, v25
	v_cvt_pk_bf16_f32 v18, v12, v13
	v_mov_b32_dpp v198, v14 row_shr:1 row_mask:0xf bank_mask:0xf bound_ctrl:1
	v_mov_b32_dpp v199, v15 row_shr:1 row_mask:0xf bank_mask:0xf bound_ctrl:1
	v_mov_b32_dpp v214, v6 row_shr:1 row_mask:0xf bank_mask:0xf bound_ctrl:1
	v_mov_b32_dpp v215, v7 row_shr:1 row_mask:0xf bank_mask:0xf bound_ctrl:1
	v_mov_b32_dpp v212, v26 row_shr:1 row_mask:0xf bank_mask:0xf bound_ctrl:1
	v_mov_b32_dpp v213, v27 row_shr:1 row_mask:0xf bank_mask:0xf bound_ctrl:1
	v_mov_b32_dpp v216, v22 row_shr:1 row_mask:0xf bank_mask:0xf bound_ctrl:1
	v_mov_b32_dpp v217, v23 row_shr:1 row_mask:0xf bank_mask:0xf bound_ctrl:1
	v_pk_fma_f32 v[14:15], v[14:15], v[86:87], v[82:83]
	v_pk_fma_f32 v[6:7], v[6:7], v[90:91], v[78:79]
	v_pk_fma_f32 v[14:15], v[26:27], v[66:67], v[14:15]
	v_pk_fma_f32 v[6:7], v[22:23], v[62:63], v[6:7]
	v_pk_fma_f32 v[14:15], v[42:43], v[58:59], v[14:15]
	v_pk_fma_f32 v[6:7], v[38:39], v[54:55], v[6:7]
	v_pk_fma_f32 v[26:27], v[26:27], v[86:87], v[82:83]
	v_pk_fma_f32 v[22:23], v[22:23], v[90:91], v[78:79]
	v_pk_fma_f32 v[26:27], v[42:43], v[66:67], v[26:27]
	v_pk_fma_f32 v[22:23], v[38:39], v[62:63], v[22:23]
	v_pk_fma_f32 v[26:27], v[74:75], v[58:59], v[26:27]
	v_pk_fma_f32 v[22:23], v[70:71], v[54:55], v[22:23]
	v_pk_fma_f32 v[42:43], v[42:43], v[86:87], v[82:83]
	v_pk_fma_f32 v[38:39], v[38:39], v[90:91], v[78:79]
	v_pk_fma_f32 v[42:43], v[74:75], v[66:67], v[42:43]
	v_pk_fma_f32 v[38:39], v[70:71], v[62:63], v[38:39]
	v_pk_fma_f32 v[42:43], v[198:199], v[58:59], v[42:43]
	v_pk_fma_f32 v[38:39], v[214:215], v[54:55], v[38:39]
	v_pk_fma_f32 v[74:75], v[74:75], v[86:87], v[82:83]
	v_pk_fma_f32 v[70:71], v[70:71], v[90:91], v[78:79]
	v_pk_fma_f32 v[74:75], v[198:199], v[66:67], v[74:75]
	v_pk_fma_f32 v[70:71], v[214:215], v[62:63], v[70:71]
	v_pk_fma_f32 v[74:75], v[212:213], v[58:59], v[74:75]
	v_pk_fma_f32 v[70:71], v[216:217], v[54:55], v[70:71]
	v_pk_mul_f32 v[222:223], v[74:75], s[50:51]
	v_pk_mul_f32 v[242:243], v[42:43], s[50:51]
	v_pk_mul_f32 v[244:245], v[26:27], s[50:51]
	v_pk_mul_f32 v[246:247], v[14:15], s[50:51]
	v_exp_f32_e32 v222, v222
	v_exp_f32_e32 v223, v223
	v_exp_f32_e32 v242, v242
	v_exp_f32_e32 v243, v243
	v_exp_f32_e32 v244, v244
	v_exp_f32_e32 v245, v245
	v_exp_f32_e32 v246, v246
	v_exp_f32_e32 v247, v247
	v_pk_add_f32 v[222:223], v[222:223], 1.0 op_sel_hi:[1,0]
	v_pk_add_f32 v[242:243], v[242:243], 1.0 op_sel_hi:[1,0]
	v_pk_add_f32 v[244:245], v[244:245], 1.0 op_sel_hi:[1,0]
	v_pk_add_f32 v[246:247], v[246:247], 1.0 op_sel_hi:[1,0]
	v_rcp_f32_e32 v222, v222
	v_rcp_f32_e32 v223, v223
	v_rcp_f32_e32 v242, v242
	v_rcp_f32_e32 v243, v243
	v_rcp_f32_e32 v244, v244
	v_rcp_f32_e32 v245, v245
	v_rcp_f32_e32 v246, v246
	v_rcp_f32_e32 v247, v247
	v_pk_mul_f32 v[74:75], v[74:75], v[222:223]
	v_pk_mul_f32 v[42:43], v[42:43], v[242:243]
	v_pk_mul_f32 v[26:27], v[26:27], v[244:245]
	v_pk_mul_f32 v[14:15], v[14:15], v[246:247]
	v_pk_mul_f32 v[74:75], v[74:75], v[70:71]
	v_pk_mul_f32 v[42:43], v[42:43], v[38:39]
	v_pk_mul_f32 v[26:27], v[26:27], v[22:23]
	v_pk_mul_f32 v[14:15], v[14:15], v[6:7]
	v_cvt_pk_bf16_f32 v115, v74, v75
	v_cvt_pk_bf16_f32 v51, v42, v43
	v_cvt_pk_bf16_f32 v35, v26, v27
	v_cvt_pk_bf16_f32 v19, v14, v15
	s_add_u32 s20, s82, 0xb0000
	s_addc_u32 s21, s83, 0
	global_store_dwordx4 v240, v[112:115], s[20:21]
	s_add_u32 s20, s82, 0xb1600
	s_addc_u32 s21, s83, 0
	global_store_dwordx4 v240, v[48:51], s[20:21]
	s_add_u32 s20, s82, 0xb2c00
	s_addc_u32 s21, s83, 0
	global_store_dwordx4 v240, v[32:35], s[20:21]
	s_add_u32 s20, s82, 0xb4200
	s_addc_u32 s21, s83, 0
	global_store_dwordx4 v240, v[16:19], s[20:21]
	s_mov_b64 s[50:51], -1
	s_branch .LBB0_76

.LBB0_136:
	s_add_u32 s23, s48, 0xfffc0080
	s_addc_u32 s24, s49, -1
	s_add_i32 s25, 0, 0x10000
	v_add_u32_e32 v145, s25, v143
	ds_read_b128 v[146:149], v145
	ds_read_b128 v[150:153], v145 offset:1024
	ds_read_b128 v[154:157], v145 offset:2048
	ds_read_b128 v[158:161], v145 offset:3072
	s_cmp_eq_u32 s22, 12
	s_cselect_b32 s53, s45, s24
	s_cselect_b32 s52, s44, s23
	s_cselect_b32 s51, s47, s21
	s_cselect_b32 s50, s46, s20
	v_lshl_add_u64 v[194:195], s[48:49], 0, v[138:139]
	s_add_i32 m0, s54, 0xc000
	ds_read_b128 v[162:165], v144
	ds_read_b128 v[166:169], v144 offset:1024
	ds_read_b128 v[170:173], v144 offset:2048
	ds_read_b128 v[174:177], v144 offset:3072
	ds_read_b128 v[178:181], v144 offset:4096
	ds_read_b128 v[182:185], v144 offset:5120
	ds_read_b128 v[186:189], v144 offset:6144
	ds_read_b128 v[190:193], v144 offset:7168
	global_load_lds_dwordx4 v[194:195], off
	v_lshl_add_u64 v[194:195], s[48:49], 0, v[140:141]
	s_add_i32 m0, s54, 0xe000
	s_nop 0
	global_load_lds_dwordx4 v[194:195], off
	s_waitcnt lgkmcnt(8)
	s_barrier
	s_waitcnt lgkmcnt(0)
	s_setprio 0
	s_waitcnt lgkmcnt(0)
	v_mfma_f32_16x16x32_bf16 v[128:131], v[146:149], v[162:165], v[128:131]
	v_mfma_f32_16x16x32_bf16 v[124:127], v[154:157], v[162:165], v[124:127]
	v_mfma_f32_16x16x32_bf16 v[120:123], v[146:149], v[170:173], v[120:123]
	v_mfma_f32_16x16x32_bf16 v[116:119], v[154:157], v[170:173], v[116:119]
	v_mfma_f32_16x16x32_bf16 v[104:107], v[146:149], v[178:181], v[104:107]
	v_mfma_f32_16x16x32_bf16 v[100:103], v[154:157], v[178:181], v[100:103]
	v_mfma_f32_16x16x32_bf16 v[88:91], v[146:149], v[186:189], v[88:91]
	v_mfma_f32_16x16x32_bf16 v[84:87], v[154:157], v[186:189], v[84:87]
	v_mfma_f32_16x16x32_bf16 v[128:131], v[150:153], v[166:169], v[128:131]
	v_mfma_f32_16x16x32_bf16 v[124:127], v[158:161], v[166:169], v[124:127]
	v_mfma_f32_16x16x32_bf16 v[120:123], v[150:153], v[174:177], v[120:123]
	v_mfma_f32_16x16x32_bf16 v[116:119], v[158:161], v[174:177], v[116:119]
	v_mfma_f32_16x16x32_bf16 v[104:107], v[150:153], v[182:185], v[104:107]
	v_mfma_f32_16x16x32_bf16 v[100:103], v[158:161], v[182:185], v[100:103]
	v_mfma_f32_16x16x32_bf16 v[88:91], v[150:153], v[190:193], v[88:91]
	v_mfma_f32_16x16x32_bf16 v[84:87], v[158:161], v[190:193], v[84:87]
	s_setprio 1
	s_barrier
	s_add_i32 s23, 0, 0x14000
	s_add_i32 s24, s25, s37
	v_add_u32_e32 v145, s23, v143
	v_lshl_add_u64 v[194:195], s[50:51], 0, v[132:133]
	s_mov_b32 m0, s24
	ds_read_b128 v[202:205], v145
	ds_read_b128 v[206:209], v145 offset:1024
	ds_read_b128 v[210:213], v145 offset:2048
	ds_read_b128 v[214:217], v145 offset:3072
	global_load_lds_dwordx4 v[194:195], off
	v_lshl_add_u64 v[198:199], s[50:51], 0, v[136:137]
	s_add_i32 m0, s24, 0x2000
	s_nop 0
	global_load_lds_dwordx4 v[198:199], off
	s_barrier
	s_waitcnt lgkmcnt(0)
	s_setprio 0
	s_waitcnt lgkmcnt(0)
	v_mfma_f32_16x16x32_bf16 v[112:115], v[202:205], v[162:165], v[112:115]
	v_mfma_f32_16x16x32_bf16 v[108:111], v[210:213], v[162:165], v[108:111]
	v_mfma_f32_16x16x32_bf16 v[96:99], v[202:205], v[170:173], v[96:99]
	v_mfma_f32_16x16x32_bf16 v[92:95], v[210:213], v[170:173], v[92:95]
	v_mfma_f32_16x16x32_bf16 v[80:83], v[202:205], v[178:181], v[80:83]
	v_mfma_f32_16x16x32_bf16 v[76:79], v[210:213], v[178:181], v[76:79]
	v_mfma_f32_16x16x32_bf16 v[72:75], v[202:205], v[186:189], v[72:75]
	v_mfma_f32_16x16x32_bf16 v[68:71], v[210:213], v[186:189], v[68:71]
	v_mfma_f32_16x16x32_bf16 v[112:115], v[206:209], v[166:169], v[112:115]
	v_mfma_f32_16x16x32_bf16 v[108:111], v[214:217], v[166:169], v[108:111]
	v_mfma_f32_16x16x32_bf16 v[96:99], v[206:209], v[174:177], v[96:99]
	v_mfma_f32_16x16x32_bf16 v[92:95], v[214:217], v[174:177], v[92:95]
	v_mfma_f32_16x16x32_bf16 v[80:83], v[206:209], v[182:185], v[80:83]
	v_mfma_f32_16x16x32_bf16 v[76:79], v[214:217], v[182:185], v[76:79]
	v_mfma_f32_16x16x32_bf16 v[72:75], v[206:209], v[190:193], v[72:75]
	v_mfma_f32_16x16x32_bf16 v[68:71], v[214:217], v[190:193], v[68:71]
	s_setprio 1
	s_mov_b32 m0, s54
	v_lshl_add_u64 v[222:223], s[52:53], 0, v[0:1]
	s_barrier
	ds_read_b128 v[162:165], v144 offset:16384
	ds_read_b128 v[166:169], v144 offset:17408
	ds_read_b128 v[170:173], v144 offset:18432
	ds_read_b128 v[174:177], v144 offset:19456
	ds_read_b128 v[178:181], v144 offset:20480
	ds_read_b128 v[182:185], v144 offset:21504
	ds_read_b128 v[186:189], v144 offset:22528
	ds_read_b128 v[190:193], v144 offset:23552
	global_load_lds_dwordx4 v[222:223], off
	v_lshl_add_u64 v[236:237], s[52:53], 0, v[134:135]
	s_mov_b32 m0, s55
	s_nop 0
	global_load_lds_dwordx4 v[236:237], off
	s_barrier
	s_waitcnt lgkmcnt(0)
	s_setprio 0
	s_waitcnt lgkmcnt(0)
	v_mfma_f32_16x16x32_bf16 v[64:67], v[146:149], v[162:165], v[64:67]
	v_mfma_f32_16x16x32_bf16 v[60:63], v[154:157], v[162:165], v[60:63]
	v_mfma_f32_16x16x32_bf16 v[56:59], v[146:149], v[170:173], v[56:59]
	v_mfma_f32_16x16x32_bf16 v[52:55], v[154:157], v[170:173], v[52:55]
	v_mfma_f32_16x16x32_bf16 v[40:43], v[146:149], v[178:181], v[40:43]
	v_mfma_f32_16x16x32_bf16 v[36:39], v[154:157], v[178:181], v[36:39]
	v_mfma_f32_16x16x32_bf16 v[24:27], v[146:149], v[186:189], v[24:27]
	v_mfma_f32_16x16x32_bf16 v[16:19], v[154:157], v[186:189], v[16:19]
	v_mfma_f32_16x16x32_bf16 v[64:67], v[150:153], v[166:169], v[64:67]
	v_mfma_f32_16x16x32_bf16 v[60:63], v[158:161], v[166:169], v[60:63]
	v_mfma_f32_16x16x32_bf16 v[56:59], v[150:153], v[174:177], v[56:59]
	v_mfma_f32_16x16x32_bf16 v[52:55], v[158:161], v[174:177], v[52:55]
	v_mfma_f32_16x16x32_bf16 v[40:43], v[150:153], v[182:185], v[40:43]
	v_mfma_f32_16x16x32_bf16 v[36:39], v[158:161], v[182:185], v[36:39]
	v_mfma_f32_16x16x32_bf16 v[24:27], v[150:153], v[190:193], v[24:27]
	v_mfma_f32_16x16x32_bf16 v[16:19], v[158:161], v[190:193], v[16:19]
	s_setprio 1
	s_barrier
	s_add_u32 s24, s50, 0x40000
	s_addc_u32 s25, s51, 0
	s_add_i32 s23, s23, s37
	v_lshl_add_u64 v[146:147], s[24:25], 0, v[132:133]
	s_mov_b32 m0, s23
	s_nop 0
	global_load_lds_dwordx4 v[146:147], off
	v_lshl_add_u64 v[146:147], s[24:25], 0, v[136:137]
	s_add_i32 m0, s23, 0x2000
	s_nop 0
	global_load_lds_dwordx4 v[146:147], off
	s_waitcnt vmcnt(6)
	s_barrier
	s_setprio 0
	v_mfma_f32_16x16x32_bf16 v[48:51], v[202:205], v[162:165], v[48:51]
	v_mfma_f32_16x16x32_bf16 v[44:47], v[210:213], v[162:165], v[44:47]
	v_mfma_f32_16x16x32_bf16 v[32:35], v[202:205], v[170:173], v[32:35]
	v_mfma_f32_16x16x32_bf16 v[28:31], v[210:213], v[170:173], v[28:31]
	v_mfma_f32_16x16x32_bf16 v[20:23], v[202:205], v[178:181], v[20:23]
	v_mfma_f32_16x16x32_bf16 v[12:15], v[210:213], v[178:181], v[12:15]
	v_mfma_f32_16x16x32_bf16 v[8:11], v[202:205], v[186:189], v[8:11]
	v_mfma_f32_16x16x32_bf16 v[4:7], v[210:213], v[186:189], v[4:7]
	v_mfma_f32_16x16x32_bf16 v[48:51], v[206:209], v[166:169], v[48:51]
	v_mfma_f32_16x16x32_bf16 v[44:47], v[214:217], v[166:169], v[44:47]
	v_mfma_f32_16x16x32_bf16 v[32:35], v[206:209], v[174:177], v[32:35]
	v_mfma_f32_16x16x32_bf16 v[28:31], v[214:217], v[174:177], v[28:31]
	v_mfma_f32_16x16x32_bf16 v[20:23], v[206:209], v[182:185], v[20:23]
	v_mfma_f32_16x16x32_bf16 v[12:15], v[214:217], v[182:185], v[12:15]
	v_mfma_f32_16x16x32_bf16 v[8:11], v[206:209], v[190:193], v[8:11]
	v_mfma_f32_16x16x32_bf16 v[4:7], v[214:217], v[190:193], v[4:7]
	s_setprio 1
	s_add_i32 s23, 0, 0x18000
	v_add_u32_e32 v145, s23, v143
	s_barrier
	ds_read_b128 v[146:149], v145
	ds_read_b128 v[150:153], v145 offset:1024
	ds_read_b128 v[154:157], v145 offset:2048
	ds_read_b128 v[158:161], v145 offset:3072
	s_add_u32 s24, s52, 0x40000
	s_addc_u32 s25, s53, 0
	s_mov_b32 m0, s56
	v_lshl_add_u64 v[202:203], s[24:25], 0, v[0:1]
	ds_read_b128 v[162:165], v144 offset:32768
	ds_read_b128 v[166:169], v144 offset:33792
	ds_read_b128 v[170:173], v144 offset:34816
	ds_read_b128 v[174:177], v144 offset:35840
	ds_read_b128 v[178:181], v144 offset:36864
	ds_read_b128 v[182:185], v144 offset:37888
	ds_read_b128 v[186:189], v144 offset:38912
	ds_read_b128 v[190:193], v144 offset:39936
	global_load_lds_dwordx4 v[202:203], off
	v_lshl_add_u64 v[202:203], s[24:25], 0, v[134:135]
	s_mov_b32 m0, s57
	s_nop 0
	global_load_lds_dwordx4 v[202:203], off
	s_waitcnt lgkmcnt(8)
	s_barrier
	s_waitcnt lgkmcnt(0)
	s_setprio 0
	s_waitcnt lgkmcnt(0)
	v_mfma_f32_16x16x32_bf16 v[128:131], v[146:149], v[162:165], v[128:131]
	v_mfma_f32_16x16x32_bf16 v[124:127], v[154:157], v[162:165], v[124:127]
	v_mfma_f32_16x16x32_bf16 v[120:123], v[146:149], v[170:173], v[120:123]
	v_mfma_f32_16x16x32_bf16 v[116:119], v[154:157], v[170:173], v[116:119]
	v_mfma_f32_16x16x32_bf16 v[104:107], v[146:149], v[178:181], v[104:107]
	v_mfma_f32_16x16x32_bf16 v[100:103], v[154:157], v[178:181], v[100:103]
	v_mfma_f32_16x16x32_bf16 v[88:91], v[146:149], v[186:189], v[88:91]
	v_mfma_f32_16x16x32_bf16 v[84:87], v[154:157], v[186:189], v[84:87]
	v_mfma_f32_16x16x32_bf16 v[128:131], v[150:153], v[166:169], v[128:131]
	v_mfma_f32_16x16x32_bf16 v[124:127], v[158:161], v[166:169], v[124:127]
	v_mfma_f32_16x16x32_bf16 v[120:123], v[150:153], v[174:177], v[120:123]
	v_mfma_f32_16x16x32_bf16 v[116:119], v[158:161], v[174:177], v[116:119]
	v_mfma_f32_16x16x32_bf16 v[104:107], v[150:153], v[182:185], v[104:107]
	v_mfma_f32_16x16x32_bf16 v[100:103], v[158:161], v[182:185], v[100:103]
	v_mfma_f32_16x16x32_bf16 v[88:91], v[150:153], v[190:193], v[88:91]
	v_mfma_f32_16x16x32_bf16 v[84:87], v[158:161], v[190:193], v[84:87]
	s_setprio 1
	s_barrier
	s_add_i32 s26, 0, 0x1c000
	s_add_i32 s23, s23, s37
	v_add_u32_e32 v145, s26, v143
	v_lshl_add_u64 v[194:195], v[194:195], 0, s[76:77]
	s_mov_b32 m0, s23
	ds_read_b128 v[202:205], v145
	ds_read_b128 v[206:209], v145 offset:1024
	ds_read_b128 v[210:213], v145 offset:2048
	ds_read_b128 v[214:217], v145 offset:3072
	global_load_lds_dwordx4 v[194:195], off
	v_lshl_add_u64 v[194:195], v[198:199], 0, s[76:77]
	s_add_i32 m0, s23, 0x2000
	s_nop 0
	global_load_lds_dwordx4 v[194:195], off
	s_barrier
	s_waitcnt lgkmcnt(0)
	s_setprio 0
	s_waitcnt lgkmcnt(0)
	v_mfma_f32_16x16x32_bf16 v[112:115], v[202:205], v[162:165], v[112:115]
	v_mfma_f32_16x16x32_bf16 v[108:111], v[210:213], v[162:165], v[108:111]
	v_mfma_f32_16x16x32_bf16 v[96:99], v[202:205], v[170:173], v[96:99]
	v_mfma_f32_16x16x32_bf16 v[92:95], v[210:213], v[170:173], v[92:95]
	v_mfma_f32_16x16x32_bf16 v[80:83], v[202:205], v[178:181], v[80:83]
	v_mfma_f32_16x16x32_bf16 v[76:79], v[210:213], v[178:181], v[76:79]
	v_mfma_f32_16x16x32_bf16 v[72:75], v[202:205], v[186:189], v[72:75]
	v_mfma_f32_16x16x32_bf16 v[68:71], v[210:213], v[186:189], v[68:71]
	v_mfma_f32_16x16x32_bf16 v[112:115], v[206:209], v[166:169], v[112:115]
	v_mfma_f32_16x16x32_bf16 v[108:111], v[214:217], v[166:169], v[108:111]
	v_mfma_f32_16x16x32_bf16 v[96:99], v[206:209], v[174:177], v[96:99]
	v_mfma_f32_16x16x32_bf16 v[92:95], v[214:217], v[174:177], v[92:95]
	v_mfma_f32_16x16x32_bf16 v[80:83], v[206:209], v[182:185], v[80:83]
	v_mfma_f32_16x16x32_bf16 v[76:79], v[214:217], v[182:185], v[76:79]
	v_mfma_f32_16x16x32_bf16 v[72:75], v[206:209], v[190:193], v[72:75]
	v_mfma_f32_16x16x32_bf16 v[68:71], v[214:217], v[190:193], v[68:71]
	s_setprio 1
	s_mov_b32 m0, s59
	v_lshl_add_u64 v[194:195], v[222:223], 0, s[76:77]
	s_barrier
	ds_read_b128 v[162:165], v144 offset:49152
	ds_read_b128 v[166:169], v144 offset:50176
	ds_read_b128 v[170:173], v144 offset:51200
	ds_read_b128 v[174:177], v144 offset:52224
	ds_read_b128 v[178:181], v144 offset:53248
	ds_read_b128 v[182:185], v144 offset:54272
	ds_read_b128 v[186:189], v144 offset:55296
	ds_read_b128 v[190:193], v144 offset:56320
	global_load_lds_dwordx4 v[194:195], off
	v_lshl_add_u64 v[194:195], v[236:237], 0, s[76:77]
	s_mov_b32 m0, s60
	s_nop 0
	global_load_lds_dwordx4 v[194:195], off
	s_barrier
	s_waitcnt lgkmcnt(0)
	s_setprio 0
	s_waitcnt lgkmcnt(0)
	v_mfma_f32_16x16x32_bf16 v[64:67], v[146:149], v[162:165], v[64:67]
	v_mfma_f32_16x16x32_bf16 v[60:63], v[154:157], v[162:165], v[60:63]
	v_mfma_f32_16x16x32_bf16 v[56:59], v[146:149], v[170:173], v[56:59]
	v_mfma_f32_16x16x32_bf16 v[52:55], v[154:157], v[170:173], v[52:55]
	v_mfma_f32_16x16x32_bf16 v[40:43], v[146:149], v[178:181], v[40:43]
	v_mfma_f32_16x16x32_bf16 v[36:39], v[154:157], v[178:181], v[36:39]
	v_mfma_f32_16x16x32_bf16 v[24:27], v[146:149], v[186:189], v[24:27]
	v_mfma_f32_16x16x32_bf16 v[16:19], v[154:157], v[186:189], v[16:19]
	v_mfma_f32_16x16x32_bf16 v[64:67], v[150:153], v[166:169], v[64:67]
	v_mfma_f32_16x16x32_bf16 v[60:63], v[158:161], v[166:169], v[60:63]
	v_mfma_f32_16x16x32_bf16 v[56:59], v[150:153], v[174:177], v[56:59]
	v_mfma_f32_16x16x32_bf16 v[52:55], v[158:161], v[174:177], v[52:55]
	v_mfma_f32_16x16x32_bf16 v[40:43], v[150:153], v[182:185], v[40:43]
	v_mfma_f32_16x16x32_bf16 v[36:39], v[158:161], v[182:185], v[36:39]
	v_mfma_f32_16x16x32_bf16 v[24:27], v[150:153], v[190:193], v[24:27]
	v_mfma_f32_16x16x32_bf16 v[16:19], v[158:161], v[190:193], v[16:19]
	s_setprio 1
	s_barrier
	s_add_u32 s24, s50, 0x40080
	s_addc_u32 s25, s51, 0
	s_add_i32 s23, s26, s37
	v_lshl_add_u64 v[146:147], s[24:25], 0, v[132:133]
	s_mov_b32 m0, s23
	s_nop 0
	global_load_lds_dwordx4 v[146:147], off
	v_lshl_add_u64 v[146:147], s[24:25], 0, v[136:137]
	s_add_i32 m0, s23, 0x2000
	s_nop 0
	global_load_lds_dwordx4 v[146:147], off
	s_waitcnt vmcnt(6)
	s_barrier
	s_setprio 0
	v_mfma_f32_16x16x32_bf16 v[48:51], v[202:205], v[162:165], v[48:51]
	v_mfma_f32_16x16x32_bf16 v[44:47], v[210:213], v[162:165], v[44:47]
	v_mfma_f32_16x16x32_bf16 v[32:35], v[202:205], v[170:173], v[32:35]
	v_mfma_f32_16x16x32_bf16 v[28:31], v[210:213], v[170:173], v[28:31]
	v_mfma_f32_16x16x32_bf16 v[20:23], v[202:205], v[178:181], v[20:23]
	v_mfma_f32_16x16x32_bf16 v[12:15], v[210:213], v[178:181], v[12:15]
	v_mfma_f32_16x16x32_bf16 v[8:11], v[202:205], v[186:189], v[8:11]
	v_mfma_f32_16x16x32_bf16 v[4:7], v[210:213], v[186:189], v[4:7]
	v_mfma_f32_16x16x32_bf16 v[48:51], v[206:209], v[166:169], v[48:51]
	v_mfma_f32_16x16x32_bf16 v[44:47], v[214:217], v[166:169], v[44:47]
	v_mfma_f32_16x16x32_bf16 v[32:35], v[206:209], v[174:177], v[32:35]
	v_mfma_f32_16x16x32_bf16 v[28:31], v[214:217], v[174:177], v[28:31]
	v_mfma_f32_16x16x32_bf16 v[20:23], v[206:209], v[182:185], v[20:23]
	v_mfma_f32_16x16x32_bf16 v[12:15], v[214:217], v[182:185], v[12:15]
	v_mfma_f32_16x16x32_bf16 v[8:11], v[206:209], v[190:193], v[8:11]
	v_mfma_f32_16x16x32_bf16 v[4:7], v[214:217], v[190:193], v[4:7]
	s_setprio 1
	s_add_i32 s22, s22, 2
	s_add_u32 s48, s48, 0x100
	s_addc_u32 s49, s49, 0
	s_add_u32 s20, s20, 0x100
	s_addc_u32 s21, s21, 0
	s_cmp_gt_u32 s22, 13
	s_barrier
	s_cbranch_scc0 .LBB0_136
	v_lshl_add_u32 v146, s0, 8, v142
	v_cvt_pk_bf16_f32 v72, v72, v73
	v_cvt_pk_bf16_f32 v73, v74, v75
	v_cvt_pk_bf16_f32 v74, v68, v69
	v_add_u32_e32 v68, 0x80, v146
	s_lshl_b32 s0, s1, 8
	v_ashrrev_i32_e32 v147, 31, v146
	v_readlane_b32 s20, v252, 12
	v_cvt_pk_bf16_f32 v112, v112, v113
	v_cvt_pk_bf16_f32 v113, v114, v115
	v_cvt_pk_bf16_f32 v114, v108, v109
	v_or_b32_e32 v108, 16, v146
	v_ashrrev_i32_e32 v69, 31, v68
	v_cvt_pk_bf16_f32 v48, v48, v49
	v_cvt_pk_bf16_f32 v49, v50, v51
	v_cvt_pk_bf16_f32 v50, v44, v45
	v_add_u32_e32 v44, 0x90, v146
	s_ashr_i32 s1, s0, 31
	v_lshlrev_b64 v[148:149], 11, v[146:147]
	v_readlane_b32 s21, v252, 13
	v_ashrrev_i32_e32 v109, 31, v108
	v_cvt_pk_bf16_f32 v96, v96, v97
	v_cvt_pk_bf16_f32 v97, v98, v99
	v_cvt_pk_bf16_f32 v98, v92, v93
	v_or_b32_e32 v92, 32, v146
	v_lshlrev_b64 v[68:69], 11, v[68:69]
	v_ashrrev_i32_e32 v45, 31, v44
	v_cvt_pk_bf16_f32 v32, v32, v33
	v_cvt_pk_bf16_f32 v33, v34, v35
	v_cvt_pk_bf16_f32 v34, v28, v29
	v_add_u32_e32 v28, 0xa0, v146
	v_lshl_add_u64 v[148:149], s[20:21], 0, v[148:149]
	s_lshl_b64 s[0:1], s[0:1], 1
	v_lshlrev_b64 v[108:109], 11, v[108:109]
	v_ashrrev_i32_e32 v93, 31, v92
	v_cvt_pk_bf16_f32 v80, v80, v81
	v_cvt_pk_bf16_f32 v81, v82, v83
	v_cvt_pk_bf16_f32 v82, v76, v77
	v_or_b32_e32 v76, 48, v146
	v_lshl_add_u64 v[68:69], s[20:21], 0, v[68:69]
	v_lshlrev_b64 v[44:45], 11, v[44:45]
	v_ashrrev_i32_e32 v29, 31, v28
	v_cvt_pk_bf16_f32 v20, v20, v21
	v_cvt_pk_bf16_f32 v21, v22, v23
	v_cvt_pk_bf16_f32 v22, v12, v13
	v_add_u32_e32 v12, 0xb0, v146
	v_lshl_add_u64 v[148:149], v[148:149], 0, s[0:1]
	v_lshl_add_u64 v[108:109], s[20:21], 0, v[108:109]
	v_lshlrev_b64 v[92:93], 11, v[92:93]
	v_ashrrev_i32_e32 v77, 31, v76
	v_lshl_add_u64 v[68:69], v[68:69], 0, s[0:1]
	v_lshl_add_u64 v[44:45], s[20:21], 0, v[44:45]
	v_lshlrev_b64 v[28:29], 11, v[28:29]
	v_ashrrev_i32_e32 v13, 31, v12
	v_lshl_add_u64 v[148:149], v[148:149], 0, s[72:73]
	v_lshl_add_u64 v[108:109], v[108:109], 0, s[0:1]
	v_lshl_add_u64 v[92:93], s[20:21], 0, v[92:93]
	v_lshlrev_b64 v[76:77], 11, v[76:77]
	v_lshl_add_u64 v[68:69], v[68:69], 0, s[72:73]
	v_lshl_add_u64 v[44:45], v[44:45], 0, s[0:1]
	v_lshl_add_u64 v[28:29], s[20:21], 0, v[28:29]
	v_lshlrev_b64 v[12:13], 11, v[12:13]
	v_lshl_add_u64 v[148:149], v[148:149], 0, v[2:3]
	v_cvt_pk_bf16_f32 v115, v110, v111
	v_lshl_add_u64 v[108:109], v[108:109], 0, s[72:73]
	v_lshl_add_u64 v[92:93], v[92:93], 0, s[0:1]
	v_lshl_add_u64 v[76:77], s[20:21], 0, v[76:77]
	v_lshl_add_u64 v[68:69], v[68:69], 0, v[2:3]
	v_cvt_pk_bf16_f32 v51, v46, v47
	v_lshl_add_u64 v[44:45], v[44:45], 0, s[72:73]
	v_lshl_add_u64 v[28:29], v[28:29], 0, s[0:1]
	v_lshl_add_u64 v[12:13], s[20:21], 0, v[12:13]
	global_store_dwordx4 v[148:149], v[112:115], off offset:256
	v_cvt_pk_bf16_f32 v99, v94, v95
	v_lshl_add_u64 v[92:93], v[92:93], 0, s[72:73]
	v_lshl_add_u64 v[112:113], v[108:109], 0, v[2:3]
	v_lshl_add_u64 v[76:77], v[76:77], 0, s[0:1]
	global_store_dwordx4 v[68:69], v[48:51], off offset:256
	v_cvt_pk_bf16_f32 v35, v30, v31
	v_lshl_add_u64 v[28:29], v[28:29], 0, s[72:73]
	v_lshl_add_u64 v[48:49], v[44:45], 0, v[2:3]
	v_lshl_add_u64 v[12:13], v[12:13], 0, s[0:1]
	global_store_dwordx4 v[112:113], v[96:99], off offset:256
	v_cvt_pk_bf16_f32 v83, v78, v79
	v_lshl_add_u64 v[76:77], v[76:77], 0, s[72:73]
	v_lshl_add_u64 v[96:97], v[92:93], 0, v[2:3]
	global_store_dwordx4 v[48:49], v[32:35], off offset:256
	v_cvt_pk_bf16_f32 v23, v14, v15
	v_lshl_add_u64 v[12:13], v[12:13], 0, s[72:73]
	v_lshl_add_u64 v[32:33], v[28:29], 0, v[2:3]
	v_cvt_pk_bf16_f32 v128, v128, v129
	v_cvt_pk_bf16_f32 v129, v130, v131
	v_cvt_pk_bf16_f32 v130, v124, v125
	v_cvt_pk_bf16_f32 v131, v126, v127
	v_cvt_pk_bf16_f32 v108, v120, v121
	v_cvt_pk_bf16_f32 v109, v122, v123
	v_cvt_pk_bf16_f32 v110, v116, v117
	v_cvt_pk_bf16_f32 v111, v118, v119
	v_cvt_pk_bf16_f32 v92, v104, v105
	v_cvt_pk_bf16_f32 v93, v106, v107
	v_cvt_pk_bf16_f32 v94, v100, v101
	v_cvt_pk_bf16_f32 v95, v102, v103
	global_store_dwordx4 v[96:97], v[80:83], off offset:256
	v_cvt_pk_bf16_f32 v78, v84, v85
	v_cvt_pk_bf16_f32 v79, v86, v87
	v_lshl_add_u64 v[80:81], v[76:77], 0, v[2:3]
	v_cvt_pk_bf16_f32 v76, v88, v89
	v_cvt_pk_bf16_f32 v77, v90, v91
	v_cvt_pk_bf16_f32 v75, v70, v71
	v_cvt_pk_bf16_f32 v64, v64, v65
	v_cvt_pk_bf16_f32 v65, v66, v67
	v_cvt_pk_bf16_f32 v66, v60, v61
	v_cvt_pk_bf16_f32 v67, v62, v63
	v_cvt_pk_bf16_f32 v44, v56, v57
	v_cvt_pk_bf16_f32 v45, v58, v59
	v_cvt_pk_bf16_f32 v46, v52, v53
	v_cvt_pk_bf16_f32 v47, v54, v55
	v_cvt_pk_bf16_f32 v28, v40, v41
	v_cvt_pk_bf16_f32 v29, v42, v43
	v_cvt_pk_bf16_f32 v30, v36, v37
	v_cvt_pk_bf16_f32 v31, v38, v39
	global_store_dwordx4 v[32:33], v[20:23], off offset:256
	v_cvt_pk_bf16_f32 v14, v16, v17
	v_cvt_pk_bf16_f32 v15, v18, v19
	v_lshl_add_u64 v[20:21], v[12:13], 0, v[2:3]
	v_cvt_pk_bf16_f32 v12, v24, v25
	v_cvt_pk_bf16_f32 v13, v26, v27
	v_cvt_pk_bf16_f32 v8, v8, v9
	v_cvt_pk_bf16_f32 v9, v10, v11
	v_cvt_pk_bf16_f32 v10, v4, v5
	v_cvt_pk_bf16_f32 v11, v6, v7
	s_and_b64 vcc, exec, s[38:39]
	s_mov_b32 s1, s40
	s_mov_b32 s0, s42
	s_mov_b64 s[50:51], s[46:47]
	s_mov_b64 s[48:49], s[44:45]
	global_store_dwordx4 v[148:149], v[128:131], off
	global_store_dwordx4 v[112:113], v[108:111], off
	global_store_dwordx4 v[96:97], v[92:95], off
	global_store_dwordx4 v[80:81], v[76:79], off
	global_store_dwordx4 v[80:81], v[72:75], off offset:256
	global_store_dwordx4 v[68:69], v[64:67], off
	global_store_dwordx4 v[48:49], v[44:47], off
	global_store_dwordx4 v[32:33], v[28:31], off
	global_store_dwordx4 v[20:21], v[12:15], off
	global_store_dwordx4 v[20:21], v[8:11], off offset:256
	s_cbranch_vccz .LBB0_129
	s_waitcnt vmcnt(0)
	s_cmpk_gt_u32 s31, 0xff
	s_cbranch_scc1 .LBB0_140
	s_barrier

.LBB0_175:
	s_add_i32 s26, s27, 2
	s_add_u32 s44, s40, 0x100
	s_addc_u32 s45, s41, 0
	s_add_i32 s30, 0, 0x10000
	v_add_u32_e32 v0, s30, v157
	ds_read_b128 v[132:135], v0
	ds_read_b128 v[164:167], v0 offset:1024
	ds_read_b128 v[168:171], v0 offset:2048
	ds_read_b128 v[174:177], v0 offset:3072
	s_cmp_eq_u32 s23, s27
	s_cselect_b32 s49, s1, s45
	s_cselect_b32 s48, s0, s44
	s_cselect_b32 s47, s43, s25
	s_cselect_b32 s46, s42, s24
	v_lshl_add_u64 v[0:1], s[40:41], 0, v[160:161]
	s_add_i32 m0, s53, 0xc000
	ds_read_b128 v[178:181], v172
	ds_read_b128 v[182:185], v172 offset:1024
	ds_read_b128 v[186:189], v172 offset:2048
	ds_read_b128 v[190:193], v172 offset:3072
	ds_read_b128 v[202:205], v172 offset:4096
	ds_read_b128 v[206:209], v172 offset:5120
	ds_read_b128 v[210:213], v172 offset:6144
	ds_read_b128 v[214:217], v172 offset:7168
	global_load_lds_dwordx4 v[0:1], off
	v_lshl_add_u64 v[0:1], s[40:41], 0, v[162:163]
	s_add_i32 m0, s53, 0xe000
	s_nop 0
	global_load_lds_dwordx4 v[0:1], off
	s_waitcnt lgkmcnt(8)
	s_barrier
	s_waitcnt lgkmcnt(0)
	s_setprio 0
	s_waitcnt lgkmcnt(0)
	v_mfma_f32_16x16x32_bf16 v[4:7], v[132:135], v[178:181], v[4:7]
	v_mfma_f32_16x16x32_bf16 v[8:11], v[168:171], v[178:181], v[8:11]
	v_mfma_f32_16x16x32_bf16 v[128:131], v[132:135], v[186:189], v[128:131]
	v_mfma_f32_16x16x32_bf16 v[124:127], v[168:171], v[186:189], v[124:127]
	v_mfma_f32_16x16x32_bf16 v[120:123], v[132:135], v[202:205], v[120:123]
	v_mfma_f32_16x16x32_bf16 v[116:119], v[168:171], v[202:205], v[116:119]
	v_mfma_f32_16x16x32_bf16 v[112:115], v[132:135], v[210:213], v[112:115]
	v_mfma_f32_16x16x32_bf16 v[108:111], v[168:171], v[210:213], v[108:111]
	v_mfma_f32_16x16x32_bf16 v[4:7], v[164:167], v[182:185], v[4:7]
	v_mfma_f32_16x16x32_bf16 v[8:11], v[174:177], v[182:185], v[8:11]
	v_mfma_f32_16x16x32_bf16 v[128:131], v[164:167], v[190:193], v[128:131]
	v_mfma_f32_16x16x32_bf16 v[124:127], v[174:177], v[190:193], v[124:127]
	v_mfma_f32_16x16x32_bf16 v[120:123], v[164:167], v[206:209], v[120:123]
	v_mfma_f32_16x16x32_bf16 v[116:119], v[174:177], v[206:209], v[116:119]
	v_mfma_f32_16x16x32_bf16 v[112:115], v[164:167], v[214:217], v[112:115]
	v_mfma_f32_16x16x32_bf16 v[108:111], v[174:177], v[214:217], v[108:111]
	s_setprio 1
	s_barrier
	s_add_i32 s27, 0, 0x14000
	v_add_u32_e32 v0, s27, v157
	s_add_i32 s30, s30, s52
	ds_read_b128 v[236:239], v0
	ds_read_b128 v[240:243], v0 offset:1024
	ds_read_b128 v[244:247], v0 offset:2048
	ds_read_b128 v[248:251], v0 offset:3072
	v_lshl_add_u64 v[0:1], s[46:47], 0, v[138:139]
	s_mov_b32 m0, s30
	v_lshl_add_u64 v[194:195], s[46:47], 0, v[142:143]
	global_load_lds_dwordx4 v[0:1], off
	s_add_i32 m0, s30, 0x2000
	s_nop 0
	global_load_lds_dwordx4 v[194:195], off
	s_barrier
	s_waitcnt lgkmcnt(0)
	s_setprio 0
	s_waitcnt lgkmcnt(0)
	v_mfma_f32_16x16x32_bf16 v[12:15], v[236:239], v[178:181], v[12:15]
	v_mfma_f32_16x16x32_bf16 v[16:19], v[244:247], v[178:181], v[16:19]
	v_mfma_f32_16x16x32_bf16 v[104:107], v[236:239], v[186:189], v[104:107]
	v_mfma_f32_16x16x32_bf16 v[100:103], v[244:247], v[186:189], v[100:103]
	v_mfma_f32_16x16x32_bf16 v[96:99], v[236:239], v[202:205], v[96:99]
	v_mfma_f32_16x16x32_bf16 v[92:95], v[244:247], v[202:205], v[92:95]
	v_mfma_f32_16x16x32_bf16 v[88:91], v[236:239], v[210:213], v[88:91]
	v_mfma_f32_16x16x32_bf16 v[84:87], v[244:247], v[210:213], v[84:87]
	v_mfma_f32_16x16x32_bf16 v[12:15], v[240:243], v[182:185], v[12:15]
	v_mfma_f32_16x16x32_bf16 v[16:19], v[248:251], v[182:185], v[16:19]
	v_mfma_f32_16x16x32_bf16 v[104:107], v[240:243], v[190:193], v[104:107]
	v_mfma_f32_16x16x32_bf16 v[100:103], v[248:251], v[190:193], v[100:103]
	v_mfma_f32_16x16x32_bf16 v[96:99], v[240:243], v[206:209], v[96:99]
	v_mfma_f32_16x16x32_bf16 v[92:95], v[248:251], v[206:209], v[92:95]
	v_mfma_f32_16x16x32_bf16 v[88:91], v[240:243], v[214:217], v[88:91]
	v_mfma_f32_16x16x32_bf16 v[84:87], v[248:251], v[214:217], v[84:87]
	s_setprio 1
	s_mov_b32 m0, s53
	v_lshl_add_u64 v[222:223], s[48:49], 0, v[136:137]
	s_barrier
	ds_read_b128 v[178:181], v172 offset:16384
	ds_read_b128 v[182:185], v172 offset:17408
	ds_read_b128 v[186:189], v172 offset:18432
	ds_read_b128 v[190:193], v172 offset:19456
	ds_read_b128 v[202:205], v172 offset:20480
	ds_read_b128 v[206:209], v172 offset:21504
	ds_read_b128 v[210:213], v172 offset:22528
	ds_read_b128 v[214:217], v172 offset:23552
	global_load_lds_dwordx4 v[222:223], off
	v_lshl_add_u64 v[198:199], s[48:49], 0, v[140:141]
	s_mov_b32 m0, s54
	s_nop 0
	global_load_lds_dwordx4 v[198:199], off
	s_barrier
	s_waitcnt lgkmcnt(0)
	s_setprio 0
	s_waitcnt lgkmcnt(0)
	v_mfma_f32_16x16x32_bf16 v[80:83], v[132:135], v[178:181], v[80:83]
	v_mfma_f32_16x16x32_bf16 v[76:79], v[168:171], v[178:181], v[76:79]
	v_mfma_f32_16x16x32_bf16 v[72:75], v[132:135], v[186:189], v[72:75]
	v_mfma_f32_16x16x32_bf16 v[68:71], v[168:171], v[186:189], v[68:71]
	v_mfma_f32_16x16x32_bf16 v[64:67], v[132:135], v[202:205], v[64:67]
	v_mfma_f32_16x16x32_bf16 v[60:63], v[168:171], v[202:205], v[60:63]
	v_mfma_f32_16x16x32_bf16 v[56:59], v[132:135], v[210:213], v[56:59]
	v_mfma_f32_16x16x32_bf16 v[52:55], v[168:171], v[210:213], v[52:55]
	v_mfma_f32_16x16x32_bf16 v[80:83], v[164:167], v[182:185], v[80:83]
	v_mfma_f32_16x16x32_bf16 v[76:79], v[174:177], v[182:185], v[76:79]
	v_mfma_f32_16x16x32_bf16 v[72:75], v[164:167], v[190:193], v[72:75]
	v_mfma_f32_16x16x32_bf16 v[68:71], v[174:177], v[190:193], v[68:71]
	v_mfma_f32_16x16x32_bf16 v[64:67], v[164:167], v[206:209], v[64:67]
	v_mfma_f32_16x16x32_bf16 v[60:63], v[174:177], v[206:209], v[60:63]
	v_mfma_f32_16x16x32_bf16 v[56:59], v[164:167], v[214:217], v[56:59]
	v_mfma_f32_16x16x32_bf16 v[52:55], v[174:177], v[214:217], v[52:55]
	s_setprio 1
	s_barrier
	s_add_u32 s30, s46, 0xc0000
	s_addc_u32 s31, s47, 0
	s_add_i32 s27, s27, s52
	v_lshl_add_u64 v[132:133], s[30:31], 0, v[138:139]
	s_mov_b32 m0, s27
	s_nop 0
	global_load_lds_dwordx4 v[132:133], off
	v_lshl_add_u64 v[132:133], s[30:31], 0, v[142:143]
	s_add_i32 m0, s27, 0x2000
	s_nop 0
	global_load_lds_dwordx4 v[132:133], off
	s_waitcnt vmcnt(6)
	s_barrier
	s_setprio 0
	v_mfma_f32_16x16x32_bf16 v[48:51], v[236:239], v[178:181], v[48:51]
	v_mfma_f32_16x16x32_bf16 v[44:47], v[244:247], v[178:181], v[44:47]
	v_mfma_f32_16x16x32_bf16 v[40:43], v[236:239], v[186:189], v[40:43]
	v_mfma_f32_16x16x32_bf16 v[36:39], v[244:247], v[186:189], v[36:39]
	v_mfma_f32_16x16x32_bf16 v[32:35], v[236:239], v[202:205], v[32:35]
	v_mfma_f32_16x16x32_bf16 v[28:31], v[244:247], v[202:205], v[28:31]
	v_mfma_f32_16x16x32_bf16 v[24:27], v[236:239], v[210:213], v[24:27]
	v_mfma_f32_16x16x32_bf16 v[20:23], v[244:247], v[210:213], v[20:23]
	v_mfma_f32_16x16x32_bf16 v[48:51], v[240:243], v[182:185], v[48:51]
	v_mfma_f32_16x16x32_bf16 v[44:47], v[248:251], v[182:185], v[44:47]
	v_mfma_f32_16x16x32_bf16 v[40:43], v[240:243], v[190:193], v[40:43]
	v_mfma_f32_16x16x32_bf16 v[36:39], v[248:251], v[190:193], v[36:39]
	v_mfma_f32_16x16x32_bf16 v[32:35], v[240:243], v[206:209], v[32:35]
	v_mfma_f32_16x16x32_bf16 v[28:31], v[248:251], v[206:209], v[28:31]
	v_mfma_f32_16x16x32_bf16 v[24:27], v[240:243], v[214:217], v[24:27]
	v_mfma_f32_16x16x32_bf16 v[20:23], v[248:251], v[214:217], v[20:23]
	s_setprio 1
	s_add_i32 s27, 0, 0x18000
	v_add_u32_e32 v2, s27, v157
	s_barrier
	ds_read_b128 v[132:135], v2
	ds_read_b128 v[164:167], v2 offset:1024
	ds_read_b128 v[168:171], v2 offset:2048
	ds_read_b128 v[174:177], v2 offset:3072
	s_add_u32 s30, s48, 0x1a0000
	s_addc_u32 s31, s49, 0
	s_mov_b32 m0, s55
	v_lshl_add_u64 v[236:237], s[30:31], 0, v[136:137]
	ds_read_b128 v[178:181], v172 offset:32768
	ds_read_b128 v[182:185], v172 offset:33792
	ds_read_b128 v[186:189], v172 offset:34816
	ds_read_b128 v[190:193], v172 offset:35840
	ds_read_b128 v[202:205], v172 offset:36864
	ds_read_b128 v[206:209], v172 offset:37888
	ds_read_b128 v[210:213], v172 offset:38912
	ds_read_b128 v[214:217], v172 offset:39936
	global_load_lds_dwordx4 v[236:237], off
	v_lshl_add_u64 v[236:237], s[30:31], 0, v[140:141]
	s_mov_b32 m0, s56
	s_nop 0
	global_load_lds_dwordx4 v[236:237], off
	s_waitcnt lgkmcnt(8)
	s_barrier
	s_waitcnt lgkmcnt(0)
	s_setprio 0
	s_waitcnt lgkmcnt(0)
	v_mfma_f32_16x16x32_bf16 v[4:7], v[132:135], v[178:181], v[4:7]
	v_mfma_f32_16x16x32_bf16 v[8:11], v[168:171], v[178:181], v[8:11]
	v_mfma_f32_16x16x32_bf16 v[128:131], v[132:135], v[186:189], v[128:131]
	v_mfma_f32_16x16x32_bf16 v[124:127], v[168:171], v[186:189], v[124:127]
	v_mfma_f32_16x16x32_bf16 v[120:123], v[132:135], v[202:205], v[120:123]
	v_mfma_f32_16x16x32_bf16 v[116:119], v[168:171], v[202:205], v[116:119]
	v_mfma_f32_16x16x32_bf16 v[112:115], v[132:135], v[210:213], v[112:115]
	v_mfma_f32_16x16x32_bf16 v[108:111], v[168:171], v[210:213], v[108:111]
	v_mfma_f32_16x16x32_bf16 v[4:7], v[164:167], v[182:185], v[4:7]
	v_mfma_f32_16x16x32_bf16 v[8:11], v[174:177], v[182:185], v[8:11]
	v_mfma_f32_16x16x32_bf16 v[128:131], v[164:167], v[190:193], v[128:131]
	v_mfma_f32_16x16x32_bf16 v[124:127], v[174:177], v[190:193], v[124:127]
	v_mfma_f32_16x16x32_bf16 v[120:123], v[164:167], v[206:209], v[120:123]
	v_mfma_f32_16x16x32_bf16 v[116:119], v[174:177], v[206:209], v[116:119]
	v_mfma_f32_16x16x32_bf16 v[112:115], v[164:167], v[214:217], v[112:115]
	v_mfma_f32_16x16x32_bf16 v[108:111], v[174:177], v[214:217], v[108:111]
	s_setprio 1
	s_barrier
	s_add_i32 s36, 0, 0x1c000
	s_add_i32 s27, s27, s52
	v_add_u32_e32 v2, s36, v157
	v_lshl_add_u64 v[0:1], v[0:1], 0, s[76:77]
	s_mov_b32 m0, s27
	ds_read_b128 v[236:239], v2
	ds_read_b128 v[240:243], v2 offset:1024
	ds_read_b128 v[244:247], v2 offset:2048
	ds_read_b128 v[248:251], v2 offset:3072
	global_load_lds_dwordx4 v[0:1], off
	v_lshl_add_u64 v[0:1], v[194:195], 0, s[76:77]
	s_add_i32 m0, s27, 0x2000
	s_nop 0
	global_load_lds_dwordx4 v[0:1], off
	s_barrier
	s_waitcnt lgkmcnt(0)
	s_setprio 0
	s_waitcnt lgkmcnt(0)
	v_mfma_f32_16x16x32_bf16 v[12:15], v[236:239], v[178:181], v[12:15]
	v_mfma_f32_16x16x32_bf16 v[16:19], v[244:247], v[178:181], v[16:19]
	v_mfma_f32_16x16x32_bf16 v[104:107], v[236:239], v[186:189], v[104:107]
	v_mfma_f32_16x16x32_bf16 v[100:103], v[244:247], v[186:189], v[100:103]
	v_mfma_f32_16x16x32_bf16 v[96:99], v[236:239], v[202:205], v[96:99]
	v_mfma_f32_16x16x32_bf16 v[92:95], v[244:247], v[202:205], v[92:95]
	v_mfma_f32_16x16x32_bf16 v[88:91], v[236:239], v[210:213], v[88:91]
	v_mfma_f32_16x16x32_bf16 v[84:87], v[244:247], v[210:213], v[84:87]
	v_mfma_f32_16x16x32_bf16 v[12:15], v[240:243], v[182:185], v[12:15]
	v_mfma_f32_16x16x32_bf16 v[16:19], v[248:251], v[182:185], v[16:19]
	v_mfma_f32_16x16x32_bf16 v[104:107], v[240:243], v[190:193], v[104:107]
	v_mfma_f32_16x16x32_bf16 v[100:103], v[248:251], v[190:193], v[100:103]
	v_mfma_f32_16x16x32_bf16 v[96:99], v[240:243], v[206:209], v[96:99]
	v_mfma_f32_16x16x32_bf16 v[92:95], v[248:251], v[206:209], v[92:95]
	v_mfma_f32_16x16x32_bf16 v[88:91], v[240:243], v[214:217], v[88:91]
	v_mfma_f32_16x16x32_bf16 v[84:87], v[248:251], v[214:217], v[84:87]
	s_setprio 1
	s_mov_b32 m0, s59
	v_lshl_add_u64 v[0:1], v[222:223], 0, s[76:77]
	s_barrier
	ds_read_b128 v[178:181], v172 offset:49152
	ds_read_b128 v[182:185], v172 offset:50176
	ds_read_b128 v[186:189], v172 offset:51200
	ds_read_b128 v[190:193], v172 offset:52224
	ds_read_b128 v[202:205], v172 offset:53248
	ds_read_b128 v[206:209], v172 offset:54272
	ds_read_b128 v[210:213], v172 offset:55296
	ds_read_b128 v[214:217], v172 offset:56320
	global_load_lds_dwordx4 v[0:1], off
	v_lshl_add_u64 v[0:1], v[198:199], 0, s[76:77]
	s_mov_b32 m0, s60
	s_nop 0
	global_load_lds_dwordx4 v[0:1], off
	s_barrier
	s_waitcnt lgkmcnt(0)
	s_setprio 0
	s_waitcnt lgkmcnt(0)
	v_mfma_f32_16x16x32_bf16 v[80:83], v[132:135], v[178:181], v[80:83]
	v_mfma_f32_16x16x32_bf16 v[76:79], v[168:171], v[178:181], v[76:79]
	v_mfma_f32_16x16x32_bf16 v[72:75], v[132:135], v[186:189], v[72:75]
	v_mfma_f32_16x16x32_bf16 v[68:71], v[168:171], v[186:189], v[68:71]
	v_mfma_f32_16x16x32_bf16 v[64:67], v[132:135], v[202:205], v[64:67]
	v_mfma_f32_16x16x32_bf16 v[60:63], v[168:171], v[202:205], v[60:63]
	v_mfma_f32_16x16x32_bf16 v[56:59], v[132:135], v[210:213], v[56:59]
	v_mfma_f32_16x16x32_bf16 v[52:55], v[168:171], v[210:213], v[52:55]
	v_mfma_f32_16x16x32_bf16 v[80:83], v[164:167], v[182:185], v[80:83]
	v_mfma_f32_16x16x32_bf16 v[76:79], v[174:177], v[182:185], v[76:79]
	v_mfma_f32_16x16x32_bf16 v[72:75], v[164:167], v[190:193], v[72:75]
	v_mfma_f32_16x16x32_bf16 v[68:71], v[174:177], v[190:193], v[68:71]
	v_mfma_f32_16x16x32_bf16 v[64:67], v[164:167], v[206:209], v[64:67]
	v_mfma_f32_16x16x32_bf16 v[60:63], v[174:177], v[206:209], v[60:63]
	v_mfma_f32_16x16x32_bf16 v[56:59], v[164:167], v[214:217], v[56:59]
	v_mfma_f32_16x16x32_bf16 v[52:55], v[174:177], v[214:217], v[52:55]
	s_setprio 1
	s_barrier
	s_add_u32 s30, s46, 0xc0080
	s_addc_u32 s31, s47, 0
	s_add_i32 s27, s36, s52
	v_lshl_add_u64 v[0:1], s[30:31], 0, v[138:139]
	s_mov_b32 m0, s27
	s_nop 0
	global_load_lds_dwordx4 v[0:1], off
	v_lshl_add_u64 v[0:1], s[30:31], 0, v[142:143]
	s_add_i32 m0, s27, 0x2000
	s_nop 0
	global_load_lds_dwordx4 v[0:1], off
	s_waitcnt vmcnt(6)
	s_barrier
	s_setprio 0
	v_mfma_f32_16x16x32_bf16 v[48:51], v[236:239], v[178:181], v[48:51]
	v_mfma_f32_16x16x32_bf16 v[44:47], v[244:247], v[178:181], v[44:47]
	v_mfma_f32_16x16x32_bf16 v[40:43], v[236:239], v[186:189], v[40:43]
	v_mfma_f32_16x16x32_bf16 v[36:39], v[244:247], v[186:189], v[36:39]
	v_mfma_f32_16x16x32_bf16 v[32:35], v[236:239], v[202:205], v[32:35]
	v_mfma_f32_16x16x32_bf16 v[28:31], v[244:247], v[202:205], v[28:31]
	v_mfma_f32_16x16x32_bf16 v[24:27], v[236:239], v[210:213], v[24:27]
	v_mfma_f32_16x16x32_bf16 v[20:23], v[244:247], v[210:213], v[20:23]
	v_mfma_f32_16x16x32_bf16 v[48:51], v[240:243], v[182:185], v[48:51]
	v_mfma_f32_16x16x32_bf16 v[44:47], v[248:251], v[182:185], v[44:47]
	v_mfma_f32_16x16x32_bf16 v[40:43], v[240:243], v[190:193], v[40:43]
	v_mfma_f32_16x16x32_bf16 v[36:39], v[248:251], v[190:193], v[36:39]
	v_mfma_f32_16x16x32_bf16 v[32:35], v[240:243], v[206:209], v[32:35]
	v_mfma_f32_16x16x32_bf16 v[28:31], v[248:251], v[206:209], v[28:31]
	v_mfma_f32_16x16x32_bf16 v[24:27], v[240:243], v[214:217], v[24:27]
	v_mfma_f32_16x16x32_bf16 v[20:23], v[248:251], v[214:217], v[20:23]
	s_setprio 1
	s_add_u32 s24, s24, 0x100
	s_addc_u32 s25, s25, 0
	s_cmp_ge_i32 s26, s22
	s_mov_b64 s[40:41], s[44:45]
	s_mov_b32 s27, s26
	s_barrier
	s_cbranch_scc0 .LBB0_175
	s_lshl_b32 s46, s66, 8
	v_lshl_or_b32 v0, s20, 8, v159
	s_mov_b32 s44, 0xbfb8aa3b
	s_mov_b32 s45, 0xbfb8aa3b
	v_lshlrev_b32_e32 v0, 1, v0
	v_add_u32_e32 v0, 0x1000, v0
	s_cmp_lg_u32 s21, 1
	s_cbranch_scc0 .Lg2_kind1
	v_readlane_b32 s22, v252, 34
	v_readlane_b32 s23, v252, 35
	v_add_u32_e32 v2, s46, v144
	v_mad_u32_u24 v2, v2, s29, v0
	global_load_dwordx4 v[132:135], v2, s[96:97] offset:2048
	v_add_u32_e32 v2, s46, v144
	v_mad_u32_u24 v2, v2, s29, v0
	global_load_dwordx4 v[178:181], v2, s[96:97] offset:2304
	v_add_u32_e32 v2, s46, v146
	v_mad_u32_u24 v2, v2, s29, v0
	global_load_dwordx4 v[182:185], v2, s[96:97] offset:2048
	v_add_u32_e32 v2, s46, v146
	v_mad_u32_u24 v2, v2, s29, v0
	global_load_dwordx4 v[186:189], v2, s[96:97] offset:2304
	v_add_u32_e32 v2, s46, v148
	v_mad_u32_u24 v2, v2, s29, v0
	global_load_dwordx4 v[190:193], v2, s[96:97] offset:2048
	v_add_u32_e32 v2, s46, v148
	v_mad_u32_u24 v2, v2, s29, v0
	global_load_dwordx4 v[202:205], v2, s[96:97] offset:2304
	v_add_u32_e32 v2, s46, v150
	v_mad_u32_u24 v2, v2, s29, v0
	global_load_dwordx4 v[206:209], v2, s[96:97] offset:2048
	v_add_u32_e32 v2, s46, v150
	v_mad_u32_u24 v2, v2, s29, v0
	global_load_dwordx4 v[210:213], v2, s[96:97] offset:2304
	v_add_u32_e32 v2, s46, v152
	v_mad_u32_u24 v2, v2, s29, v0
	global_load_dwordx4 v[214:217], v2, s[96:97] offset:2048
	v_add_u32_e32 v2, s46, v152
	v_mad_u32_u24 v2, v2, s29, v0
	global_load_dwordx4 v[236:239], v2, s[96:97] offset:2304
	v_add_u32_e32 v2, s46, v154
	v_mad_u32_u24 v2, v2, s29, v0
	global_load_dwordx4 v[240:243], v2, s[96:97] offset:2048
	v_add_u32_e32 v2, s46, v154
	v_mad_u32_u24 v2, v2, s29, v0
	global_load_dwordx4 v[244:247], v2, s[96:97] offset:2304
	v_add_u32_e32 v2, s46, v156
	v_mad_u32_u24 v2, v2, s29, v0
	global_load_dwordx4 v[248:251], v2, s[96:97] offset:2048
	s_waitcnt vmcnt(12)
	v_lshlrev_b32_e32 v164, 16, v132
	v_and_b32_e32 v165, 0xffff0000, v132
	v_lshlrev_b32_e32 v166, 16, v133
	v_and_b32_e32 v167, 0xffff0000, v133
	v_lshlrev_b32_e32 v168, 16, v134
	v_and_b32_e32 v169, 0xffff0000, v134
	v_lshlrev_b32_e32 v170, 16, v135
	v_and_b32_e32 v171, 0xffff0000, v135
	v_add_u32_e32 v2, s46, v156
	v_mad_u32_u24 v2, v2, s29, v0
	global_load_dwordx4 v[132:135], v2, s[96:97] offset:2304
	v_add_u32_e32 v1, s46, v144
	v_lshl_add_u32 v1, v1, 11, v0
	v_med3_f32 v164, v164, s34, v227
	v_med3_f32 v165, v165, s34, v227
	v_med3_f32 v166, v166, s34, v227
	v_med3_f32 v167, v167, s34, v227
	v_med3_f32 v168, v168, s34, v227
	v_med3_f32 v169, v169, s34, v227
	v_med3_f32 v170, v170, s34, v227
	v_med3_f32 v171, v171, s34, v227
	v_pk_mul_f32 v[164:165], v[164:165], s[44:45]
	v_pk_mul_f32 v[166:167], v[166:167], s[44:45]
	v_pk_mul_f32 v[168:169], v[168:169], s[44:45]
	v_pk_mul_f32 v[170:171], v[170:171], s[44:45]
	v_exp_f32_e32 v164, v164
	v_exp_f32_e32 v165, v165
	v_exp_f32_e32 v166, v166
	v_exp_f32_e32 v167, v167
	v_exp_f32_e32 v168, v168
	v_exp_f32_e32 v169, v169
	v_exp_f32_e32 v170, v170
	v_exp_f32_e32 v171, v171
	v_pk_add_f32 v[164:165], v[164:165], 1.0 op_sel_hi:[1,0]
	v_pk_add_f32 v[166:167], v[166:167], 1.0 op_sel_hi:[1,0]
	v_pk_add_f32 v[168:169], v[168:169], 1.0 op_sel_hi:[1,0]
	v_pk_add_f32 v[170:171], v[170:171], 1.0 op_sel_hi:[1,0]
	v_rcp_f32_e32 v164, v164
	v_rcp_f32_e32 v165, v165
	v_rcp_f32_e32 v166, v166
	v_rcp_f32_e32 v167, v167
	v_rcp_f32_e32 v168, v168
	v_rcp_f32_e32 v169, v169
	v_rcp_f32_e32 v170, v170
	v_rcp_f32_e32 v171, v171
	v_pk_mul_f32 v[164:165], v[4:5], v[164:165]
	v_pk_mul_f32 v[166:167], v[6:7], v[166:167]
	v_pk_mul_f32 v[168:169], v[8:9], v[168:169]
	v_pk_mul_f32 v[170:171], v[10:11], v[170:171]
	v_cvt_pk_bf16_f32 v174, v164, v165
	v_cvt_pk_bf16_f32 v175, v166, v167
	v_cvt_pk_bf16_f32 v176, v168, v169
	v_cvt_pk_bf16_f32 v177, v170, v171
	global_store_dwordx4 v1, v[174:177], s[22:23] offset:-4096
	s_waitcnt vmcnt(13)
	v_lshlrev_b32_e32 v164, 16, v178
	v_and_b32_e32 v165, 0xffff0000, v178
	v_lshlrev_b32_e32 v166, 16, v179
	v_and_b32_e32 v167, 0xffff0000, v179
	v_lshlrev_b32_e32 v168, 16, v180
	v_and_b32_e32 v169, 0xffff0000, v180
	v_lshlrev_b32_e32 v170, 16, v181
	v_and_b32_e32 v171, 0xffff0000, v181
	v_add_u32_e32 v2, s46, v158
	v_mad_u32_u24 v2, v2, s29, v0
	global_load_dwordx4 v[178:181], v2, s[96:97] offset:2048
	v_med3_f32 v164, v164, s34, v227
	v_med3_f32 v165, v165, s34, v227
	v_med3_f32 v166, v166, s34, v227
	v_med3_f32 v167, v167, s34, v227
	v_med3_f32 v168, v168, s34, v227
	v_med3_f32 v169, v169, s34, v227
	v_med3_f32 v170, v170, s34, v227
	v_med3_f32 v171, v171, s34, v227
	v_pk_mul_f32 v[164:165], v[164:165], s[44:45]
	v_pk_mul_f32 v[166:167], v[166:167], s[44:45]
	v_pk_mul_f32 v[168:169], v[168:169], s[44:45]
	v_pk_mul_f32 v[170:171], v[170:171], s[44:45]
	v_exp_f32_e32 v164, v164
	v_exp_f32_e32 v165, v165
	v_exp_f32_e32 v166, v166
	v_exp_f32_e32 v167, v167
	v_exp_f32_e32 v168, v168
	v_exp_f32_e32 v169, v169
	v_exp_f32_e32 v170, v170
	v_exp_f32_e32 v171, v171
	v_pk_add_f32 v[164:165], v[164:165], 1.0 op_sel_hi:[1,0]
	v_pk_add_f32 v[166:167], v[166:167], 1.0 op_sel_hi:[1,0]
	v_pk_add_f32 v[168:169], v[168:169], 1.0 op_sel_hi:[1,0]
	v_pk_add_f32 v[170:171], v[170:171], 1.0 op_sel_hi:[1,0]
	v_rcp_f32_e32 v164, v164
	v_rcp_f32_e32 v165, v165
	v_rcp_f32_e32 v166, v166
	v_rcp_f32_e32 v167, v167
	v_rcp_f32_e32 v168, v168
	v_rcp_f32_e32 v169, v169
	v_rcp_f32_e32 v170, v170
	v_rcp_f32_e32 v171, v171
	v_pk_mul_f32 v[164:165], v[12:13], v[164:165]
	v_pk_mul_f32 v[166:167], v[14:15], v[166:167]
	v_pk_mul_f32 v[168:169], v[16:17], v[168:169]
	v_pk_mul_f32 v[170:171], v[18:19], v[170:171]
	v_cvt_pk_bf16_f32 v174, v164, v165
	v_cvt_pk_bf16_f32 v175, v166, v167
	v_cvt_pk_bf16_f32 v176, v168, v169
	v_cvt_pk_bf16_f32 v177, v170, v171
	global_store_dwordx4 v1, v[174:177], s[22:23] offset:-3840
	s_waitcnt vmcnt(14)
	v_lshlrev_b32_e32 v164, 16, v182
	v_and_b32_e32 v165, 0xffff0000, v182
	v_lshlrev_b32_e32 v166, 16, v183
	v_and_b32_e32 v167, 0xffff0000, v183
	v_lshlrev_b32_e32 v168, 16, v184
	v_and_b32_e32 v169, 0xffff0000, v184
	v_lshlrev_b32_e32 v170, 16, v185
	v_and_b32_e32 v171, 0xffff0000, v185
	v_add_u32_e32 v2, s46, v158
	v_mad_u32_u24 v2, v2, s29, v0
	global_load_dwordx4 v[182:185], v2, s[96:97] offset:2304
	v_add_u32_e32 v1, s46, v146
	v_lshl_add_u32 v1, v1, 11, v0
	v_med3_f32 v164, v164, s34, v227
	v_med3_f32 v165, v165, s34, v227
	v_med3_f32 v166, v166, s34, v227
	v_med3_f32 v167, v167, s34, v227
	v_med3_f32 v168, v168, s34, v227
	v_med3_f32 v169, v169, s34, v227
	v_med3_f32 v170, v170, s34, v227
	v_med3_f32 v171, v171, s34, v227
	v_pk_mul_f32 v[164:165], v[164:165], s[44:45]
	v_pk_mul_f32 v[166:167], v[166:167], s[44:45]
	v_pk_mul_f32 v[168:169], v[168:169], s[44:45]
	v_pk_mul_f32 v[170:171], v[170:171], s[44:45]
	v_exp_f32_e32 v164, v164
	v_exp_f32_e32 v165, v165
	v_exp_f32_e32 v166, v166
	v_exp_f32_e32 v167, v167
	v_exp_f32_e32 v168, v168
	v_exp_f32_e32 v169, v169
	v_exp_f32_e32 v170, v170
	v_exp_f32_e32 v171, v171
	v_pk_add_f32 v[164:165], v[164:165], 1.0 op_sel_hi:[1,0]
	v_pk_add_f32 v[166:167], v[166:167], 1.0 op_sel_hi:[1,0]
	v_pk_add_f32 v[168:169], v[168:169], 1.0 op_sel_hi:[1,0]
	v_pk_add_f32 v[170:171], v[170:171], 1.0 op_sel_hi:[1,0]
	v_rcp_f32_e32 v164, v164
	v_rcp_f32_e32 v165, v165
	v_rcp_f32_e32 v166, v166
	v_rcp_f32_e32 v167, v167
	v_rcp_f32_e32 v168, v168
	v_rcp_f32_e32 v169, v169
	v_rcp_f32_e32 v170, v170
	v_rcp_f32_e32 v171, v171
	v_pk_mul_f32 v[164:165], v[128:129], v[164:165]
	v_pk_mul_f32 v[166:167], v[130:131], v[166:167]
	v_pk_mul_f32 v[168:169], v[124:125], v[168:169]
	v_pk_mul_f32 v[170:171], v[126:127], v[170:171]
	v_cvt_pk_bf16_f32 v174, v164, v165
	v_cvt_pk_bf16_f32 v175, v166, v167
	v_cvt_pk_bf16_f32 v176, v168, v169
	v_cvt_pk_bf16_f32 v177, v170, v171
	global_store_dwordx4 v1, v[174:177], s[22:23] offset:-4096
	s_waitcnt vmcnt(15)
	v_lshlrev_b32_e32 v164, 16, v186
	v_and_b32_e32 v165, 0xffff0000, v186
	v_lshlrev_b32_e32 v166, 16, v187
	v_and_b32_e32 v167, 0xffff0000, v187
	v_lshlrev_b32_e32 v168, 16, v188
	v_and_b32_e32 v169, 0xffff0000, v188
	v_lshlrev_b32_e32 v170, 16, v189
	v_and_b32_e32 v171, 0xffff0000, v189
	v_med3_f32 v164, v164, s34, v227
	v_med3_f32 v165, v165, s34, v227
	v_med3_f32 v166, v166, s34, v227
	v_med3_f32 v167, v167, s34, v227
	v_med3_f32 v168, v168, s34, v227
	v_med3_f32 v169, v169, s34, v227
	v_med3_f32 v170, v170, s34, v227
	v_med3_f32 v171, v171, s34, v227
	v_pk_mul_f32 v[164:165], v[164:165], s[44:45]
	v_pk_mul_f32 v[166:167], v[166:167], s[44:45]
	v_pk_mul_f32 v[168:169], v[168:169], s[44:45]
	v_pk_mul_f32 v[170:171], v[170:171], s[44:45]
	v_exp_f32_e32 v164, v164
	v_exp_f32_e32 v165, v165
	v_exp_f32_e32 v166, v166
	v_exp_f32_e32 v167, v167
	v_exp_f32_e32 v168, v168
	v_exp_f32_e32 v169, v169
	v_exp_f32_e32 v170, v170
	v_exp_f32_e32 v171, v171
	v_pk_add_f32 v[164:165], v[164:165], 1.0 op_sel_hi:[1,0]
	v_pk_add_f32 v[166:167], v[166:167], 1.0 op_sel_hi:[1,0]
	v_pk_add_f32 v[168:169], v[168:169], 1.0 op_sel_hi:[1,0]
	v_pk_add_f32 v[170:171], v[170:171], 1.0 op_sel_hi:[1,0]
	v_rcp_f32_e32 v164, v164
	v_rcp_f32_e32 v165, v165
	v_rcp_f32_e32 v166, v166
	v_rcp_f32_e32 v167, v167
	v_rcp_f32_e32 v168, v168
	v_rcp_f32_e32 v169, v169
	v_rcp_f32_e32 v170, v170
	v_rcp_f32_e32 v171, v171
	v_pk_mul_f32 v[164:165], v[104:105], v[164:165]
	v_pk_mul_f32 v[166:167], v[106:107], v[166:167]
	v_pk_mul_f32 v[168:169], v[100:101], v[168:169]
	v_pk_mul_f32 v[170:171], v[102:103], v[170:171]
	v_cvt_pk_bf16_f32 v174, v164, v165
	v_cvt_pk_bf16_f32 v175, v166, v167
	v_cvt_pk_bf16_f32 v176, v168, v169
	v_cvt_pk_bf16_f32 v177, v170, v171
	global_store_dwordx4 v1, v[174:177], s[22:23] offset:-3840
	s_waitcnt vmcnt(15)
	v_lshlrev_b32_e32 v164, 16, v190
	v_and_b32_e32 v165, 0xffff0000, v190
	v_lshlrev_b32_e32 v166, 16, v191
	v_and_b32_e32 v167, 0xffff0000, v191
	v_lshlrev_b32_e32 v168, 16, v192
	v_and_b32_e32 v169, 0xffff0000, v192
	v_lshlrev_b32_e32 v170, 16, v193
	v_and_b32_e32 v171, 0xffff0000, v193
	v_add_u32_e32 v1, s46, v148
	v_lshl_add_u32 v1, v1, 11, v0
	v_med3_f32 v164, v164, s34, v227
	v_med3_f32 v165, v165, s34, v227
	v_med3_f32 v166, v166, s34, v227
	v_med3_f32 v167, v167, s34, v227
	v_med3_f32 v168, v168, s34, v227
	v_med3_f32 v169, v169, s34, v227
	v_med3_f32 v170, v170, s34, v227
	v_med3_f32 v171, v171, s34, v227
	v_pk_mul_f32 v[164:165], v[164:165], s[44:45]
	v_pk_mul_f32 v[166:167], v[166:167], s[44:45]
	v_pk_mul_f32 v[168:169], v[168:169], s[44:45]
	v_pk_mul_f32 v[170:171], v[170:171], s[44:45]
	v_exp_f32_e32 v164, v164
	v_exp_f32_e32 v165, v165
	v_exp_f32_e32 v166, v166
	v_exp_f32_e32 v167, v167
	v_exp_f32_e32 v168, v168
	v_exp_f32_e32 v169, v169
	v_exp_f32_e32 v170, v170
	v_exp_f32_e32 v171, v171
	v_pk_add_f32 v[164:165], v[164:165], 1.0 op_sel_hi:[1,0]
	v_pk_add_f32 v[166:167], v[166:167], 1.0 op_sel_hi:[1,0]
	v_pk_add_f32 v[168:169], v[168:169], 1.0 op_sel_hi:[1,0]
	v_pk_add_f32 v[170:171], v[170:171], 1.0 op_sel_hi:[1,0]
	v_rcp_f32_e32 v164, v164
	v_rcp_f32_e32 v165, v165
	v_rcp_f32_e32 v166, v166
	v_rcp_f32_e32 v167, v167
	v_rcp_f32_e32 v168, v168
	v_rcp_f32_e32 v169, v169
	v_rcp_f32_e32 v170, v170
	v_rcp_f32_e32 v171, v171
	v_pk_mul_f32 v[164:165], v[120:121], v[164:165]
	v_pk_mul_f32 v[166:167], v[122:123], v[166:167]
	v_pk_mul_f32 v[168:169], v[116:117], v[168:169]
	v_pk_mul_f32 v[170:171], v[118:119], v[170:171]
	v_cvt_pk_bf16_f32 v174, v164, v165
	v_cvt_pk_bf16_f32 v175, v166, v167
	v_cvt_pk_bf16_f32 v176, v168, v169
	v_cvt_pk_bf16_f32 v177, v170, v171
	global_store_dwordx4 v1, v[174:177], s[22:23] offset:-4096
	s_waitcnt vmcnt(15)
	v_lshlrev_b32_e32 v164, 16, v202
	v_and_b32_e32 v165, 0xffff0000, v202
	v_lshlrev_b32_e32 v166, 16, v203
	v_and_b32_e32 v167, 0xffff0000, v203
	v_lshlrev_b32_e32 v168, 16, v204
	v_and_b32_e32 v169, 0xffff0000, v204
	v_lshlrev_b32_e32 v170, 16, v205
	v_and_b32_e32 v171, 0xffff0000, v205
	v_med3_f32 v164, v164, s34, v227
	v_med3_f32 v165, v165, s34, v227
	v_med3_f32 v166, v166, s34, v227
	v_med3_f32 v167, v167, s34, v227
	v_med3_f32 v168, v168, s34, v227
	v_med3_f32 v169, v169, s34, v227
	v_med3_f32 v170, v170, s34, v227
	v_med3_f32 v171, v171, s34, v227
	v_pk_mul_f32 v[164:165], v[164:165], s[44:45]
	v_pk_mul_f32 v[166:167], v[166:167], s[44:45]
	v_pk_mul_f32 v[168:169], v[168:169], s[44:45]
	v_pk_mul_f32 v[170:171], v[170:171], s[44:45]
	v_exp_f32_e32 v164, v164
	v_exp_f32_e32 v165, v165
	v_exp_f32_e32 v166, v166
	v_exp_f32_e32 v167, v167
	v_exp_f32_e32 v168, v168
	v_exp_f32_e32 v169, v169
	v_exp_f32_e32 v170, v170
	v_exp_f32_e32 v171, v171
	v_pk_add_f32 v[164:165], v[164:165], 1.0 op_sel_hi:[1,0]
	v_pk_add_f32 v[166:167], v[166:167], 1.0 op_sel_hi:[1,0]
	v_pk_add_f32 v[168:169], v[168:169], 1.0 op_sel_hi:[1,0]
	v_pk_add_f32 v[170:171], v[170:171], 1.0 op_sel_hi:[1,0]
	v_rcp_f32_e32 v164, v164
	v_rcp_f32_e32 v165, v165
	v_rcp_f32_e32 v166, v166
	v_rcp_f32_e32 v167, v167
	v_rcp_f32_e32 v168, v168
	v_rcp_f32_e32 v169, v169
	v_rcp_f32_e32 v170, v170
	v_rcp_f32_e32 v171, v171
	v_pk_mul_f32 v[164:165], v[96:97], v[164:165]
	v_pk_mul_f32 v[166:167], v[98:99], v[166:167]
	v_pk_mul_f32 v[168:169], v[92:93], v[168:169]
	v_pk_mul_f32 v[170:171], v[94:95], v[170:171]
	v_cvt_pk_bf16_f32 v174, v164, v165
	v_cvt_pk_bf16_f32 v175, v166, v167
	v_cvt_pk_bf16_f32 v176, v168, v169
	v_cvt_pk_bf16_f32 v177, v170, v171
	global_store_dwordx4 v1, v[174:177], s[22:23] offset:-3840
	s_waitcnt vmcnt(15)
	v_lshlrev_b32_e32 v164, 16, v206
	v_and_b32_e32 v165, 0xffff0000, v206
	v_lshlrev_b32_e32 v166, 16, v207
	v_and_b32_e32 v167, 0xffff0000, v207
	v_lshlrev_b32_e32 v168, 16, v208
	v_and_b32_e32 v169, 0xffff0000, v208
	v_lshlrev_b32_e32 v170, 16, v209
	v_and_b32_e32 v171, 0xffff0000, v209
	v_add_u32_e32 v1, s46, v150
	v_lshl_add_u32 v1, v1, 11, v0
	v_med3_f32 v164, v164, s34, v227
	v_med3_f32 v165, v165, s34, v227
	v_med3_f32 v166, v166, s34, v227
	v_med3_f32 v167, v167, s34, v227
	v_med3_f32 v168, v168, s34, v227
	v_med3_f32 v169, v169, s34, v227
	v_med3_f32 v170, v170, s34, v227
	v_med3_f32 v171, v171, s34, v227
	v_pk_mul_f32 v[164:165], v[164:165], s[44:45]
	v_pk_mul_f32 v[166:167], v[166:167], s[44:45]
	v_pk_mul_f32 v[168:169], v[168:169], s[44:45]
	v_pk_mul_f32 v[170:171], v[170:171], s[44:45]
	v_exp_f32_e32 v164, v164
	v_exp_f32_e32 v165, v165
	v_exp_f32_e32 v166, v166
	v_exp_f32_e32 v167, v167
	v_exp_f32_e32 v168, v168
	v_exp_f32_e32 v169, v169
	v_exp_f32_e32 v170, v170
	v_exp_f32_e32 v171, v171
	v_pk_add_f32 v[164:165], v[164:165], 1.0 op_sel_hi:[1,0]
	v_pk_add_f32 v[166:167], v[166:167], 1.0 op_sel_hi:[1,0]
	v_pk_add_f32 v[168:169], v[168:169], 1.0 op_sel_hi:[1,0]
	v_pk_add_f32 v[170:171], v[170:171], 1.0 op_sel_hi:[1,0]
	v_rcp_f32_e32 v164, v164
	v_rcp_f32_e32 v165, v165
	v_rcp_f32_e32 v166, v166
	v_rcp_f32_e32 v167, v167
	v_rcp_f32_e32 v168, v168
	v_rcp_f32_e32 v169, v169
	v_rcp_f32_e32 v170, v170
	v_rcp_f32_e32 v171, v171
	v_pk_mul_f32 v[164:165], v[112:113], v[164:165]
	v_pk_mul_f32 v[166:167], v[114:115], v[166:167]
	v_pk_mul_f32 v[168:169], v[108:109], v[168:169]
	v_pk_mul_f32 v[170:171], v[110:111], v[170:171]
	v_cvt_pk_bf16_f32 v174, v164, v165
	v_cvt_pk_bf16_f32 v175, v166, v167
	v_cvt_pk_bf16_f32 v176, v168, v169
	v_cvt_pk_bf16_f32 v177, v170, v171
	global_store_dwordx4 v1, v[174:177], s[22:23] offset:-4096
	s_waitcnt vmcnt(15)
	v_lshlrev_b32_e32 v164, 16, v210
	v_and_b32_e32 v165, 0xffff0000, v210
	v_lshlrev_b32_e32 v166, 16, v211
	v_and_b32_e32 v167, 0xffff0000, v211
	v_lshlrev_b32_e32 v168, 16, v212
	v_and_b32_e32 v169, 0xffff0000, v212
	v_lshlrev_b32_e32 v170, 16, v213
	v_and_b32_e32 v171, 0xffff0000, v213
	v_med3_f32 v164, v164, s34, v227
	v_med3_f32 v165, v165, s34, v227
	v_med3_f32 v166, v166, s34, v227
	v_med3_f32 v167, v167, s34, v227
	v_med3_f32 v168, v168, s34, v227
	v_med3_f32 v169, v169, s34, v227
	v_med3_f32 v170, v170, s34, v227
	v_med3_f32 v171, v171, s34, v227
	v_pk_mul_f32 v[164:165], v[164:165], s[44:45]
	v_pk_mul_f32 v[166:167], v[166:167], s[44:45]
	v_pk_mul_f32 v[168:169], v[168:169], s[44:45]
	v_pk_mul_f32 v[170:171], v[170:171], s[44:45]
	v_exp_f32_e32 v164, v164
	v_exp_f32_e32 v165, v165
	v_exp_f32_e32 v166, v166
	v_exp_f32_e32 v167, v167
	v_exp_f32_e32 v168, v168
	v_exp_f32_e32 v169, v169
	v_exp_f32_e32 v170, v170
	v_exp_f32_e32 v171, v171
	v_pk_add_f32 v[164:165], v[164:165], 1.0 op_sel_hi:[1,0]
	v_pk_add_f32 v[166:167], v[166:167], 1.0 op_sel_hi:[1,0]
	v_pk_add_f32 v[168:169], v[168:169], 1.0 op_sel_hi:[1,0]
	v_pk_add_f32 v[170:171], v[170:171], 1.0 op_sel_hi:[1,0]
	v_rcp_f32_e32 v164, v164
	v_rcp_f32_e32 v165, v165
	v_rcp_f32_e32 v166, v166
	v_rcp_f32_e32 v167, v167
	v_rcp_f32_e32 v168, v168
	v_rcp_f32_e32 v169, v169
	v_rcp_f32_e32 v170, v170
	v_rcp_f32_e32 v171, v171
	v_pk_mul_f32 v[164:165], v[88:89], v[164:165]
	v_pk_mul_f32 v[166:167], v[90:91], v[166:167]
	v_pk_mul_f32 v[168:169], v[84:85], v[168:169]
	v_pk_mul_f32 v[170:171], v[86:87], v[170:171]
	v_cvt_pk_bf16_f32 v174, v164, v165
	v_cvt_pk_bf16_f32 v175, v166, v167
	v_cvt_pk_bf16_f32 v176, v168, v169
	v_cvt_pk_bf16_f32 v177, v170, v171
	global_store_dwordx4 v1, v[174:177], s[22:23] offset:-3840
	s_waitcnt vmcnt(15)
	v_lshlrev_b32_e32 v164, 16, v214
	v_and_b32_e32 v165, 0xffff0000, v214
	v_lshlrev_b32_e32 v166, 16, v215
	v_and_b32_e32 v167, 0xffff0000, v215
	v_lshlrev_b32_e32 v168, 16, v216
	v_and_b32_e32 v169, 0xffff0000, v216
	v_lshlrev_b32_e32 v170, 16, v217
	v_and_b32_e32 v171, 0xffff0000, v217
	v_add_u32_e32 v1, s46, v152
	v_lshl_add_u32 v1, v1, 11, v0
	v_med3_f32 v164, v164, s34, v227
	v_med3_f32 v165, v165, s34, v227
	v_med3_f32 v166, v166, s34, v227
	v_med3_f32 v167, v167, s34, v227
	v_med3_f32 v168, v168, s34, v227
	v_med3_f32 v169, v169, s34, v227
	v_med3_f32 v170, v170, s34, v227
	v_med3_f32 v171, v171, s34, v227
	v_pk_mul_f32 v[164:165], v[164:165], s[44:45]
	v_pk_mul_f32 v[166:167], v[166:167], s[44:45]
	v_pk_mul_f32 v[168:169], v[168:169], s[44:45]
	v_pk_mul_f32 v[170:171], v[170:171], s[44:45]
	v_exp_f32_e32 v164, v164
	v_exp_f32_e32 v165, v165
	v_exp_f32_e32 v166, v166
	v_exp_f32_e32 v167, v167
	v_exp_f32_e32 v168, v168
	v_exp_f32_e32 v169, v169
	v_exp_f32_e32 v170, v170
	v_exp_f32_e32 v171, v171
	v_pk_add_f32 v[164:165], v[164:165], 1.0 op_sel_hi:[1,0]
	v_pk_add_f32 v[166:167], v[166:167], 1.0 op_sel_hi:[1,0]
	v_pk_add_f32 v[168:169], v[168:169], 1.0 op_sel_hi:[1,0]
	v_pk_add_f32 v[170:171], v[170:171], 1.0 op_sel_hi:[1,0]
	v_rcp_f32_e32 v164, v164
	v_rcp_f32_e32 v165, v165
	v_rcp_f32_e32 v166, v166
	v_rcp_f32_e32 v167, v167
	v_rcp_f32_e32 v168, v168
	v_rcp_f32_e32 v169, v169
	v_rcp_f32_e32 v170, v170
	v_rcp_f32_e32 v171, v171
	v_pk_mul_f32 v[164:165], v[80:81], v[164:165]
	v_pk_mul_f32 v[166:167], v[82:83], v[166:167]
	v_pk_mul_f32 v[168:169], v[76:77], v[168:169]
	v_pk_mul_f32 v[170:171], v[78:79], v[170:171]
	v_cvt_pk_bf16_f32 v174, v164, v165
	v_cvt_pk_bf16_f32 v175, v166, v167
	v_cvt_pk_bf16_f32 v176, v168, v169
	v_cvt_pk_bf16_f32 v177, v170, v171
	global_store_dwordx4 v1, v[174:177], s[22:23] offset:-4096
	s_waitcnt vmcnt(15)
	v_lshlrev_b32_e32 v164, 16, v236
	v_and_b32_e32 v165, 0xffff0000, v236
	v_lshlrev_b32_e32 v166, 16, v237
	v_and_b32_e32 v167, 0xffff0000, v237
	v_lshlrev_b32_e32 v168, 16, v238
	v_and_b32_e32 v169, 0xffff0000, v238
	v_lshlrev_b32_e32 v170, 16, v239
	v_and_b32_e32 v171, 0xffff0000, v239
	v_med3_f32 v164, v164, s34, v227
	v_med3_f32 v165, v165, s34, v227
	v_med3_f32 v166, v166, s34, v227
	v_med3_f32 v167, v167, s34, v227
	v_med3_f32 v168, v168, s34, v227
	v_med3_f32 v169, v169, s34, v227
	v_med3_f32 v170, v170, s34, v227
	v_med3_f32 v171, v171, s34, v227
	v_pk_mul_f32 v[164:165], v[164:165], s[44:45]
	v_pk_mul_f32 v[166:167], v[166:167], s[44:45]
	v_pk_mul_f32 v[168:169], v[168:169], s[44:45]
	v_pk_mul_f32 v[170:171], v[170:171], s[44:45]
	v_exp_f32_e32 v164, v164
	v_exp_f32_e32 v165, v165
	v_exp_f32_e32 v166, v166
	v_exp_f32_e32 v167, v167
	v_exp_f32_e32 v168, v168
	v_exp_f32_e32 v169, v169
	v_exp_f32_e32 v170, v170
	v_exp_f32_e32 v171, v171
	v_pk_add_f32 v[164:165], v[164:165], 1.0 op_sel_hi:[1,0]
	v_pk_add_f32 v[166:167], v[166:167], 1.0 op_sel_hi:[1,0]
	v_pk_add_f32 v[168:169], v[168:169], 1.0 op_sel_hi:[1,0]
	v_pk_add_f32 v[170:171], v[170:171], 1.0 op_sel_hi:[1,0]
	v_rcp_f32_e32 v164, v164
	v_rcp_f32_e32 v165, v165
	v_rcp_f32_e32 v166, v166
	v_rcp_f32_e32 v167, v167
	v_rcp_f32_e32 v168, v168
	v_rcp_f32_e32 v169, v169
	v_rcp_f32_e32 v170, v170
	v_rcp_f32_e32 v171, v171
	v_pk_mul_f32 v[164:165], v[48:49], v[164:165]
	v_pk_mul_f32 v[166:167], v[50:51], v[166:167]
	v_pk_mul_f32 v[168:169], v[44:45], v[168:169]
	v_pk_mul_f32 v[170:171], v[46:47], v[170:171]
	v_cvt_pk_bf16_f32 v174, v164, v165
	v_cvt_pk_bf16_f32 v175, v166, v167
	v_cvt_pk_bf16_f32 v176, v168, v169
	v_cvt_pk_bf16_f32 v177, v170, v171
	global_store_dwordx4 v1, v[174:177], s[22:23] offset:-3840
	s_waitcnt vmcnt(15)
	v_lshlrev_b32_e32 v164, 16, v240
	v_and_b32_e32 v165, 0xffff0000, v240
	v_lshlrev_b32_e32 v166, 16, v241
	v_and_b32_e32 v167, 0xffff0000, v241
	v_lshlrev_b32_e32 v168, 16, v242
	v_and_b32_e32 v169, 0xffff0000, v242
	v_lshlrev_b32_e32 v170, 16, v243
	v_and_b32_e32 v171, 0xffff0000, v243
	v_add_u32_e32 v1, s46, v154
	v_lshl_add_u32 v1, v1, 11, v0
	v_med3_f32 v164, v164, s34, v227
	v_med3_f32 v165, v165, s34, v227
	v_med3_f32 v166, v166, s34, v227
	v_med3_f32 v167, v167, s34, v227
	v_med3_f32 v168, v168, s34, v227
	v_med3_f32 v169, v169, s34, v227
	v_med3_f32 v170, v170, s34, v227
	v_med3_f32 v171, v171, s34, v227
	v_pk_mul_f32 v[164:165], v[164:165], s[44:45]
	v_pk_mul_f32 v[166:167], v[166:167], s[44:45]
	v_pk_mul_f32 v[168:169], v[168:169], s[44:45]
	v_pk_mul_f32 v[170:171], v[170:171], s[44:45]
	v_exp_f32_e32 v164, v164
	v_exp_f32_e32 v165, v165
	v_exp_f32_e32 v166, v166
	v_exp_f32_e32 v167, v167
	v_exp_f32_e32 v168, v168
	v_exp_f32_e32 v169, v169
	v_exp_f32_e32 v170, v170
	v_exp_f32_e32 v171, v171
	v_pk_add_f32 v[164:165], v[164:165], 1.0 op_sel_hi:[1,0]
	v_pk_add_f32 v[166:167], v[166:167], 1.0 op_sel_hi:[1,0]
	v_pk_add_f32 v[168:169], v[168:169], 1.0 op_sel_hi:[1,0]
	v_pk_add_f32 v[170:171], v[170:171], 1.0 op_sel_hi:[1,0]
	v_rcp_f32_e32 v164, v164
	v_rcp_f32_e32 v165, v165
	v_rcp_f32_e32 v166, v166
	v_rcp_f32_e32 v167, v167
	v_rcp_f32_e32 v168, v168
	v_rcp_f32_e32 v169, v169
	v_rcp_f32_e32 v170, v170
	v_rcp_f32_e32 v171, v171
	v_pk_mul_f32 v[164:165], v[72:73], v[164:165]
	v_pk_mul_f32 v[166:167], v[74:75], v[166:167]
	v_pk_mul_f32 v[168:169], v[68:69], v[168:169]
	v_pk_mul_f32 v[170:171], v[70:71], v[170:171]
	v_cvt_pk_bf16_f32 v174, v164, v165
	v_cvt_pk_bf16_f32 v175, v166, v167
	v_cvt_pk_bf16_f32 v176, v168, v169
	v_cvt_pk_bf16_f32 v177, v170, v171
	global_store_dwordx4 v1, v[174:177], s[22:23] offset:-4096
	s_waitcnt vmcnt(15)
	v_lshlrev_b32_e32 v164, 16, v244
	v_and_b32_e32 v165, 0xffff0000, v244
	v_lshlrev_b32_e32 v166, 16, v245
	v_and_b32_e32 v167, 0xffff0000, v245
	v_lshlrev_b32_e32 v168, 16, v246
	v_and_b32_e32 v169, 0xffff0000, v246
	v_lshlrev_b32_e32 v170, 16, v247
	v_and_b32_e32 v171, 0xffff0000, v247
	v_med3_f32 v164, v164, s34, v227
	v_med3_f32 v165, v165, s34, v227
	v_med3_f32 v166, v166, s34, v227
	v_med3_f32 v167, v167, s34, v227
	v_med3_f32 v168, v168, s34, v227
	v_med3_f32 v169, v169, s34, v227
	v_med3_f32 v170, v170, s34, v227
	v_med3_f32 v171, v171, s34, v227
	v_pk_mul_f32 v[164:165], v[164:165], s[44:45]
	v_pk_mul_f32 v[166:167], v[166:167], s[44:45]
	v_pk_mul_f32 v[168:169], v[168:169], s[44:45]
	v_pk_mul_f32 v[170:171], v[170:171], s[44:45]
	v_exp_f32_e32 v164, v164
	v_exp_f32_e32 v165, v165
	v_exp_f32_e32 v166, v166
	v_exp_f32_e32 v167, v167
	v_exp_f32_e32 v168, v168
	v_exp_f32_e32 v169, v169
	v_exp_f32_e32 v170, v170
	v_exp_f32_e32 v171, v171
	v_pk_add_f32 v[164:165], v[164:165], 1.0 op_sel_hi:[1,0]
	v_pk_add_f32 v[166:167], v[166:167], 1.0 op_sel_hi:[1,0]
	v_pk_add_f32 v[168:169], v[168:169], 1.0 op_sel_hi:[1,0]
	v_pk_add_f32 v[170:171], v[170:171], 1.0 op_sel_hi:[1,0]
	v_rcp_f32_e32 v164, v164
	v_rcp_f32_e32 v165, v165
	v_rcp_f32_e32 v166, v166
	v_rcp_f32_e32 v167, v167
	v_rcp_f32_e32 v168, v168
	v_rcp_f32_e32 v169, v169
	v_rcp_f32_e32 v170, v170
	v_rcp_f32_e32 v171, v171
	v_pk_mul_f32 v[164:165], v[40:41], v[164:165]
	v_pk_mul_f32 v[166:167], v[42:43], v[166:167]
	v_pk_mul_f32 v[168:169], v[36:37], v[168:169]
	v_pk_mul_f32 v[170:171], v[38:39], v[170:171]
	v_cvt_pk_bf16_f32 v174, v164, v165
	v_cvt_pk_bf16_f32 v175, v166, v167
	v_cvt_pk_bf16_f32 v176, v168, v169
	v_cvt_pk_bf16_f32 v177, v170, v171
	global_store_dwordx4 v1, v[174:177], s[22:23] offset:-3840
	s_waitcnt vmcnt(15)
	v_lshlrev_b32_e32 v164, 16, v248
	v_and_b32_e32 v165, 0xffff0000, v248
	v_lshlrev_b32_e32 v166, 16, v249
	v_and_b32_e32 v167, 0xffff0000, v249
	v_lshlrev_b32_e32 v168, 16, v250
	v_and_b32_e32 v169, 0xffff0000, v250
	v_lshlrev_b32_e32 v170, 16, v251
	v_and_b32_e32 v171, 0xffff0000, v251
	v_add_u32_e32 v1, s46, v156
	v_lshl_add_u32 v1, v1, 11, v0
	v_med3_f32 v164, v164, s34, v227
	v_med3_f32 v165, v165, s34, v227
	v_med3_f32 v166, v166, s34, v227
	v_med3_f32 v167, v167, s34, v227
	v_med3_f32 v168, v168, s34, v227
	v_med3_f32 v169, v169, s34, v227
	v_med3_f32 v170, v170, s34, v227
	v_med3_f32 v171, v171, s34, v227
	v_pk_mul_f32 v[164:165], v[164:165], s[44:45]
	v_pk_mul_f32 v[166:167], v[166:167], s[44:45]
	v_pk_mul_f32 v[168:169], v[168:169], s[44:45]
	v_pk_mul_f32 v[170:171], v[170:171], s[44:45]
	v_exp_f32_e32 v164, v164
	v_exp_f32_e32 v165, v165
	v_exp_f32_e32 v166, v166
	v_exp_f32_e32 v167, v167
	v_exp_f32_e32 v168, v168
	v_exp_f32_e32 v169, v169
	v_exp_f32_e32 v170, v170
	v_exp_f32_e32 v171, v171
	v_pk_add_f32 v[164:165], v[164:165], 1.0 op_sel_hi:[1,0]
	v_pk_add_f32 v[166:167], v[166:167], 1.0 op_sel_hi:[1,0]
	v_pk_add_f32 v[168:169], v[168:169], 1.0 op_sel_hi:[1,0]
	v_pk_add_f32 v[170:171], v[170:171], 1.0 op_sel_hi:[1,0]
	v_rcp_f32_e32 v164, v164
	v_rcp_f32_e32 v165, v165
	v_rcp_f32_e32 v166, v166
	v_rcp_f32_e32 v167, v167
	v_rcp_f32_e32 v168, v168
	v_rcp_f32_e32 v169, v169
	v_rcp_f32_e32 v170, v170
	v_rcp_f32_e32 v171, v171
	v_pk_mul_f32 v[164:165], v[64:65], v[164:165]
	v_pk_mul_f32 v[166:167], v[66:67], v[166:167]
	v_pk_mul_f32 v[168:169], v[60:61], v[168:169]
	v_pk_mul_f32 v[170:171], v[62:63], v[170:171]
	v_cvt_pk_bf16_f32 v174, v164, v165
	v_cvt_pk_bf16_f32 v175, v166, v167
	v_cvt_pk_bf16_f32 v176, v168, v169
	v_cvt_pk_bf16_f32 v177, v170, v171
	global_store_dwordx4 v1, v[174:177], s[22:23] offset:-4096
	s_waitcnt vmcnt(15)
	v_lshlrev_b32_e32 v164, 16, v132
	v_and_b32_e32 v165, 0xffff0000, v132
	v_lshlrev_b32_e32 v166, 16, v133
	v_and_b32_e32 v167, 0xffff0000, v133
	v_lshlrev_b32_e32 v168, 16, v134
	v_and_b32_e32 v169, 0xffff0000, v134
	v_lshlrev_b32_e32 v170, 16, v135
	v_and_b32_e32 v171, 0xffff0000, v135
	v_med3_f32 v164, v164, s34, v227
	v_med3_f32 v165, v165, s34, v227
	v_med3_f32 v166, v166, s34, v227
	v_med3_f32 v167, v167, s34, v227
	v_med3_f32 v168, v168, s34, v227
	v_med3_f32 v169, v169, s34, v227
	v_med3_f32 v170, v170, s34, v227
	v_med3_f32 v171, v171, s34, v227
	v_pk_mul_f32 v[164:165], v[164:165], s[44:45]
	v_pk_mul_f32 v[166:167], v[166:167], s[44:45]
	v_pk_mul_f32 v[168:169], v[168:169], s[44:45]
	v_pk_mul_f32 v[170:171], v[170:171], s[44:45]
	v_exp_f32_e32 v164, v164
	v_exp_f32_e32 v165, v165
	v_exp_f32_e32 v166, v166
	v_exp_f32_e32 v167, v167
	v_exp_f32_e32 v168, v168
	v_exp_f32_e32 v169, v169
	v_exp_f32_e32 v170, v170
	v_exp_f32_e32 v171, v171
	v_pk_add_f32 v[164:165], v[164:165], 1.0 op_sel_hi:[1,0]
	v_pk_add_f32 v[166:167], v[166:167], 1.0 op_sel_hi:[1,0]
	v_pk_add_f32 v[168:169], v[168:169], 1.0 op_sel_hi:[1,0]
	v_pk_add_f32 v[170:171], v[170:171], 1.0 op_sel_hi:[1,0]
	v_rcp_f32_e32 v164, v164
	v_rcp_f32_e32 v165, v165
	v_rcp_f32_e32 v166, v166
	v_rcp_f32_e32 v167, v167
	v_rcp_f32_e32 v168, v168
	v_rcp_f32_e32 v169, v169
	v_rcp_f32_e32 v170, v170
	v_rcp_f32_e32 v171, v171
	v_pk_mul_f32 v[164:165], v[32:33], v[164:165]
	v_pk_mul_f32 v[166:167], v[34:35], v[166:167]
	v_pk_mul_f32 v[168:169], v[28:29], v[168:169]
	v_pk_mul_f32 v[170:171], v[30:31], v[170:171]
	v_cvt_pk_bf16_f32 v174, v164, v165
	v_cvt_pk_bf16_f32 v175, v166, v167
	v_cvt_pk_bf16_f32 v176, v168, v169
	v_cvt_pk_bf16_f32 v177, v170, v171
	global_store_dwordx4 v1, v[174:177], s[22:23] offset:-3840
	s_waitcnt vmcnt(14)
	v_lshlrev_b32_e32 v164, 16, v178
	v_and_b32_e32 v165, 0xffff0000, v178
	v_lshlrev_b32_e32 v166, 16, v179
	v_and_b32_e32 v167, 0xffff0000, v179
	v_lshlrev_b32_e32 v168, 16, v180
	v_and_b32_e32 v169, 0xffff0000, v180
	v_lshlrev_b32_e32 v170, 16, v181
	v_and_b32_e32 v171, 0xffff0000, v181
	v_add_u32_e32 v1, s46, v158
	v_lshl_add_u32 v1, v1, 11, v0
	v_med3_f32 v164, v164, s34, v227
	v_med3_f32 v165, v165, s34, v227
	v_med3_f32 v166, v166, s34, v227
	v_med3_f32 v167, v167, s34, v227
	v_med3_f32 v168, v168, s34, v227
	v_med3_f32 v169, v169, s34, v227
	v_med3_f32 v170, v170, s34, v227
	v_med3_f32 v171, v171, s34, v227
	v_pk_mul_f32 v[164:165], v[164:165], s[44:45]
	v_pk_mul_f32 v[166:167], v[166:167], s[44:45]
	v_pk_mul_f32 v[168:169], v[168:169], s[44:45]
	v_pk_mul_f32 v[170:171], v[170:171], s[44:45]
	v_exp_f32_e32 v164, v164
	v_exp_f32_e32 v165, v165
	v_exp_f32_e32 v166, v166
	v_exp_f32_e32 v167, v167
	v_exp_f32_e32 v168, v168
	v_exp_f32_e32 v169, v169
	v_exp_f32_e32 v170, v170
	v_exp_f32_e32 v171, v171
	v_pk_add_f32 v[164:165], v[164:165], 1.0 op_sel_hi:[1,0]
	v_pk_add_f32 v[166:167], v[166:167], 1.0 op_sel_hi:[1,0]
	v_pk_add_f32 v[168:169], v[168:169], 1.0 op_sel_hi:[1,0]
	v_pk_add_f32 v[170:171], v[170:171], 1.0 op_sel_hi:[1,0]
	v_rcp_f32_e32 v164, v164
	v_rcp_f32_e32 v165, v165
	v_rcp_f32_e32 v166, v166
	v_rcp_f32_e32 v167, v167
	v_rcp_f32_e32 v168, v168
	v_rcp_f32_e32 v169, v169
	v_rcp_f32_e32 v170, v170
	v_rcp_f32_e32 v171, v171
	v_pk_mul_f32 v[164:165], v[56:57], v[164:165]
	v_pk_mul_f32 v[166:167], v[58:59], v[166:167]
	v_pk_mul_f32 v[168:169], v[52:53], v[168:169]
	v_pk_mul_f32 v[170:171], v[54:55], v[170:171]
	v_cvt_pk_bf16_f32 v174, v164, v165
	v_cvt_pk_bf16_f32 v175, v166, v167
	v_cvt_pk_bf16_f32 v176, v168, v169
	v_cvt_pk_bf16_f32 v177, v170, v171
	global_store_dwordx4 v1, v[174:177], s[22:23] offset:-4096
	s_waitcnt vmcnt(13)
	v_lshlrev_b32_e32 v164, 16, v182
	v_and_b32_e32 v165, 0xffff0000, v182
	v_lshlrev_b32_e32 v166, 16, v183
	v_and_b32_e32 v167, 0xffff0000, v183
	v_lshlrev_b32_e32 v168, 16, v184
	v_and_b32_e32 v169, 0xffff0000, v184
	v_lshlrev_b32_e32 v170, 16, v185
	v_and_b32_e32 v171, 0xffff0000, v185
	v_med3_f32 v164, v164, s34, v227
	v_med3_f32 v165, v165, s34, v227
	v_med3_f32 v166, v166, s34, v227
	v_med3_f32 v167, v167, s34, v227
	v_med3_f32 v168, v168, s34, v227
	v_med3_f32 v169, v169, s34, v227
	v_med3_f32 v170, v170, s34, v227
	v_med3_f32 v171, v171, s34, v227
	v_pk_mul_f32 v[164:165], v[164:165], s[44:45]
	v_pk_mul_f32 v[166:167], v[166:167], s[44:45]
	v_pk_mul_f32 v[168:169], v[168:169], s[44:45]
	v_pk_mul_f32 v[170:171], v[170:171], s[44:45]
	v_exp_f32_e32 v164, v164
	v_exp_f32_e32 v165, v165
	v_exp_f32_e32 v166, v166
	v_exp_f32_e32 v167, v167
	v_exp_f32_e32 v168, v168
	v_exp_f32_e32 v169, v169
	v_exp_f32_e32 v170, v170
	v_exp_f32_e32 v171, v171
	v_pk_add_f32 v[164:165], v[164:165], 1.0 op_sel_hi:[1,0]
	v_pk_add_f32 v[166:167], v[166:167], 1.0 op_sel_hi:[1,0]
	v_pk_add_f32 v[168:169], v[168:169], 1.0 op_sel_hi:[1,0]
	v_pk_add_f32 v[170:171], v[170:171], 1.0 op_sel_hi:[1,0]
	v_rcp_f32_e32 v164, v164
	v_rcp_f32_e32 v165, v165
	v_rcp_f32_e32 v166, v166
	v_rcp_f32_e32 v167, v167
	v_rcp_f32_e32 v168, v168
	v_rcp_f32_e32 v169, v169
	v_rcp_f32_e32 v170, v170
	v_rcp_f32_e32 v171, v171
	v_pk_mul_f32 v[164:165], v[24:25], v[164:165]
	v_pk_mul_f32 v[166:167], v[26:27], v[166:167]
	v_pk_mul_f32 v[168:169], v[20:21], v[168:169]
	v_pk_mul_f32 v[170:171], v[22:23], v[170:171]
	v_cvt_pk_bf16_f32 v174, v164, v165
	v_cvt_pk_bf16_f32 v175, v166, v167
	v_cvt_pk_bf16_f32 v176, v168, v169
	v_cvt_pk_bf16_f32 v177, v170, v171
	global_store_dwordx4 v1, v[174:177], s[22:23] offset:-3840
	s_mov_b64 s[40:41], 0
	s_branch .LBB0_206

.LBB0_242:
	s_add_u32 s23, s0, 0xfffc0080
	s_addc_u32 s24, s1, -1
	s_add_i32 s25, 0, 0x10000
	v_add_u32_e32 v2, s25, v187
	ds_read_b128 v[132:135], v2
	ds_read_b128 v[136:139], v2 offset:1024
	ds_read_b128 v[140:143], v2 offset:2048
	ds_read_b128 v[144:147], v2 offset:3072
	s_cmp_eq_u32 s22, 12
	s_cselect_b32 s47, s57, s24
	s_cselect_b32 s46, s56, s23
	s_cselect_b32 s45, s59, s21
	s_cselect_b32 s44, s58, s20
	v_lshl_add_u64 v[208:209], s[0:1], 0, v[194:195]
	s_add_i32 m0, s67, 0xc000
	ds_read_b128 v[148:151], v240
	ds_read_b128 v[152:155], v240 offset:1024
	ds_read_b128 v[156:159], v240 offset:2048
	ds_read_b128 v[160:163], v240 offset:3072
	ds_read_b128 v[164:167], v240 offset:4096
	ds_read_b128 v[168:171], v240 offset:5120
	ds_read_b128 v[172:175], v240 offset:6144
	ds_read_b128 v[204:207], v240 offset:7168
	global_load_lds_dwordx4 v[208:209], off
	v_lshl_add_u64 v[208:209], s[0:1], 0, v[202:203]
	s_add_i32 m0, s67, 0xe000
	s_nop 0
	global_load_lds_dwordx4 v[208:209], off
	s_waitcnt lgkmcnt(8)
	s_barrier
	s_waitcnt lgkmcnt(0)
	s_setprio 0
	s_waitcnt lgkmcnt(0)
	v_mfma_f32_16x16x32_bf16 v[128:131], v[132:135], v[148:151], v[128:131]
	v_mfma_f32_16x16x32_bf16 v[124:127], v[140:143], v[148:151], v[124:127]
	v_mfma_f32_16x16x32_bf16 v[120:123], v[132:135], v[156:159], v[120:123]
	v_mfma_f32_16x16x32_bf16 v[116:119], v[140:143], v[156:159], v[116:119]
	v_mfma_f32_16x16x32_bf16 v[112:115], v[132:135], v[164:167], v[112:115]
	v_mfma_f32_16x16x32_bf16 v[108:111], v[140:143], v[164:167], v[108:111]
	v_mfma_f32_16x16x32_bf16 v[104:107], v[132:135], v[172:175], v[104:107]
	v_mfma_f32_16x16x32_bf16 v[100:103], v[140:143], v[172:175], v[100:103]
	v_mfma_f32_16x16x32_bf16 v[128:131], v[136:139], v[152:155], v[128:131]
	v_mfma_f32_16x16x32_bf16 v[124:127], v[144:147], v[152:155], v[124:127]
	v_mfma_f32_16x16x32_bf16 v[120:123], v[136:139], v[160:163], v[120:123]
	v_mfma_f32_16x16x32_bf16 v[116:119], v[144:147], v[160:163], v[116:119]
	v_mfma_f32_16x16x32_bf16 v[112:115], v[136:139], v[168:171], v[112:115]
	v_mfma_f32_16x16x32_bf16 v[108:111], v[144:147], v[168:171], v[108:111]
	v_mfma_f32_16x16x32_bf16 v[104:107], v[136:139], v[204:207], v[104:107]
	v_mfma_f32_16x16x32_bf16 v[100:103], v[144:147], v[204:207], v[100:103]
	s_setprio 1
	s_barrier
	s_add_i32 s23, 0, 0x14000
	s_add_i32 s24, s25, s61
	v_add_u32_e32 v2, s23, v187
	v_lshl_add_u64 v[222:223], s[44:45], 0, v[176:177]
	s_mov_b32 m0, s24
	ds_read_b128 v[208:211], v2
	ds_read_b128 v[212:215], v2 offset:1024
	ds_read_b128 v[242:245], v2 offset:2048
	ds_read_b128 v[246:249], v2 offset:3072
	global_load_lds_dwordx4 v[222:223], off
	v_lshl_add_u64 v[250:251], s[44:45], 0, v[180:181]
	s_add_i32 m0, s24, 0x2000
	s_nop 0
	global_load_lds_dwordx4 v[250:251], off
	s_barrier
	s_waitcnt lgkmcnt(0)
	s_setprio 0
	s_waitcnt lgkmcnt(0)
	v_mfma_f32_16x16x32_bf16 v[64:67], v[208:211], v[148:151], v[64:67]
	v_mfma_f32_16x16x32_bf16 v[60:63], v[242:245], v[148:151], v[60:63]
	v_mfma_f32_16x16x32_bf16 v[56:59], v[208:211], v[156:159], v[56:59]
	v_mfma_f32_16x16x32_bf16 v[52:55], v[242:245], v[156:159], v[52:55]
	v_mfma_f32_16x16x32_bf16 v[48:51], v[208:211], v[164:167], v[48:51]
	v_mfma_f32_16x16x32_bf16 v[44:47], v[242:245], v[164:167], v[44:47]
	v_mfma_f32_16x16x32_bf16 v[40:43], v[208:211], v[172:175], v[40:43]
	v_mfma_f32_16x16x32_bf16 v[36:39], v[242:245], v[172:175], v[36:39]
	v_mfma_f32_16x16x32_bf16 v[64:67], v[212:215], v[152:155], v[64:67]
	v_mfma_f32_16x16x32_bf16 v[60:63], v[246:249], v[152:155], v[60:63]
	v_mfma_f32_16x16x32_bf16 v[56:59], v[212:215], v[160:163], v[56:59]
	v_mfma_f32_16x16x32_bf16 v[52:55], v[246:249], v[160:163], v[52:55]
	v_mfma_f32_16x16x32_bf16 v[48:51], v[212:215], v[168:171], v[48:51]
	v_mfma_f32_16x16x32_bf16 v[44:47], v[246:249], v[168:171], v[44:47]
	v_mfma_f32_16x16x32_bf16 v[40:43], v[212:215], v[204:207], v[40:43]
	v_mfma_f32_16x16x32_bf16 v[36:39], v[246:249], v[204:207], v[36:39]
	s_setprio 1
	s_mov_b32 m0, s67
	v_lshl_add_u64 v[216:217], s[46:47], 0, v[0:1]
	s_barrier
	ds_read_b128 v[148:151], v240 offset:16384
	ds_read_b128 v[152:155], v240 offset:17408
	ds_read_b128 v[156:159], v240 offset:18432
	ds_read_b128 v[160:163], v240 offset:19456
	ds_read_b128 v[164:167], v240 offset:20480
	ds_read_b128 v[168:171], v240 offset:21504
	ds_read_b128 v[172:175], v240 offset:22528
	ds_read_b128 v[204:207], v240 offset:23552
	global_load_lds_dwordx4 v[216:217], off
	v_lshl_add_u64 v[236:237], s[46:47], 0, v[178:179]
	s_mov_b32 m0, s74
	s_nop 0
	global_load_lds_dwordx4 v[236:237], off
	s_barrier
	s_waitcnt lgkmcnt(0)
	s_setprio 0
	s_waitcnt lgkmcnt(0)
	v_mfma_f32_16x16x32_bf16 v[96:99], v[132:135], v[148:151], v[96:99]
	v_mfma_f32_16x16x32_bf16 v[92:95], v[140:143], v[148:151], v[92:95]
	v_mfma_f32_16x16x32_bf16 v[88:91], v[132:135], v[156:159], v[88:91]
	v_mfma_f32_16x16x32_bf16 v[84:87], v[140:143], v[156:159], v[84:87]
	v_mfma_f32_16x16x32_bf16 v[80:83], v[132:135], v[164:167], v[80:83]
	v_mfma_f32_16x16x32_bf16 v[76:79], v[140:143], v[164:167], v[76:79]
	v_mfma_f32_16x16x32_bf16 v[72:75], v[132:135], v[172:175], v[72:75]
	v_mfma_f32_16x16x32_bf16 v[68:71], v[140:143], v[172:175], v[68:71]
	v_mfma_f32_16x16x32_bf16 v[96:99], v[136:139], v[152:155], v[96:99]
	v_mfma_f32_16x16x32_bf16 v[92:95], v[144:147], v[152:155], v[92:95]
	v_mfma_f32_16x16x32_bf16 v[88:91], v[136:139], v[160:163], v[88:91]
	v_mfma_f32_16x16x32_bf16 v[84:87], v[144:147], v[160:163], v[84:87]
	v_mfma_f32_16x16x32_bf16 v[80:83], v[136:139], v[168:171], v[80:83]
	v_mfma_f32_16x16x32_bf16 v[76:79], v[144:147], v[168:171], v[76:79]
	v_mfma_f32_16x16x32_bf16 v[72:75], v[136:139], v[204:207], v[72:75]
	v_mfma_f32_16x16x32_bf16 v[68:71], v[144:147], v[204:207], v[68:71]
	s_setprio 1
	s_barrier
	s_add_u32 s24, s44, 0x40000
	s_addc_u32 s25, s45, 0
	s_add_i32 s23, s23, s61
	v_lshl_add_u64 v[132:133], s[24:25], 0, v[176:177]
	s_mov_b32 m0, s23
	s_nop 0
	global_load_lds_dwordx4 v[132:133], off
	v_lshl_add_u64 v[132:133], s[24:25], 0, v[180:181]
	s_add_i32 m0, s23, 0x2000
	s_nop 0
	global_load_lds_dwordx4 v[132:133], off
	s_waitcnt vmcnt(6)
	s_barrier
	s_setprio 0
	v_mfma_f32_16x16x32_bf16 v[32:35], v[208:211], v[148:151], v[32:35]
	v_mfma_f32_16x16x32_bf16 v[28:31], v[242:245], v[148:151], v[28:31]
	v_mfma_f32_16x16x32_bf16 v[24:27], v[208:211], v[156:159], v[24:27]
	v_mfma_f32_16x16x32_bf16 v[20:23], v[242:245], v[156:159], v[20:23]
	v_mfma_f32_16x16x32_bf16 v[16:19], v[208:211], v[164:167], v[16:19]
	v_mfma_f32_16x16x32_bf16 v[12:15], v[242:245], v[164:167], v[12:15]
	v_mfma_f32_16x16x32_bf16 v[8:11], v[208:211], v[172:175], v[8:11]
	v_mfma_f32_16x16x32_bf16 v[4:7], v[242:245], v[172:175], v[4:7]
	v_mfma_f32_16x16x32_bf16 v[32:35], v[212:215], v[152:155], v[32:35]
	v_mfma_f32_16x16x32_bf16 v[28:31], v[246:249], v[152:155], v[28:31]
	v_mfma_f32_16x16x32_bf16 v[24:27], v[212:215], v[160:163], v[24:27]
	v_mfma_f32_16x16x32_bf16 v[20:23], v[246:249], v[160:163], v[20:23]
	v_mfma_f32_16x16x32_bf16 v[16:19], v[212:215], v[168:171], v[16:19]
	v_mfma_f32_16x16x32_bf16 v[12:15], v[246:249], v[168:171], v[12:15]
	v_mfma_f32_16x16x32_bf16 v[8:11], v[212:215], v[204:207], v[8:11]
	v_mfma_f32_16x16x32_bf16 v[4:7], v[246:249], v[204:207], v[4:7]
	s_setprio 1
	s_add_i32 s23, 0, 0x18000
	v_add_u32_e32 v2, s23, v187
	s_barrier
	ds_read_b128 v[132:135], v2
	ds_read_b128 v[136:139], v2 offset:1024
	ds_read_b128 v[140:143], v2 offset:2048
	ds_read_b128 v[144:147], v2 offset:3072
	s_add_u32 s24, s46, 0x40000
	s_addc_u32 s25, s47, 0
	s_mov_b32 m0, s75
	v_lshl_add_u64 v[208:209], s[24:25], 0, v[0:1]
	ds_read_b128 v[148:151], v240 offset:32768
	ds_read_b128 v[152:155], v240 offset:33792
	ds_read_b128 v[156:159], v240 offset:34816
	ds_read_b128 v[160:163], v240 offset:35840
	ds_read_b128 v[164:167], v240 offset:36864
	ds_read_b128 v[168:171], v240 offset:37888
	ds_read_b128 v[172:175], v240 offset:38912
	ds_read_b128 v[204:207], v240 offset:39936
	global_load_lds_dwordx4 v[208:209], off
	v_lshl_add_u64 v[208:209], s[24:25], 0, v[178:179]
	s_mov_b32 m0, s82
	s_nop 0
	global_load_lds_dwordx4 v[208:209], off
	s_waitcnt lgkmcnt(8)
	s_barrier
	s_waitcnt lgkmcnt(0)
	s_setprio 0
	s_waitcnt lgkmcnt(0)
	v_mfma_f32_16x16x32_bf16 v[128:131], v[132:135], v[148:151], v[128:131]
	v_mfma_f32_16x16x32_bf16 v[124:127], v[140:143], v[148:151], v[124:127]
	v_mfma_f32_16x16x32_bf16 v[120:123], v[132:135], v[156:159], v[120:123]
	v_mfma_f32_16x16x32_bf16 v[116:119], v[140:143], v[156:159], v[116:119]
	v_mfma_f32_16x16x32_bf16 v[112:115], v[132:135], v[164:167], v[112:115]
	v_mfma_f32_16x16x32_bf16 v[108:111], v[140:143], v[164:167], v[108:111]
	v_mfma_f32_16x16x32_bf16 v[104:107], v[132:135], v[172:175], v[104:107]
	v_mfma_f32_16x16x32_bf16 v[100:103], v[140:143], v[172:175], v[100:103]
	v_mfma_f32_16x16x32_bf16 v[128:131], v[136:139], v[152:155], v[128:131]
	v_mfma_f32_16x16x32_bf16 v[124:127], v[144:147], v[152:155], v[124:127]
	v_mfma_f32_16x16x32_bf16 v[120:123], v[136:139], v[160:163], v[120:123]
	v_mfma_f32_16x16x32_bf16 v[116:119], v[144:147], v[160:163], v[116:119]
	v_mfma_f32_16x16x32_bf16 v[112:115], v[136:139], v[168:171], v[112:115]
	v_mfma_f32_16x16x32_bf16 v[108:111], v[144:147], v[168:171], v[108:111]
	v_mfma_f32_16x16x32_bf16 v[104:107], v[136:139], v[204:207], v[104:107]
	v_mfma_f32_16x16x32_bf16 v[100:103], v[144:147], v[204:207], v[100:103]
	s_setprio 1
	s_barrier
	s_add_i32 s26, 0, 0x1c000
	s_add_i32 s23, s23, s61
	v_add_u32_e32 v2, s26, v187
	v_lshl_add_u64 v[222:223], v[222:223], 0, s[76:77]
	s_mov_b32 m0, s23
	ds_read_b128 v[208:211], v2
	ds_read_b128 v[212:215], v2 offset:1024
	ds_read_b128 v[242:245], v2 offset:2048
	ds_read_b128 v[246:249], v2 offset:3072
	global_load_lds_dwordx4 v[222:223], off
	v_lshl_add_u64 v[222:223], v[250:251], 0, s[76:77]
	s_add_i32 m0, s23, 0x2000
	s_nop 0
	global_load_lds_dwordx4 v[222:223], off
	s_barrier
	s_waitcnt lgkmcnt(0)
	s_setprio 0
	s_waitcnt lgkmcnt(0)
	v_mfma_f32_16x16x32_bf16 v[64:67], v[208:211], v[148:151], v[64:67]
	v_mfma_f32_16x16x32_bf16 v[60:63], v[242:245], v[148:151], v[60:63]
	v_mfma_f32_16x16x32_bf16 v[56:59], v[208:211], v[156:159], v[56:59]
	v_mfma_f32_16x16x32_bf16 v[52:55], v[242:245], v[156:159], v[52:55]
	v_mfma_f32_16x16x32_bf16 v[48:51], v[208:211], v[164:167], v[48:51]
	v_mfma_f32_16x16x32_bf16 v[44:47], v[242:245], v[164:167], v[44:47]
	v_mfma_f32_16x16x32_bf16 v[40:43], v[208:211], v[172:175], v[40:43]
	v_mfma_f32_16x16x32_bf16 v[36:39], v[242:245], v[172:175], v[36:39]
	v_mfma_f32_16x16x32_bf16 v[64:67], v[212:215], v[152:155], v[64:67]
	v_mfma_f32_16x16x32_bf16 v[60:63], v[246:249], v[152:155], v[60:63]
	v_mfma_f32_16x16x32_bf16 v[56:59], v[212:215], v[160:163], v[56:59]
	v_mfma_f32_16x16x32_bf16 v[52:55], v[246:249], v[160:163], v[52:55]
	v_mfma_f32_16x16x32_bf16 v[48:51], v[212:215], v[168:171], v[48:51]
	v_mfma_f32_16x16x32_bf16 v[44:47], v[246:249], v[168:171], v[44:47]
	v_mfma_f32_16x16x32_bf16 v[40:43], v[212:215], v[204:207], v[40:43]
	v_mfma_f32_16x16x32_bf16 v[36:39], v[246:249], v[204:207], v[36:39]
	s_setprio 1
	s_mov_b32 m0, s48
	v_lshl_add_u64 v[216:217], v[216:217], 0, s[76:77]
	s_barrier
	ds_read_b128 v[148:151], v240 offset:49152
	ds_read_b128 v[152:155], v240 offset:50176
	ds_read_b128 v[156:159], v240 offset:51200
	ds_read_b128 v[160:163], v240 offset:52224
	ds_read_b128 v[164:167], v240 offset:53248
	ds_read_b128 v[168:171], v240 offset:54272
	ds_read_b128 v[172:175], v240 offset:55296
	ds_read_b128 v[204:207], v240 offset:56320
	global_load_lds_dwordx4 v[216:217], off
	v_lshl_add_u64 v[216:217], v[236:237], 0, s[76:77]
	s_mov_b32 m0, s50
	s_nop 0
	global_load_lds_dwordx4 v[216:217], off
	s_barrier
	s_waitcnt lgkmcnt(0)
	s_setprio 0
	s_waitcnt lgkmcnt(0)
	v_mfma_f32_16x16x32_bf16 v[96:99], v[132:135], v[148:151], v[96:99]
	v_mfma_f32_16x16x32_bf16 v[92:95], v[140:143], v[148:151], v[92:95]
	v_mfma_f32_16x16x32_bf16 v[88:91], v[132:135], v[156:159], v[88:91]
	v_mfma_f32_16x16x32_bf16 v[84:87], v[140:143], v[156:159], v[84:87]
	v_mfma_f32_16x16x32_bf16 v[80:83], v[132:135], v[164:167], v[80:83]
	v_mfma_f32_16x16x32_bf16 v[76:79], v[140:143], v[164:167], v[76:79]
	v_mfma_f32_16x16x32_bf16 v[72:75], v[132:135], v[172:175], v[72:75]
	v_mfma_f32_16x16x32_bf16 v[68:71], v[140:143], v[172:175], v[68:71]
	v_mfma_f32_16x16x32_bf16 v[96:99], v[136:139], v[152:155], v[96:99]
	v_mfma_f32_16x16x32_bf16 v[92:95], v[144:147], v[152:155], v[92:95]
	v_mfma_f32_16x16x32_bf16 v[88:91], v[136:139], v[160:163], v[88:91]
	v_mfma_f32_16x16x32_bf16 v[84:87], v[144:147], v[160:163], v[84:87]
	v_mfma_f32_16x16x32_bf16 v[80:83], v[136:139], v[168:171], v[80:83]
	v_mfma_f32_16x16x32_bf16 v[76:79], v[144:147], v[168:171], v[76:79]
	v_mfma_f32_16x16x32_bf16 v[72:75], v[136:139], v[204:207], v[72:75]
	v_mfma_f32_16x16x32_bf16 v[68:71], v[144:147], v[204:207], v[68:71]
	s_setprio 1
	s_barrier
	s_add_u32 s24, s44, 0x40080
	s_addc_u32 s25, s45, 0
	s_add_i32 s23, s26, s61
	v_lshl_add_u64 v[132:133], s[24:25], 0, v[176:177]
	s_mov_b32 m0, s23
	s_nop 0
	global_load_lds_dwordx4 v[132:133], off
	v_lshl_add_u64 v[132:133], s[24:25], 0, v[180:181]
	s_add_i32 m0, s23, 0x2000
	s_nop 0
	global_load_lds_dwordx4 v[132:133], off
	s_waitcnt vmcnt(6)
	s_barrier
	s_setprio 0
	v_mfma_f32_16x16x32_bf16 v[32:35], v[208:211], v[148:151], v[32:35]
	v_mfma_f32_16x16x32_bf16 v[28:31], v[242:245], v[148:151], v[28:31]
	v_mfma_f32_16x16x32_bf16 v[24:27], v[208:211], v[156:159], v[24:27]
	v_mfma_f32_16x16x32_bf16 v[20:23], v[242:245], v[156:159], v[20:23]
	v_mfma_f32_16x16x32_bf16 v[16:19], v[208:211], v[164:167], v[16:19]
	v_mfma_f32_16x16x32_bf16 v[12:15], v[242:245], v[164:167], v[12:15]
	v_mfma_f32_16x16x32_bf16 v[8:11], v[208:211], v[172:175], v[8:11]
	v_mfma_f32_16x16x32_bf16 v[4:7], v[242:245], v[172:175], v[4:7]
	v_mfma_f32_16x16x32_bf16 v[32:35], v[212:215], v[152:155], v[32:35]
	v_mfma_f32_16x16x32_bf16 v[28:31], v[246:249], v[152:155], v[28:31]
	v_mfma_f32_16x16x32_bf16 v[24:27], v[212:215], v[160:163], v[24:27]
	v_mfma_f32_16x16x32_bf16 v[20:23], v[246:249], v[160:163], v[20:23]
	v_mfma_f32_16x16x32_bf16 v[16:19], v[212:215], v[168:171], v[16:19]
	v_mfma_f32_16x16x32_bf16 v[12:15], v[246:249], v[168:171], v[12:15]
	v_mfma_f32_16x16x32_bf16 v[8:11], v[212:215], v[204:207], v[8:11]
	v_mfma_f32_16x16x32_bf16 v[4:7], v[246:249], v[204:207], v[4:7]
	s_setprio 1
	s_add_i32 s22, s22, 2
	s_add_u32 s0, s0, 0x100
	s_addc_u32 s1, s1, 0
	s_add_u32 s20, s20, 0x100
	s_addc_u32 s21, s21, 0
	s_cmp_gt_u32 s22, 13
	s_barrier
	s_cbranch_scc0 .LBB0_242
	s_add_i32 s0, s66, -8
	s_cmp_lt_u32 s0, 12
	s_mov_b64 s[0:1], -1
	s_cbranch_scc1 .LBB0_266
	s_cmp_gt_i32 s66, 33
	s_cselect_b64 s[64:65], -1, 0
	s_lshl_b32 s0, s66, 8
	s_lshl_b32 s53, s60, 8
	s_add_i32 s1, s0, 0xffffee00
	s_cmp_lt_i32 s66, 26
	v_cndmask_b32_e64 v2, 0, 1, s[80:81]
	s_cselect_b32 s62, s0, s1
	s_mov_b64 s[0:1], -1
	s_and_b64 vcc, exec, s[64:65]
	v_cmp_ne_u32_e64 s[44:45], 1, v2
	s_cbranch_vccz .LBB0_248
	s_and_b64 vcc, exec, s[44:45]
	s_cbranch_vccnz .LBB0_247
	v_add_u32_e32 v132, s53, v185
	v_ashrrev_i32_e32 v133, 31, v132
	v_lshlrev_b64 v[140:141], 7, v[132:133]
	global_load_dwordx4 v[132:135], v[188:189], off offset:16
	global_load_dwordx4 v[136:139], v[188:189], off
	s_mov_b32 s3, 0xbfb8aa3b
	s_mov_b32 s2, 0x800000
	s_mov_b32 s5, 0x3f317217
	s_mov_b32 s6, 0x7f800000
	s_waitcnt vmcnt(0)
	v_add_f32_e32 v147, v126, v134
	v_add_f32_e32 v2, v128, v136
	v_max_f32_e32 v142, 0, v2
	v_mul_f32_e64 v2, |v2|, s3
	v_exp_f32_e32 v2, v2
	v_add_f32_e32 v136, v124, v132
	v_add_f32_e32 v149, v127, v135
	v_add_f32_e32 v2, 1.0, v2
	v_cmp_gt_f32_e32 vcc, s2, v2
	s_nop 1
	v_cndmask_b32_e64 v132, 0, 32, vcc
	v_ldexp_f32 v2, v2, v132
	v_log_f32_e32 v2, v2
	s_nop 0
	v_mul_f32_e32 v132, 0x3f317217, v2
	v_fma_f32 v132, v2, s5, -v132
	v_fmac_f32_e32 v132, 0x3377d1cf, v2
	v_fmac_f32_e32 v132, 0x3f317217, v2
	v_cmp_lt_f32_e64 s[0:1], |v2|, s6
	s_nop 1
	v_cndmask_b32_e64 v2, v2, v132, s[0:1]
	v_cndmask_b32_e32 v132, 0, v228, vcc
	v_sub_f32_e32 v144, v2, v132
	v_mul_f32_e64 v2, |v136|, s3
	v_exp_f32_e32 v2, v2
	v_max_f32_e32 v132, 0, v136
	v_add_f32_e32 v2, 1.0, v2
	v_cmp_gt_f32_e32 vcc, s2, v2
	s_nop 1
	v_cndmask_b32_e64 v136, 0, 32, vcc
	v_ldexp_f32 v2, v2, v136
	v_log_f32_e32 v2, v2
	s_nop 0
	v_mul_f32_e32 v136, 0x3f317217, v2
	v_fma_f32 v136, v2, s5, -v136
	v_fmac_f32_e32 v136, 0x3377d1cf, v2
	v_fmac_f32_e32 v136, 0x3f317217, v2
	v_cmp_lt_f32_e64 s[0:1], |v2|, s6
	s_nop 1
	v_cndmask_b32_e64 v2, v2, v136, s[0:1]
	v_cndmask_b32_e32 v136, 0, v228, vcc
	v_sub_f32_e32 v136, v2, v136
	v_add_f32_e32 v2, v129, v137
	v_max_f32_e32 v143, 0, v2
	v_mul_f32_e64 v2, |v2|, s3
	v_exp_f32_e32 v2, v2
	v_add_f32_e32 v137, v125, v133
	v_add_f32_e32 v2, 1.0, v2
	v_cmp_gt_f32_e32 vcc, s2, v2
	s_nop 1
	v_cndmask_b32_e64 v133, 0, 32, vcc
	v_ldexp_f32 v2, v2, v133
	v_log_f32_e32 v2, v2
	s_nop 0
	v_mul_f32_e32 v133, 0x3f317217, v2
	v_fma_f32 v133, v2, s5, -v133
	v_fmac_f32_e32 v133, 0x3377d1cf, v2
	v_fmac_f32_e32 v133, 0x3f317217, v2
	v_cmp_lt_f32_e64 s[0:1], |v2|, s6
	s_nop 1
	v_cndmask_b32_e64 v2, v2, v133, s[0:1]
	v_cndmask_b32_e32 v133, 0, v228, vcc
	v_sub_f32_e32 v145, v2, v133
	v_mul_f32_e64 v2, |v137|, s3
	v_exp_f32_e32 v2, v2
	v_max_f32_e32 v133, 0, v137
	v_pk_add_f32 v[142:143], v[142:143], v[144:145]
	v_add_f32_e32 v2, 1.0, v2
	v_cmp_gt_f32_e32 vcc, s2, v2
	s_nop 1
	v_cndmask_b32_e64 v137, 0, 32, vcc
	v_ldexp_f32 v2, v2, v137
	v_log_f32_e32 v2, v2
	s_nop 0
	v_mul_f32_e32 v137, 0x3f317217, v2
	v_fma_f32 v137, v2, s5, -v137
	v_fmac_f32_e32 v137, 0x3377d1cf, v2
	v_fmac_f32_e32 v137, 0x3f317217, v2
	v_cmp_lt_f32_e64 s[0:1], |v2|, s6
	s_nop 1
	v_cndmask_b32_e64 v2, v2, v137, s[0:1]
	v_cndmask_b32_e32 v137, 0, v228, vcc
	v_sub_f32_e32 v137, v2, v137
	v_add_f32_e32 v2, v130, v138
	v_max_f32_e32 v138, 0, v2
	v_mul_f32_e64 v2, |v2|, s3
	v_exp_f32_e32 v2, v2
	v_pk_add_f32 v[132:133], v[132:133], v[136:137]
	v_lshl_add_u64 v[136:137], v[190:191], 0, v[140:141]
	v_add_f32_e32 v2, 1.0, v2
	v_cmp_gt_f32_e32 vcc, s2, v2
	s_nop 1
	v_cndmask_b32_e64 v134, 0, 32, vcc
	v_ldexp_f32 v2, v2, v134
	v_log_f32_e32 v2, v2
	s_nop 0
	v_mul_f32_e32 v134, 0x3f317217, v2
	v_fma_f32 v134, v2, s5, -v134
	v_fmac_f32_e32 v134, 0x3377d1cf, v2
	v_fmac_f32_e32 v134, 0x3f317217, v2
	v_cmp_lt_f32_e64 s[0:1], |v2|, s6
	s_nop 1
	v_cndmask_b32_e64 v2, v2, v134, s[0:1]
	v_cndmask_b32_e32 v134, 0, v228, vcc
	v_sub_f32_e32 v146, v2, v134
	v_mul_f32_e64 v2, |v147|, s3
	v_exp_f32_e32 v2, v2
	v_max_f32_e32 v134, 0, v147
	v_add_f32_e32 v2, 1.0, v2
	v_cmp_gt_f32_e32 vcc, s2, v2
	s_nop 1
	v_cndmask_b32_e64 v147, 0, 32, vcc
	v_ldexp_f32 v2, v2, v147
	v_log_f32_e32 v2, v2
	s_nop 0
	v_mul_f32_e32 v147, 0x3f317217, v2
	v_fma_f32 v147, v2, s5, -v147
	v_fmac_f32_e32 v147, 0x3377d1cf, v2
	v_fmac_f32_e32 v147, 0x3f317217, v2
	v_cmp_lt_f32_e64 s[0:1], |v2|, s6
	s_nop 1
	v_cndmask_b32_e64 v2, v2, v147, s[0:1]
	v_cndmask_b32_e32 v147, 0, v228, vcc
	v_sub_f32_e32 v148, v2, v147
	v_add_f32_e32 v2, v131, v139
	v_max_f32_e32 v139, 0, v2
	v_mul_f32_e64 v2, |v2|, s3
	v_exp_f32_e32 v2, v2
	s_nop 0
	v_add_f32_e32 v2, 1.0, v2
	v_cmp_gt_f32_e32 vcc, s2, v2
	s_nop 1
	v_cndmask_b32_e64 v135, 0, 32, vcc
	v_ldexp_f32 v2, v2, v135
	v_log_f32_e32 v2, v2
	s_nop 0
	v_mul_f32_e32 v135, 0x3f317217, v2
	v_fma_f32 v135, v2, s5, -v135
	v_fmac_f32_e32 v135, 0x3377d1cf, v2
	v_fmac_f32_e32 v135, 0x3f317217, v2
	v_cmp_lt_f32_e64 s[0:1], |v2|, s6
	s_nop 1
	v_cndmask_b32_e64 v2, v2, v135, s[0:1]
	v_cndmask_b32_e32 v135, 0, v228, vcc
	v_sub_f32_e32 v147, v2, v135
	v_mul_f32_e64 v2, |v149|, s3
	v_exp_f32_e32 v2, v2
	v_pk_add_f32 v[144:145], v[138:139], v[146:147]
	v_max_f32_e32 v135, 0, v149
	v_add_f32_e32 v2, 1.0, v2
	v_cmp_gt_f32_e32 vcc, s2, v2
	s_nop 1
	v_cndmask_b32_e64 v138, 0, 32, vcc
	v_ldexp_f32 v2, v2, v138
	v_log_f32_e32 v2, v2
	s_nop 0
	v_mul_f32_e32 v138, 0x3f317217, v2
	v_fma_f32 v138, v2, s5, -v138
	v_fmac_f32_e32 v138, 0x3377d1cf, v2
	v_fmac_f32_e32 v138, 0x3f317217, v2
	v_cmp_lt_f32_e64 s[0:1], |v2|, s6
	s_nop 1
	v_cndmask_b32_e64 v2, v2, v138, s[0:1]
	v_cndmask_b32_e32 v138, 0, v228, vcc
	v_sub_f32_e32 v149, v2, v138
	v_pk_add_f32 v[134:135], v[134:135], v[148:149]
	global_store_dwordx4 v[136:137], v[142:145], off
	global_store_dwordx4 v[136:137], v[132:135], off offset:16

.LBB0_427:
	s_add_u32 s23, s0, 0xfffc0080
	s_addc_u32 s24, s1, -1
	s_add_i32 s25, 0, 0x10000
	v_add_u32_e32 v2, s25, v187
	ds_read_b128 v[132:135], v2
	ds_read_b128 v[136:139], v2 offset:1024
	ds_read_b128 v[140:143], v2 offset:2048
	ds_read_b128 v[144:147], v2 offset:3072
	s_cmp_eq_u32 s22, 12
	s_cselect_b32 s47, s57, s24
	s_cselect_b32 s46, s56, s23
	s_cselect_b32 s45, s59, s21
	s_cselect_b32 s44, s58, s20
	v_lshl_add_u64 v[208:209], s[0:1], 0, v[194:195]
	s_add_i32 m0, s74, 0xc000
	ds_read_b128 v[148:151], v240
	ds_read_b128 v[152:155], v240 offset:1024
	ds_read_b128 v[156:159], v240 offset:2048
	ds_read_b128 v[160:163], v240 offset:3072
	ds_read_b128 v[164:167], v240 offset:4096
	ds_read_b128 v[168:171], v240 offset:5120
	ds_read_b128 v[172:175], v240 offset:6144
	ds_read_b128 v[204:207], v240 offset:7168
	global_load_lds_dwordx4 v[208:209], off
	v_lshl_add_u64 v[208:209], s[0:1], 0, v[202:203]
	s_add_i32 m0, s74, 0xe000
	s_nop 0
	global_load_lds_dwordx4 v[208:209], off
	s_waitcnt lgkmcnt(8)
	s_barrier
	s_waitcnt lgkmcnt(0)
	s_setprio 0
	s_waitcnt lgkmcnt(0)
	v_mfma_f32_16x16x32_bf16 v[128:131], v[132:135], v[148:151], v[128:131]
	v_mfma_f32_16x16x32_bf16 v[124:127], v[140:143], v[148:151], v[124:127]
	v_mfma_f32_16x16x32_bf16 v[120:123], v[132:135], v[156:159], v[120:123]
	v_mfma_f32_16x16x32_bf16 v[116:119], v[140:143], v[156:159], v[116:119]
	v_mfma_f32_16x16x32_bf16 v[112:115], v[132:135], v[164:167], v[112:115]
	v_mfma_f32_16x16x32_bf16 v[108:111], v[140:143], v[164:167], v[108:111]
	v_mfma_f32_16x16x32_bf16 v[104:107], v[132:135], v[172:175], v[104:107]
	v_mfma_f32_16x16x32_bf16 v[100:103], v[140:143], v[172:175], v[100:103]
	v_mfma_f32_16x16x32_bf16 v[128:131], v[136:139], v[152:155], v[128:131]
	v_mfma_f32_16x16x32_bf16 v[124:127], v[144:147], v[152:155], v[124:127]
	v_mfma_f32_16x16x32_bf16 v[120:123], v[136:139], v[160:163], v[120:123]
	v_mfma_f32_16x16x32_bf16 v[116:119], v[144:147], v[160:163], v[116:119]
	v_mfma_f32_16x16x32_bf16 v[112:115], v[136:139], v[168:171], v[112:115]
	v_mfma_f32_16x16x32_bf16 v[108:111], v[144:147], v[168:171], v[108:111]
	v_mfma_f32_16x16x32_bf16 v[104:107], v[136:139], v[204:207], v[104:107]
	v_mfma_f32_16x16x32_bf16 v[100:103], v[144:147], v[204:207], v[100:103]
	s_setprio 1
	s_barrier
	s_add_i32 s23, 0, 0x14000
	s_add_i32 s24, s25, s67
	v_add_u32_e32 v2, s23, v187
	v_lshl_add_u64 v[250:251], s[44:45], 0, v[176:177]
	s_mov_b32 m0, s24
	ds_read_b128 v[208:211], v2
	ds_read_b128 v[212:215], v2 offset:1024
	ds_read_b128 v[242:245], v2 offset:2048
	ds_read_b128 v[246:249], v2 offset:3072
	global_load_lds_dwordx4 v[250:251], off
	v_lshl_add_u64 v[222:223], s[44:45], 0, v[180:181]
	s_add_i32 m0, s24, 0x2000
	s_nop 0
	global_load_lds_dwordx4 v[222:223], off
	s_barrier
	s_waitcnt lgkmcnt(0)
	s_setprio 0
	s_waitcnt lgkmcnt(0)
	v_mfma_f32_16x16x32_bf16 v[64:67], v[208:211], v[148:151], v[64:67]
	v_mfma_f32_16x16x32_bf16 v[60:63], v[242:245], v[148:151], v[60:63]
	v_mfma_f32_16x16x32_bf16 v[56:59], v[208:211], v[156:159], v[56:59]
	v_mfma_f32_16x16x32_bf16 v[52:55], v[242:245], v[156:159], v[52:55]
	v_mfma_f32_16x16x32_bf16 v[48:51], v[208:211], v[164:167], v[48:51]
	v_mfma_f32_16x16x32_bf16 v[44:47], v[242:245], v[164:167], v[44:47]
	v_mfma_f32_16x16x32_bf16 v[40:43], v[208:211], v[172:175], v[40:43]
	v_mfma_f32_16x16x32_bf16 v[36:39], v[242:245], v[172:175], v[36:39]
	v_mfma_f32_16x16x32_bf16 v[64:67], v[212:215], v[152:155], v[64:67]
	v_mfma_f32_16x16x32_bf16 v[60:63], v[246:249], v[152:155], v[60:63]
	v_mfma_f32_16x16x32_bf16 v[56:59], v[212:215], v[160:163], v[56:59]
	v_mfma_f32_16x16x32_bf16 v[52:55], v[246:249], v[160:163], v[52:55]
	v_mfma_f32_16x16x32_bf16 v[48:51], v[212:215], v[168:171], v[48:51]
	v_mfma_f32_16x16x32_bf16 v[44:47], v[246:249], v[168:171], v[44:47]
	v_mfma_f32_16x16x32_bf16 v[40:43], v[212:215], v[204:207], v[40:43]
	v_mfma_f32_16x16x32_bf16 v[36:39], v[246:249], v[204:207], v[36:39]
	s_setprio 1
	s_mov_b32 m0, s74
	v_lshl_add_u64 v[216:217], s[46:47], 0, v[0:1]
	s_barrier
	ds_read_b128 v[148:151], v240 offset:16384
	ds_read_b128 v[152:155], v240 offset:17408
	ds_read_b128 v[156:159], v240 offset:18432
	ds_read_b128 v[160:163], v240 offset:19456
	ds_read_b128 v[164:167], v240 offset:20480
	ds_read_b128 v[168:171], v240 offset:21504
	ds_read_b128 v[172:175], v240 offset:22528
	ds_read_b128 v[204:207], v240 offset:23552
	global_load_lds_dwordx4 v[216:217], off
	v_lshl_add_u64 v[236:237], s[46:47], 0, v[178:179]
	s_mov_b32 m0, s75
	s_nop 0
	global_load_lds_dwordx4 v[236:237], off
	s_barrier
	s_waitcnt lgkmcnt(0)
	s_setprio 0
	s_waitcnt lgkmcnt(0)
	v_mfma_f32_16x16x32_bf16 v[96:99], v[132:135], v[148:151], v[96:99]
	v_mfma_f32_16x16x32_bf16 v[92:95], v[140:143], v[148:151], v[92:95]
	v_mfma_f32_16x16x32_bf16 v[88:91], v[132:135], v[156:159], v[88:91]
	v_mfma_f32_16x16x32_bf16 v[84:87], v[140:143], v[156:159], v[84:87]
	v_mfma_f32_16x16x32_bf16 v[80:83], v[132:135], v[164:167], v[80:83]
	v_mfma_f32_16x16x32_bf16 v[76:79], v[140:143], v[164:167], v[76:79]
	v_mfma_f32_16x16x32_bf16 v[72:75], v[132:135], v[172:175], v[72:75]
	v_mfma_f32_16x16x32_bf16 v[68:71], v[140:143], v[172:175], v[68:71]
	v_mfma_f32_16x16x32_bf16 v[96:99], v[136:139], v[152:155], v[96:99]
	v_mfma_f32_16x16x32_bf16 v[92:95], v[144:147], v[152:155], v[92:95]
	v_mfma_f32_16x16x32_bf16 v[88:91], v[136:139], v[160:163], v[88:91]
	v_mfma_f32_16x16x32_bf16 v[84:87], v[144:147], v[160:163], v[84:87]
	v_mfma_f32_16x16x32_bf16 v[80:83], v[136:139], v[168:171], v[80:83]
	v_mfma_f32_16x16x32_bf16 v[76:79], v[144:147], v[168:171], v[76:79]
	v_mfma_f32_16x16x32_bf16 v[72:75], v[136:139], v[204:207], v[72:75]
	v_mfma_f32_16x16x32_bf16 v[68:71], v[144:147], v[204:207], v[68:71]
	s_setprio 1
	s_barrier
	s_add_u32 s24, s44, 0x40000
	s_addc_u32 s25, s45, 0
	s_add_i32 s23, s23, s67
	v_lshl_add_u64 v[132:133], s[24:25], 0, v[176:177]
	s_mov_b32 m0, s23
	s_nop 0
	global_load_lds_dwordx4 v[132:133], off
	v_lshl_add_u64 v[132:133], s[24:25], 0, v[180:181]
	s_add_i32 m0, s23, 0x2000
	s_nop 0
	global_load_lds_dwordx4 v[132:133], off
	s_waitcnt vmcnt(6)
	s_barrier
	s_setprio 0
	v_mfma_f32_16x16x32_bf16 v[32:35], v[208:211], v[148:151], v[32:35]
	v_mfma_f32_16x16x32_bf16 v[28:31], v[242:245], v[148:151], v[28:31]
	v_mfma_f32_16x16x32_bf16 v[24:27], v[208:211], v[156:159], v[24:27]
	v_mfma_f32_16x16x32_bf16 v[20:23], v[242:245], v[156:159], v[20:23]
	v_mfma_f32_16x16x32_bf16 v[16:19], v[208:211], v[164:167], v[16:19]
	v_mfma_f32_16x16x32_bf16 v[12:15], v[242:245], v[164:167], v[12:15]
	v_mfma_f32_16x16x32_bf16 v[8:11], v[208:211], v[172:175], v[8:11]
	v_mfma_f32_16x16x32_bf16 v[4:7], v[242:245], v[172:175], v[4:7]
	v_mfma_f32_16x16x32_bf16 v[32:35], v[212:215], v[152:155], v[32:35]
	v_mfma_f32_16x16x32_bf16 v[28:31], v[246:249], v[152:155], v[28:31]
	v_mfma_f32_16x16x32_bf16 v[24:27], v[212:215], v[160:163], v[24:27]
	v_mfma_f32_16x16x32_bf16 v[20:23], v[246:249], v[160:163], v[20:23]
	v_mfma_f32_16x16x32_bf16 v[16:19], v[212:215], v[168:171], v[16:19]
	v_mfma_f32_16x16x32_bf16 v[12:15], v[246:249], v[168:171], v[12:15]
	v_mfma_f32_16x16x32_bf16 v[8:11], v[212:215], v[204:207], v[8:11]
	v_mfma_f32_16x16x32_bf16 v[4:7], v[246:249], v[204:207], v[4:7]
	s_setprio 1
	s_add_i32 s23, 0, 0x18000
	v_add_u32_e32 v2, s23, v187
	s_barrier
	ds_read_b128 v[132:135], v2
	ds_read_b128 v[136:139], v2 offset:1024
	ds_read_b128 v[140:143], v2 offset:2048
	ds_read_b128 v[144:147], v2 offset:3072
	s_add_u32 s24, s46, 0x40000
	s_addc_u32 s25, s47, 0
	s_mov_b32 m0, s82
	v_lshl_add_u64 v[208:209], s[24:25], 0, v[0:1]
	ds_read_b128 v[148:151], v240 offset:32768
	ds_read_b128 v[152:155], v240 offset:33792
	ds_read_b128 v[156:159], v240 offset:34816
	ds_read_b128 v[160:163], v240 offset:35840
	ds_read_b128 v[164:167], v240 offset:36864
	ds_read_b128 v[168:171], v240 offset:37888
	ds_read_b128 v[172:175], v240 offset:38912
	ds_read_b128 v[204:207], v240 offset:39936
	global_load_lds_dwordx4 v[208:209], off
	v_lshl_add_u64 v[208:209], s[24:25], 0, v[178:179]
	s_mov_b32 m0, s83
	s_nop 0
	global_load_lds_dwordx4 v[208:209], off
	s_waitcnt lgkmcnt(8)
	s_barrier
	s_waitcnt lgkmcnt(0)
	s_setprio 0
	s_waitcnt lgkmcnt(0)
	v_mfma_f32_16x16x32_bf16 v[128:131], v[132:135], v[148:151], v[128:131]
	v_mfma_f32_16x16x32_bf16 v[124:127], v[140:143], v[148:151], v[124:127]
	v_mfma_f32_16x16x32_bf16 v[120:123], v[132:135], v[156:159], v[120:123]
	v_mfma_f32_16x16x32_bf16 v[116:119], v[140:143], v[156:159], v[116:119]
	v_mfma_f32_16x16x32_bf16 v[112:115], v[132:135], v[164:167], v[112:115]
	v_mfma_f32_16x16x32_bf16 v[108:111], v[140:143], v[164:167], v[108:111]
	v_mfma_f32_16x16x32_bf16 v[104:107], v[132:135], v[172:175], v[104:107]
	v_mfma_f32_16x16x32_bf16 v[100:103], v[140:143], v[172:175], v[100:103]
	v_mfma_f32_16x16x32_bf16 v[128:131], v[136:139], v[152:155], v[128:131]
	v_mfma_f32_16x16x32_bf16 v[124:127], v[144:147], v[152:155], v[124:127]
	v_mfma_f32_16x16x32_bf16 v[120:123], v[136:139], v[160:163], v[120:123]
	v_mfma_f32_16x16x32_bf16 v[116:119], v[144:147], v[160:163], v[116:119]
	v_mfma_f32_16x16x32_bf16 v[112:115], v[136:139], v[168:171], v[112:115]
	v_mfma_f32_16x16x32_bf16 v[108:111], v[144:147], v[168:171], v[108:111]
	v_mfma_f32_16x16x32_bf16 v[104:107], v[136:139], v[204:207], v[104:107]
	v_mfma_f32_16x16x32_bf16 v[100:103], v[144:147], v[204:207], v[100:103]
	s_setprio 1
	s_barrier
	s_add_i32 s26, 0, 0x1c000
	s_add_i32 s23, s23, s67
	v_add_u32_e32 v2, s26, v187
	v_lshl_add_u64 v[250:251], v[250:251], 0, s[76:77]
	s_mov_b32 m0, s23
	ds_read_b128 v[208:211], v2
	ds_read_b128 v[212:215], v2 offset:1024
	ds_read_b128 v[242:245], v2 offset:2048
	ds_read_b128 v[246:249], v2 offset:3072
	global_load_lds_dwordx4 v[250:251], off
	v_lshl_add_u64 v[222:223], v[222:223], 0, s[76:77]
	s_add_i32 m0, s23, 0x2000
	s_nop 0
	global_load_lds_dwordx4 v[222:223], off
	s_barrier
	s_waitcnt lgkmcnt(0)
	s_setprio 0
	s_waitcnt lgkmcnt(0)
	v_mfma_f32_16x16x32_bf16 v[64:67], v[208:211], v[148:151], v[64:67]
	v_mfma_f32_16x16x32_bf16 v[60:63], v[242:245], v[148:151], v[60:63]
	v_mfma_f32_16x16x32_bf16 v[56:59], v[208:211], v[156:159], v[56:59]
	v_mfma_f32_16x16x32_bf16 v[52:55], v[242:245], v[156:159], v[52:55]
	v_mfma_f32_16x16x32_bf16 v[48:51], v[208:211], v[164:167], v[48:51]
	v_mfma_f32_16x16x32_bf16 v[44:47], v[242:245], v[164:167], v[44:47]
	v_mfma_f32_16x16x32_bf16 v[40:43], v[208:211], v[172:175], v[40:43]
	v_mfma_f32_16x16x32_bf16 v[36:39], v[242:245], v[172:175], v[36:39]
	v_mfma_f32_16x16x32_bf16 v[64:67], v[212:215], v[152:155], v[64:67]
	v_mfma_f32_16x16x32_bf16 v[60:63], v[246:249], v[152:155], v[60:63]
	v_mfma_f32_16x16x32_bf16 v[56:59], v[212:215], v[160:163], v[56:59]
	v_mfma_f32_16x16x32_bf16 v[52:55], v[246:249], v[160:163], v[52:55]
	v_mfma_f32_16x16x32_bf16 v[48:51], v[212:215], v[168:171], v[48:51]
	v_mfma_f32_16x16x32_bf16 v[44:47], v[246:249], v[168:171], v[44:47]
	v_mfma_f32_16x16x32_bf16 v[40:43], v[212:215], v[204:207], v[40:43]
	v_mfma_f32_16x16x32_bf16 v[36:39], v[246:249], v[204:207], v[36:39]
	s_setprio 1
	s_mov_b32 m0, s48
	v_lshl_add_u64 v[216:217], v[216:217], 0, s[76:77]
	s_barrier
	ds_read_b128 v[148:151], v240 offset:49152
	ds_read_b128 v[152:155], v240 offset:50176
	ds_read_b128 v[156:159], v240 offset:51200
	ds_read_b128 v[160:163], v240 offset:52224
	ds_read_b128 v[164:167], v240 offset:53248
	ds_read_b128 v[168:171], v240 offset:54272
	ds_read_b128 v[172:175], v240 offset:55296
	ds_read_b128 v[204:207], v240 offset:56320
	global_load_lds_dwordx4 v[216:217], off
	v_lshl_add_u64 v[216:217], v[236:237], 0, s[76:77]
	s_mov_b32 m0, s50
	s_nop 0
	global_load_lds_dwordx4 v[216:217], off
	s_barrier
	s_waitcnt lgkmcnt(0)
	s_setprio 0
	s_waitcnt lgkmcnt(0)
	v_mfma_f32_16x16x32_bf16 v[96:99], v[132:135], v[148:151], v[96:99]
	v_mfma_f32_16x16x32_bf16 v[92:95], v[140:143], v[148:151], v[92:95]
	v_mfma_f32_16x16x32_bf16 v[88:91], v[132:135], v[156:159], v[88:91]
	v_mfma_f32_16x16x32_bf16 v[84:87], v[140:143], v[156:159], v[84:87]
	v_mfma_f32_16x16x32_bf16 v[80:83], v[132:135], v[164:167], v[80:83]
	v_mfma_f32_16x16x32_bf16 v[76:79], v[140:143], v[164:167], v[76:79]
	v_mfma_f32_16x16x32_bf16 v[72:75], v[132:135], v[172:175], v[72:75]
	v_mfma_f32_16x16x32_bf16 v[68:71], v[140:143], v[172:175], v[68:71]
	v_mfma_f32_16x16x32_bf16 v[96:99], v[136:139], v[152:155], v[96:99]
	v_mfma_f32_16x16x32_bf16 v[92:95], v[144:147], v[152:155], v[92:95]
	v_mfma_f32_16x16x32_bf16 v[88:91], v[136:139], v[160:163], v[88:91]
	v_mfma_f32_16x16x32_bf16 v[84:87], v[144:147], v[160:163], v[84:87]
	v_mfma_f32_16x16x32_bf16 v[80:83], v[136:139], v[168:171], v[80:83]
	v_mfma_f32_16x16x32_bf16 v[76:79], v[144:147], v[168:171], v[76:79]
	v_mfma_f32_16x16x32_bf16 v[72:75], v[136:139], v[204:207], v[72:75]
	v_mfma_f32_16x16x32_bf16 v[68:71], v[144:147], v[204:207], v[68:71]
	s_setprio 1
	s_barrier
	s_add_u32 s24, s44, 0x40080
	s_addc_u32 s25, s45, 0
	s_add_i32 s23, s26, s67
	v_lshl_add_u64 v[132:133], s[24:25], 0, v[176:177]
	s_mov_b32 m0, s23
	s_nop 0
	global_load_lds_dwordx4 v[132:133], off
	v_lshl_add_u64 v[132:133], s[24:25], 0, v[180:181]
	s_add_i32 m0, s23, 0x2000
	s_nop 0
	global_load_lds_dwordx4 v[132:133], off
	s_waitcnt vmcnt(6)
	s_barrier
	s_setprio 0
	v_mfma_f32_16x16x32_bf16 v[32:35], v[208:211], v[148:151], v[32:35]
	v_mfma_f32_16x16x32_bf16 v[28:31], v[242:245], v[148:151], v[28:31]
	v_mfma_f32_16x16x32_bf16 v[24:27], v[208:211], v[156:159], v[24:27]
	v_mfma_f32_16x16x32_bf16 v[20:23], v[242:245], v[156:159], v[20:23]
	v_mfma_f32_16x16x32_bf16 v[16:19], v[208:211], v[164:167], v[16:19]
	v_mfma_f32_16x16x32_bf16 v[12:15], v[242:245], v[164:167], v[12:15]
	v_mfma_f32_16x16x32_bf16 v[8:11], v[208:211], v[172:175], v[8:11]
	v_mfma_f32_16x16x32_bf16 v[4:7], v[242:245], v[172:175], v[4:7]
	v_mfma_f32_16x16x32_bf16 v[32:35], v[212:215], v[152:155], v[32:35]
	v_mfma_f32_16x16x32_bf16 v[28:31], v[246:249], v[152:155], v[28:31]
	v_mfma_f32_16x16x32_bf16 v[24:27], v[212:215], v[160:163], v[24:27]
	v_mfma_f32_16x16x32_bf16 v[20:23], v[246:249], v[160:163], v[20:23]
	v_mfma_f32_16x16x32_bf16 v[16:19], v[212:215], v[168:171], v[16:19]
	v_mfma_f32_16x16x32_bf16 v[12:15], v[246:249], v[168:171], v[12:15]
	v_mfma_f32_16x16x32_bf16 v[8:11], v[212:215], v[204:207], v[8:11]
	v_mfma_f32_16x16x32_bf16 v[4:7], v[246:249], v[204:207], v[4:7]
	s_setprio 1
	s_add_i32 s22, s22, 2
	s_add_u32 s0, s0, 0x100
	s_addc_u32 s1, s1, 0
	s_add_u32 s20, s20, 0x100
	s_addc_u32 s21, s21, 0
	s_cmp_gt_u32 s22, 13
	s_barrier
	s_cbranch_scc0 .LBB0_427
	s_add_i32 s0, s61, -8
	s_cmp_lt_u32 s0, 12
	s_mov_b64 s[0:1], -1
	s_cbranch_scc1 .LBB0_451
	s_cmp_gt_i32 s61, 33
	s_cselect_b64 s[64:65], -1, 0
	s_lshl_b32 s0, s61, 8
	s_lshl_b32 s53, s60, 8
	s_add_i32 s1, s0, 0xffffee00
	s_cmp_lt_i32 s61, 26
	v_cndmask_b32_e64 v2, 0, 1, s[36:37]
	s_cselect_b32 s62, s0, s1
	s_mov_b64 s[0:1], -1
	s_and_b64 vcc, exec, s[64:65]
	v_cmp_ne_u32_e64 s[44:45], 1, v2
	s_cbranch_vccz .LBB0_433
	s_and_b64 vcc, exec, s[44:45]
	s_cbranch_vccnz .LBB0_432
	v_add_u32_e32 v132, s53, v185
	v_ashrrev_i32_e32 v133, 31, v132
	v_lshlrev_b64 v[140:141], 7, v[132:133]
	global_load_dwordx4 v[204:207], v[188:189], off offset:16
	global_load_dwordx4 v[208:211], v[188:189], off
	s_mov_b32 s3, 0xbfb8aa3b
	s_mov_b32 s2, 0x800000
	s_mov_b32 s4, 0x3f317217
	s_mov_b32 s5, 0x7f800000
	s_waitcnt vmcnt(0)
	v_mov_b32_e32 v132, v204
	v_mov_b32_e32 v133, v205
	v_mov_b32_e32 v134, v206
	v_mov_b32_e32 v135, v207
	v_mov_b32_e32 v136, v208
	v_mov_b32_e32 v137, v209
	v_mov_b32_e32 v138, v210
	v_mov_b32_e32 v139, v211
	v_add_f32_e32 v147, v126, v134
	v_add_f32_e32 v2, v128, v136
	v_max_f32_e32 v142, 0, v2
	v_mul_f32_e64 v2, |v2|, s3
	v_exp_f32_e32 v2, v2
	v_add_f32_e32 v136, v124, v132
	v_add_f32_e32 v149, v127, v135
	v_add_f32_e32 v2, 1.0, v2
	v_cmp_gt_f32_e32 vcc, s2, v2
	s_nop 1
	v_cndmask_b32_e64 v132, 0, 32, vcc
	v_ldexp_f32 v2, v2, v132
	v_log_f32_e32 v2, v2
	s_nop 0
	v_mul_f32_e32 v132, 0x3f317217, v2
	v_fma_f32 v132, v2, s4, -v132
	v_fmac_f32_e32 v132, 0x3377d1cf, v2
	v_fmac_f32_e32 v132, 0x3f317217, v2
	v_cmp_lt_f32_e64 s[0:1], |v2|, s5
	s_nop 1
	v_cndmask_b32_e64 v2, v2, v132, s[0:1]
	v_cndmask_b32_e32 v132, 0, v228, vcc
	v_sub_f32_e32 v144, v2, v132
	v_mul_f32_e64 v2, |v136|, s3
	v_exp_f32_e32 v2, v2
	v_max_f32_e32 v132, 0, v136
	v_add_f32_e32 v2, 1.0, v2
	v_cmp_gt_f32_e32 vcc, s2, v2
	s_nop 1
	v_cndmask_b32_e64 v136, 0, 32, vcc
	v_ldexp_f32 v2, v2, v136
	v_log_f32_e32 v2, v2
	s_nop 0
	v_mul_f32_e32 v136, 0x3f317217, v2
	v_fma_f32 v136, v2, s4, -v136
	v_fmac_f32_e32 v136, 0x3377d1cf, v2
	v_fmac_f32_e32 v136, 0x3f317217, v2
	v_cmp_lt_f32_e64 s[0:1], |v2|, s5
	s_nop 1
	v_cndmask_b32_e64 v2, v2, v136, s[0:1]
	v_cndmask_b32_e32 v136, 0, v228, vcc
	v_sub_f32_e32 v136, v2, v136
	v_add_f32_e32 v2, v129, v137
	v_max_f32_e32 v143, 0, v2
	v_mul_f32_e64 v2, |v2|, s3
	v_exp_f32_e32 v2, v2
	v_add_f32_e32 v137, v125, v133
	v_add_f32_e32 v2, 1.0, v2
	v_cmp_gt_f32_e32 vcc, s2, v2
	s_nop 1
	v_cndmask_b32_e64 v133, 0, 32, vcc
	v_ldexp_f32 v2, v2, v133
	v_log_f32_e32 v2, v2
	s_nop 0
	v_mul_f32_e32 v133, 0x3f317217, v2
	v_fma_f32 v133, v2, s4, -v133
	v_fmac_f32_e32 v133, 0x3377d1cf, v2
	v_fmac_f32_e32 v133, 0x3f317217, v2
	v_cmp_lt_f32_e64 s[0:1], |v2|, s5
	s_nop 1
	v_cndmask_b32_e64 v2, v2, v133, s[0:1]
	v_cndmask_b32_e32 v133, 0, v228, vcc
	v_sub_f32_e32 v145, v2, v133
	v_mul_f32_e64 v2, |v137|, s3
	v_exp_f32_e32 v2, v2
	v_max_f32_e32 v133, 0, v137
	v_pk_add_f32 v[142:143], v[142:143], v[144:145]
	v_add_f32_e32 v2, 1.0, v2
	v_cmp_gt_f32_e32 vcc, s2, v2
	s_nop 1
	v_cndmask_b32_e64 v137, 0, 32, vcc
	v_ldexp_f32 v2, v2, v137
	v_log_f32_e32 v2, v2
	s_nop 0
	v_mul_f32_e32 v137, 0x3f317217, v2
	v_fma_f32 v137, v2, s4, -v137
	v_fmac_f32_e32 v137, 0x3377d1cf, v2
	v_fmac_f32_e32 v137, 0x3f317217, v2
	v_cmp_lt_f32_e64 s[0:1], |v2|, s5
	s_nop 1
	v_cndmask_b32_e64 v2, v2, v137, s[0:1]
	v_cndmask_b32_e32 v137, 0, v228, vcc
	v_sub_f32_e32 v137, v2, v137
	v_add_f32_e32 v2, v130, v138
	v_max_f32_e32 v138, 0, v2
	v_mul_f32_e64 v2, |v2|, s3
	v_exp_f32_e32 v2, v2
	v_pk_add_f32 v[132:133], v[132:133], v[136:137]
	v_lshl_add_u64 v[136:137], v[190:191], 0, v[140:141]
	v_add_f32_e32 v2, 1.0, v2
	v_cmp_gt_f32_e32 vcc, s2, v2
	s_nop 1
	v_cndmask_b32_e64 v134, 0, 32, vcc
	v_ldexp_f32 v2, v2, v134
	v_log_f32_e32 v2, v2
	s_nop 0
	v_mul_f32_e32 v134, 0x3f317217, v2
	v_fma_f32 v134, v2, s4, -v134
	v_fmac_f32_e32 v134, 0x3377d1cf, v2
	v_fmac_f32_e32 v134, 0x3f317217, v2
	v_cmp_lt_f32_e64 s[0:1], |v2|, s5
	s_nop 1
	v_cndmask_b32_e64 v2, v2, v134, s[0:1]
	v_cndmask_b32_e32 v134, 0, v228, vcc
	v_sub_f32_e32 v146, v2, v134
	v_mul_f32_e64 v2, |v147|, s3
	v_exp_f32_e32 v2, v2
	v_max_f32_e32 v134, 0, v147
	v_add_f32_e32 v2, 1.0, v2
	v_cmp_gt_f32_e32 vcc, s2, v2
	s_nop 1
	v_cndmask_b32_e64 v147, 0, 32, vcc
	v_ldexp_f32 v2, v2, v147
	v_log_f32_e32 v2, v2
	s_nop 0
	v_mul_f32_e32 v147, 0x3f317217, v2
	v_fma_f32 v147, v2, s4, -v147
	v_fmac_f32_e32 v147, 0x3377d1cf, v2
	v_fmac_f32_e32 v147, 0x3f317217, v2
	v_cmp_lt_f32_e64 s[0:1], |v2|, s5
	s_nop 1
	v_cndmask_b32_e64 v2, v2, v147, s[0:1]
	v_cndmask_b32_e32 v147, 0, v228, vcc
	v_sub_f32_e32 v148, v2, v147
	v_add_f32_e32 v2, v131, v139
	v_max_f32_e32 v139, 0, v2
	v_mul_f32_e64 v2, |v2|, s3
	v_exp_f32_e32 v2, v2
	s_nop 0
	v_add_f32_e32 v2, 1.0, v2
	v_cmp_gt_f32_e32 vcc, s2, v2
	s_nop 1
	v_cndmask_b32_e64 v135, 0, 32, vcc
	v_ldexp_f32 v2, v2, v135
	v_log_f32_e32 v2, v2
	s_nop 0
	v_mul_f32_e32 v135, 0x3f317217, v2
	v_fma_f32 v135, v2, s4, -v135
	v_fmac_f32_e32 v135, 0x3377d1cf, v2
	v_fmac_f32_e32 v135, 0x3f317217, v2
	v_cmp_lt_f32_e64 s[0:1], |v2|, s5
	s_nop 1
	v_cndmask_b32_e64 v2, v2, v135, s[0:1]
	v_cndmask_b32_e32 v135, 0, v228, vcc
	v_sub_f32_e32 v147, v2, v135
	v_mul_f32_e64 v2, |v149|, s3
	v_exp_f32_e32 v2, v2
	v_pk_add_f32 v[144:145], v[138:139], v[146:147]
	v_max_f32_e32 v135, 0, v149
	v_add_f32_e32 v2, 1.0, v2
	v_cmp_gt_f32_e32 vcc, s2, v2
	s_nop 1
	v_cndmask_b32_e64 v138, 0, 32, vcc
	v_ldexp_f32 v2, v2, v138
	v_log_f32_e32 v2, v2
	s_nop 0
	v_mul_f32_e32 v138, 0x3f317217, v2
	v_fma_f32 v138, v2, s4, -v138
	v_fmac_f32_e32 v138, 0x3377d1cf, v2
	v_fmac_f32_e32 v138, 0x3f317217, v2
	v_cmp_lt_f32_e64 s[0:1], |v2|, s5
	s_nop 1
	v_cndmask_b32_e64 v2, v2, v138, s[0:1]
	v_cndmask_b32_e32 v138, 0, v228, vcc
	v_sub_f32_e32 v149, v2, v138
	v_pk_add_f32 v[134:135], v[134:135], v[148:149]
	global_store_dwordx4 v[136:137], v[142:145], off
	global_store_dwordx4 v[136:137], v[132:135], off offset:16
